# removed all 112 s_setprio flips from the 7 GEMM main loops
# speedup vs baseline: 1.0110x; 1.0110x over previous
.LBB0_87:
	s_add_u32 s16, s14, 0xfff80080
	s_addc_u32 s17, s15, -1
	s_add_i32 s43, 0, 0x10000
	v_add_u32_e32 v140, s43, v183
	ds_read_b128 v[128:131], v140
	ds_read_b128 v[132:135], v140 offset:1024
	ds_read_b128 v[136:139], v140 offset:2048
	ds_read_b128 v[140:143], v140 offset:3072
	s_cmp_eq_u32 s42, 28
	s_cselect_b32 s19, s7, s17
	s_cselect_b32 s18, s38, s16
	s_cselect_b32 s17, s5, s41
	s_cselect_b32 s16, s39, s40
	v_lshl_add_u64 v[190:191], s[14:15], 0, v[166:167]
	s_add_i32 m0, s28, 0xc000
	ds_read_b128 v[144:147], v185
	ds_read_b128 v[148:151], v185 offset:1024
	ds_read_b128 v[152:155], v185 offset:2048
	ds_read_b128 v[156:159], v185 offset:3072
	ds_read_b128 v[170:173], v185 offset:4096
	ds_read_b128 v[174:177], v185 offset:5120
	ds_read_b128 v[178:181], v185 offset:6144
	ds_read_b128 v[186:189], v185 offset:7168
	global_load_lds_dwordx4 v[190:191], off
	v_lshl_add_u64 v[190:191], s[14:15], 0, v[168:169]
	s_add_i32 m0, s28, 0xe000
	s_nop 0
	global_load_lds_dwordx4 v[190:191], off
	s_waitcnt lgkmcnt(8)
	s_barrier
	s_waitcnt lgkmcnt(0)
	s_waitcnt lgkmcnt(0)
	v_mfma_f32_16x16x32_bf16 v[124:127], v[128:131], v[144:147], v[124:127]
	v_mfma_f32_16x16x32_bf16 v[120:123], v[136:139], v[144:147], v[120:123]
	v_mfma_f32_16x16x32_bf16 v[108:111], v[128:131], v[152:155], v[108:111]
	v_mfma_f32_16x16x32_bf16 v[104:107], v[136:139], v[152:155], v[104:107]
	v_mfma_f32_16x16x32_bf16 v[92:95], v[128:131], v[170:173], v[92:95]
	v_mfma_f32_16x16x32_bf16 v[88:91], v[136:139], v[170:173], v[88:91]
	v_mfma_f32_16x16x32_bf16 v[76:79], v[128:131], v[178:181], v[76:79]
	v_mfma_f32_16x16x32_bf16 v[72:75], v[136:139], v[178:181], v[72:75]
	v_mfma_f32_16x16x32_bf16 v[124:127], v[132:135], v[148:151], v[124:127]
	v_mfma_f32_16x16x32_bf16 v[120:123], v[140:143], v[148:151], v[120:123]
	v_mfma_f32_16x16x32_bf16 v[108:111], v[132:135], v[156:159], v[108:111]
	v_mfma_f32_16x16x32_bf16 v[104:107], v[140:143], v[156:159], v[104:107]
	v_mfma_f32_16x16x32_bf16 v[92:95], v[132:135], v[174:177], v[92:95]
	v_mfma_f32_16x16x32_bf16 v[88:91], v[140:143], v[174:177], v[88:91]
	v_mfma_f32_16x16x32_bf16 v[76:79], v[132:135], v[186:189], v[76:79]
	v_mfma_f32_16x16x32_bf16 v[72:75], v[140:143], v[186:189], v[72:75]
	s_barrier
	s_add_i32 s46, 0, 0x14000
	v_add_u32_e32 v190, s46, v183
	s_add_i32 s43, s43, s27
	ds_read_b128 v[196:199], v190
	ds_read_b128 v[204:207], v190 offset:1024
	ds_read_b128 v[208:211], v190 offset:2048
	ds_read_b128 v[214:217], v190 offset:3072
	v_lshl_add_u64 v[190:191], s[16:17], 0, v[192:193]
	s_mov_b32 m0, s43
	v_lshl_add_u64 v[218:219], s[16:17], 0, v[164:165]
	global_load_lds_dwordx4 v[190:191], off
	s_add_i32 m0, s43, 0x2000
	s_nop 0
	global_load_lds_dwordx4 v[218:219], off
	s_barrier
	s_waitcnt lgkmcnt(0)
	s_waitcnt lgkmcnt(0)
	v_mfma_f32_16x16x32_bf16 v[116:119], v[196:199], v[144:147], v[116:119]
	v_mfma_f32_16x16x32_bf16 v[112:115], v[208:211], v[144:147], v[112:115]
	v_mfma_f32_16x16x32_bf16 v[100:103], v[196:199], v[152:155], v[100:103]
	v_mfma_f32_16x16x32_bf16 v[96:99], v[208:211], v[152:155], v[96:99]
	v_mfma_f32_16x16x32_bf16 v[84:87], v[196:199], v[170:173], v[84:87]
	v_mfma_f32_16x16x32_bf16 v[80:83], v[208:211], v[170:173], v[80:83]
	v_mfma_f32_16x16x32_bf16 v[68:71], v[196:199], v[178:181], v[68:71]
	v_mfma_f32_16x16x32_bf16 v[64:67], v[208:211], v[178:181], v[64:67]
	v_mfma_f32_16x16x32_bf16 v[116:119], v[204:207], v[148:151], v[116:119]
	v_mfma_f32_16x16x32_bf16 v[112:115], v[214:217], v[148:151], v[112:115]
	v_mfma_f32_16x16x32_bf16 v[100:103], v[204:207], v[156:159], v[100:103]
	v_mfma_f32_16x16x32_bf16 v[96:99], v[214:217], v[156:159], v[96:99]
	v_mfma_f32_16x16x32_bf16 v[84:87], v[204:207], v[174:177], v[84:87]
	v_mfma_f32_16x16x32_bf16 v[80:83], v[214:217], v[174:177], v[80:83]
	v_mfma_f32_16x16x32_bf16 v[68:71], v[204:207], v[186:189], v[68:71]
	v_mfma_f32_16x16x32_bf16 v[64:67], v[214:217], v[186:189], v[64:67]
	s_mov_b32 m0, s28
	v_lshl_add_u64 v[220:221], s[18:19], 0, v[160:161]
	s_barrier
	ds_read_b128 v[144:147], v185 offset:16384
	ds_read_b128 v[148:151], v185 offset:17408
	ds_read_b128 v[152:155], v185 offset:18432
	ds_read_b128 v[156:159], v185 offset:19456
	ds_read_b128 v[170:173], v185 offset:20480
	ds_read_b128 v[174:177], v185 offset:21504
	ds_read_b128 v[178:181], v185 offset:22528
	ds_read_b128 v[186:189], v185 offset:23552
	global_load_lds_dwordx4 v[220:221], off
	v_lshl_add_u64 v[222:223], s[18:19], 0, v[162:163]
	s_mov_b32 m0, s29
	s_nop 0
	global_load_lds_dwordx4 v[222:223], off
	s_barrier
	s_waitcnt lgkmcnt(0)
	s_waitcnt lgkmcnt(0)
	v_mfma_f32_16x16x32_bf16 v[60:63], v[128:131], v[144:147], v[60:63]
	v_mfma_f32_16x16x32_bf16 v[56:59], v[136:139], v[144:147], v[56:59]
	v_mfma_f32_16x16x32_bf16 v[44:47], v[128:131], v[152:155], v[44:47]
	v_mfma_f32_16x16x32_bf16 v[40:43], v[136:139], v[152:155], v[40:43]
	v_mfma_f32_16x16x32_bf16 v[28:31], v[128:131], v[170:173], v[28:31]
	v_mfma_f32_16x16x32_bf16 v[24:27], v[136:139], v[170:173], v[24:27]
	v_mfma_f32_16x16x32_bf16 v[12:15], v[128:131], v[178:181], v[12:15]
	v_mfma_f32_16x16x32_bf16 v[8:11], v[136:139], v[178:181], v[8:11]
	v_mfma_f32_16x16x32_bf16 v[60:63], v[132:135], v[148:151], v[60:63]
	v_mfma_f32_16x16x32_bf16 v[56:59], v[140:143], v[148:151], v[56:59]
	v_mfma_f32_16x16x32_bf16 v[44:47], v[132:135], v[156:159], v[44:47]
	v_mfma_f32_16x16x32_bf16 v[40:43], v[140:143], v[156:159], v[40:43]
	v_mfma_f32_16x16x32_bf16 v[28:31], v[132:135], v[174:177], v[28:31]
	v_mfma_f32_16x16x32_bf16 v[24:27], v[140:143], v[174:177], v[24:27]
	v_mfma_f32_16x16x32_bf16 v[12:15], v[132:135], v[186:189], v[12:15]
	v_mfma_f32_16x16x32_bf16 v[8:11], v[140:143], v[186:189], v[8:11]
	s_barrier
	s_add_u32 s44, s16, 0x80000
	s_addc_u32 s45, s17, 0
	s_add_i32 s43, s46, s27
	v_lshl_add_u64 v[128:129], s[44:45], 0, v[192:193]
	s_mov_b32 m0, s43
	s_nop 0
	global_load_lds_dwordx4 v[128:129], off
	v_lshl_add_u64 v[128:129], s[44:45], 0, v[164:165]
	s_add_i32 m0, s43, 0x2000
	s_nop 0
	global_load_lds_dwordx4 v[128:129], off
	s_waitcnt vmcnt(6)
	s_barrier
	v_mfma_f32_16x16x32_bf16 v[52:55], v[196:199], v[144:147], v[52:55]
	v_mfma_f32_16x16x32_bf16 v[48:51], v[208:211], v[144:147], v[48:51]
	v_mfma_f32_16x16x32_bf16 v[36:39], v[196:199], v[152:155], v[36:39]
	v_mfma_f32_16x16x32_bf16 v[32:35], v[208:211], v[152:155], v[32:35]
	v_mfma_f32_16x16x32_bf16 v[20:23], v[196:199], v[170:173], v[20:23]
	v_mfma_f32_16x16x32_bf16 v[16:19], v[208:211], v[170:173], v[16:19]
	v_mfma_f32_16x16x32_bf16 v[4:7], v[196:199], v[178:181], v[4:7]
	v_mfma_f32_16x16x32_bf16 v[0:3], v[208:211], v[178:181], v[0:3]
	v_mfma_f32_16x16x32_bf16 v[52:55], v[204:207], v[148:151], v[52:55]
	v_mfma_f32_16x16x32_bf16 v[48:51], v[214:217], v[148:151], v[48:51]
	v_mfma_f32_16x16x32_bf16 v[36:39], v[204:207], v[156:159], v[36:39]
	v_mfma_f32_16x16x32_bf16 v[32:35], v[214:217], v[156:159], v[32:35]
	v_mfma_f32_16x16x32_bf16 v[20:23], v[204:207], v[174:177], v[20:23]
	v_mfma_f32_16x16x32_bf16 v[16:19], v[214:217], v[174:177], v[16:19]
	v_mfma_f32_16x16x32_bf16 v[4:7], v[204:207], v[186:189], v[4:7]
	v_mfma_f32_16x16x32_bf16 v[0:3], v[214:217], v[186:189], v[0:3]
	s_add_i32 s43, 0, 0x18000
	v_add_u32_e32 v140, s43, v183
	s_barrier
	ds_read_b128 v[128:131], v140
	ds_read_b128 v[132:135], v140 offset:1024
	ds_read_b128 v[136:139], v140 offset:2048
	ds_read_b128 v[140:143], v140 offset:3072
	s_add_u32 s18, s18, 0x80000
	s_addc_u32 s19, s19, 0
	s_mov_b32 m0, s30
	v_lshl_add_u64 v[196:197], s[18:19], 0, v[160:161]
	ds_read_b128 v[144:147], v185 offset:32768
	ds_read_b128 v[148:151], v185 offset:33792
	ds_read_b128 v[152:155], v185 offset:34816
	ds_read_b128 v[156:159], v185 offset:35840
	ds_read_b128 v[170:173], v185 offset:36864
	ds_read_b128 v[174:177], v185 offset:37888
	ds_read_b128 v[178:181], v185 offset:38912
	ds_read_b128 v[186:189], v185 offset:39936
	global_load_lds_dwordx4 v[196:197], off
	v_lshl_add_u64 v[196:197], s[18:19], 0, v[162:163]
	s_mov_b32 m0, s31
	s_nop 0
	global_load_lds_dwordx4 v[196:197], off
	s_waitcnt lgkmcnt(8)
	s_barrier
	s_waitcnt lgkmcnt(0)
	s_waitcnt lgkmcnt(0)
	v_mfma_f32_16x16x32_bf16 v[124:127], v[128:131], v[144:147], v[124:127]
	v_mfma_f32_16x16x32_bf16 v[120:123], v[136:139], v[144:147], v[120:123]
	v_mfma_f32_16x16x32_bf16 v[108:111], v[128:131], v[152:155], v[108:111]
	v_mfma_f32_16x16x32_bf16 v[104:107], v[136:139], v[152:155], v[104:107]
	v_mfma_f32_16x16x32_bf16 v[92:95], v[128:131], v[170:173], v[92:95]
	v_mfma_f32_16x16x32_bf16 v[88:91], v[136:139], v[170:173], v[88:91]
	v_mfma_f32_16x16x32_bf16 v[76:79], v[128:131], v[178:181], v[76:79]
	v_mfma_f32_16x16x32_bf16 v[72:75], v[136:139], v[178:181], v[72:75]
	v_mfma_f32_16x16x32_bf16 v[124:127], v[132:135], v[148:151], v[124:127]
	v_mfma_f32_16x16x32_bf16 v[120:123], v[140:143], v[148:151], v[120:123]
	v_mfma_f32_16x16x32_bf16 v[108:111], v[132:135], v[156:159], v[108:111]
	v_mfma_f32_16x16x32_bf16 v[104:107], v[140:143], v[156:159], v[104:107]
	v_mfma_f32_16x16x32_bf16 v[92:95], v[132:135], v[174:177], v[92:95]
	v_mfma_f32_16x16x32_bf16 v[88:91], v[140:143], v[174:177], v[88:91]
	v_mfma_f32_16x16x32_bf16 v[76:79], v[132:135], v[186:189], v[76:79]
	v_mfma_f32_16x16x32_bf16 v[72:75], v[140:143], v[186:189], v[72:75]
	s_barrier
	s_add_i32 s18, 0, 0x1c000
	s_add_i32 s19, s43, s27
	v_add_u32_e32 v212, s18, v183
	v_lshl_add_u64 v[190:191], v[190:191], 0, s[48:49]
	s_mov_b32 m0, s19
	ds_read_b128 v[196:199], v212
	ds_read_b128 v[204:207], v212 offset:1024
	ds_read_b128 v[208:211], v212 offset:2048
	ds_read_b128 v[214:217], v212 offset:3072
	global_load_lds_dwordx4 v[190:191], off
	v_lshl_add_u64 v[190:191], v[218:219], 0, s[48:49]
	s_add_i32 m0, s19, 0x2000
	s_nop 0
	global_load_lds_dwordx4 v[190:191], off
	s_barrier
	s_waitcnt lgkmcnt(0)
	s_waitcnt lgkmcnt(0)
	v_mfma_f32_16x16x32_bf16 v[116:119], v[196:199], v[144:147], v[116:119]
	v_mfma_f32_16x16x32_bf16 v[112:115], v[208:211], v[144:147], v[112:115]
	v_mfma_f32_16x16x32_bf16 v[100:103], v[196:199], v[152:155], v[100:103]
	v_mfma_f32_16x16x32_bf16 v[96:99], v[208:211], v[152:155], v[96:99]
	v_mfma_f32_16x16x32_bf16 v[84:87], v[196:199], v[170:173], v[84:87]
	v_mfma_f32_16x16x32_bf16 v[80:83], v[208:211], v[170:173], v[80:83]
	v_mfma_f32_16x16x32_bf16 v[68:71], v[196:199], v[178:181], v[68:71]
	v_mfma_f32_16x16x32_bf16 v[64:67], v[208:211], v[178:181], v[64:67]
	v_mfma_f32_16x16x32_bf16 v[116:119], v[204:207], v[148:151], v[116:119]
	v_mfma_f32_16x16x32_bf16 v[112:115], v[214:217], v[148:151], v[112:115]
	v_mfma_f32_16x16x32_bf16 v[100:103], v[204:207], v[156:159], v[100:103]
	v_mfma_f32_16x16x32_bf16 v[96:99], v[214:217], v[156:159], v[96:99]
	v_mfma_f32_16x16x32_bf16 v[84:87], v[204:207], v[174:177], v[84:87]
	v_mfma_f32_16x16x32_bf16 v[80:83], v[214:217], v[174:177], v[80:83]
	v_mfma_f32_16x16x32_bf16 v[68:71], v[204:207], v[186:189], v[68:71]
	v_mfma_f32_16x16x32_bf16 v[64:67], v[214:217], v[186:189], v[64:67]
	s_mov_b32 m0, s35
	v_lshl_add_u64 v[190:191], v[220:221], 0, s[48:49]
	s_barrier
	ds_read_b128 v[144:147], v185 offset:49152
	ds_read_b128 v[148:151], v185 offset:50176
	ds_read_b128 v[152:155], v185 offset:51200
	ds_read_b128 v[156:159], v185 offset:52224
	ds_read_b128 v[170:173], v185 offset:53248
	ds_read_b128 v[174:177], v185 offset:54272
	ds_read_b128 v[178:181], v185 offset:55296
	ds_read_b128 v[186:189], v185 offset:56320
	global_load_lds_dwordx4 v[190:191], off
	v_lshl_add_u64 v[190:191], v[222:223], 0, s[48:49]
	s_mov_b32 m0, s36
	s_nop 0
	global_load_lds_dwordx4 v[190:191], off
	s_barrier
	s_waitcnt lgkmcnt(0)
	s_waitcnt lgkmcnt(0)
	v_mfma_f32_16x16x32_bf16 v[60:63], v[128:131], v[144:147], v[60:63]
	v_mfma_f32_16x16x32_bf16 v[56:59], v[136:139], v[144:147], v[56:59]
	v_mfma_f32_16x16x32_bf16 v[44:47], v[128:131], v[152:155], v[44:47]
	v_mfma_f32_16x16x32_bf16 v[40:43], v[136:139], v[152:155], v[40:43]
	v_mfma_f32_16x16x32_bf16 v[28:31], v[128:131], v[170:173], v[28:31]
	v_mfma_f32_16x16x32_bf16 v[24:27], v[136:139], v[170:173], v[24:27]
	v_mfma_f32_16x16x32_bf16 v[12:15], v[128:131], v[178:181], v[12:15]
	v_mfma_f32_16x16x32_bf16 v[8:11], v[136:139], v[178:181], v[8:11]
	v_mfma_f32_16x16x32_bf16 v[60:63], v[132:135], v[148:151], v[60:63]
	v_mfma_f32_16x16x32_bf16 v[56:59], v[140:143], v[148:151], v[56:59]
	v_mfma_f32_16x16x32_bf16 v[44:47], v[132:135], v[156:159], v[44:47]
	v_mfma_f32_16x16x32_bf16 v[40:43], v[140:143], v[156:159], v[40:43]
	v_mfma_f32_16x16x32_bf16 v[28:31], v[132:135], v[174:177], v[28:31]
	v_mfma_f32_16x16x32_bf16 v[24:27], v[140:143], v[174:177], v[24:27]
	v_mfma_f32_16x16x32_bf16 v[12:15], v[132:135], v[186:189], v[12:15]
	v_mfma_f32_16x16x32_bf16 v[8:11], v[140:143], v[186:189], v[8:11]
	s_barrier
	s_add_u32 s16, s16, 0x80080
	s_addc_u32 s17, s17, 0
	s_add_i32 s18, s18, s27
	v_lshl_add_u64 v[128:129], s[16:17], 0, v[192:193]
	s_mov_b32 m0, s18
	s_nop 0
	global_load_lds_dwordx4 v[128:129], off
	v_lshl_add_u64 v[128:129], s[16:17], 0, v[164:165]
	s_add_i32 m0, s18, 0x2000
	s_nop 0
	global_load_lds_dwordx4 v[128:129], off
	s_waitcnt vmcnt(6)
	s_barrier
	v_mfma_f32_16x16x32_bf16 v[52:55], v[196:199], v[144:147], v[52:55]
	v_mfma_f32_16x16x32_bf16 v[48:51], v[208:211], v[144:147], v[48:51]
	v_mfma_f32_16x16x32_bf16 v[36:39], v[196:199], v[152:155], v[36:39]
	v_mfma_f32_16x16x32_bf16 v[32:35], v[208:211], v[152:155], v[32:35]
	v_mfma_f32_16x16x32_bf16 v[20:23], v[196:199], v[170:173], v[20:23]
	v_mfma_f32_16x16x32_bf16 v[16:19], v[208:211], v[170:173], v[16:19]
	v_mfma_f32_16x16x32_bf16 v[4:7], v[196:199], v[178:181], v[4:7]
	v_mfma_f32_16x16x32_bf16 v[0:3], v[208:211], v[178:181], v[0:3]
	v_mfma_f32_16x16x32_bf16 v[52:55], v[204:207], v[148:151], v[52:55]
	v_mfma_f32_16x16x32_bf16 v[48:51], v[214:217], v[148:151], v[48:51]
	v_mfma_f32_16x16x32_bf16 v[36:39], v[204:207], v[156:159], v[36:39]
	v_mfma_f32_16x16x32_bf16 v[32:35], v[214:217], v[156:159], v[32:35]
	v_mfma_f32_16x16x32_bf16 v[20:23], v[204:207], v[174:177], v[20:23]
	v_mfma_f32_16x16x32_bf16 v[16:19], v[214:217], v[174:177], v[16:19]
	v_mfma_f32_16x16x32_bf16 v[4:7], v[204:207], v[186:189], v[4:7]
	v_mfma_f32_16x16x32_bf16 v[0:3], v[214:217], v[186:189], v[0:3]
	s_add_i32 s42, s42, 2
	s_add_u32 s14, s14, 0x100
	s_addc_u32 s15, s15, 0
	s_add_u32 s40, s40, 0x100
	s_addc_u32 s41, s41, 0
	s_cmp_gt_u32 s42, 29
	s_barrier
	s_cbranch_scc0 .LBB0_87
	v_lshl_or_b32 v128, s13, 8, v184
	v_lshl_add_u32 v172, s12, 8, v182
	v_ashrrev_i32_e32 v129, 31, v128
	v_lshlrev_b64 v[170:171], 1, v[128:129]
	v_ashrrev_i32_e32 v173, 31, v172
	v_lshl_add_u64 v[174:175], s[2:3], 0, v[170:171]
	v_lshlrev_b64 v[128:129], 13, v[172:173]
	v_lshl_add_u64 v[130:131], v[174:175], 0, v[128:129]
	global_load_dwordx4 v[186:189], v[130:131], off
	global_load_dwordx4 v[196:199], v[130:131], off offset:256
	s_lshl_b32 s5, s13, 1
	v_mul_f32_e32 v133, 0xbfb8aa3b, v124
	v_mul_f32_e32 v135, 0xbfb8aa3b, v125
	v_mul_f32_e32 v137, 0xbfb8aa3b, v126
	v_mul_f32_e32 v138, 0xbfb8aa3b, v127
	v_mul_f32_e32 v139, 0xbfb8aa3b, v120
	v_mul_f32_e32 v140, 0xbfb8aa3b, v121
	s_and_b32 s12, s5, -4
	v_or_b32_e32 v132, 16, v172
	v_or_b32_e32 v136, 48, v172
	v_exp_f32_e32 v148, v133
	v_exp_f32_e32 v149, v135
	v_exp_f32_e32 v150, v137
	v_exp_f32_e32 v151, v138
	v_exp_f32_e32 v204, v139
	v_exp_f32_e32 v205, v140
	s_ashr_i32 s13, s12, 31
	v_or_b32_e32 v134, 32, v172
	v_ashrrev_i32_e32 v133, 31, v132
	v_ashrrev_i32_e32 v137, 31, v136
	s_lshl_b64 s[12:13], s[12:13], 2
	v_mul_f32_e32 v141, 0xbfb8aa3b, v122
	v_ashrrev_i32_e32 v135, 31, v134
	v_lshlrev_b64 v[180:181], 13, v[132:133]
	v_lshlrev_b64 v[176:177], 13, v[136:137]
	s_add_u32 s12, s33, s12
	v_exp_f32_e32 v212, v141
	v_lshlrev_b64 v[138:139], 7, v[172:173]
	v_lshlrev_b64 v[140:141], 7, v[132:133]
	v_lshlrev_b64 v[142:143], 7, v[134:135]
	v_lshlrev_b64 v[178:179], 13, v[134:135]
	v_lshlrev_b64 v[144:145], 7, v[136:137]
	v_lshl_add_u64 v[128:129], s[2:3], 0, v[128:129]
	v_lshl_add_u64 v[130:131], v[174:175], 0, v[180:181]
	v_lshl_add_u64 v[136:137], v[174:175], 0, v[176:177]
	s_addc_u32 s13, s34, s13
	v_lshl_add_u64 v[146:147], v[174:175], 0, v[178:179]
	v_lshl_add_u64 v[190:191], v[128:129], 0, v[170:171]
	global_load_dwordx4 v[156:159], v[130:131], off
	global_load_dwordx4 v[152:155], v[130:131], off offset:256
	global_load_dwordx4 v[132:135], v[136:137], off
	s_nop 0
	global_load_dwordx4 v[128:131], v[136:137], off offset:256
	v_add_f32_e32 v148, 1.0, v148
	v_add_f32_e32 v149, 1.0, v149
	v_add_f32_e32 v150, 1.0, v150
	v_add_f32_e32 v151, 1.0, v151
	v_add_f32_e32 v173, 1.0, v204
	v_add_f32_e32 v204, 1.0, v205
	v_lshl_add_u64 v[136:137], s[12:13], 0, v[138:139]
	v_lshl_add_u64 v[138:139], s[12:13], 0, v[140:141]
	v_lshl_add_u64 v[140:141], s[12:13], 0, v[142:143]
	v_lshl_add_u64 v[144:145], s[12:13], 0, v[144:145]
	v_rcp_f32_e32 v214, v148
	v_rcp_f32_e32 v215, v149
	v_rcp_f32_e32 v216, v150
	v_rcp_f32_e32 v217, v151
	v_rcp_f32_e32 v218, v204
	global_load_dwordx4 v[204:207], v[136:137], off
	global_load_dwordx4 v[208:211], v[138:139], off
	s_nop 0
	global_load_dwordx4 v[136:139], v[140:141], off
	global_load_dwordx4 v[148:151], v[146:147], off
	s_nop 0
	global_load_dwordx4 v[140:143], v[146:147], off offset:256
	s_nop 0
	global_load_dwordx4 v[144:147], v[144:145], off
	v_rcp_f32_e32 v173, v173
	v_mul_f32_e32 v124, v124, v214
	v_mul_f32_e32 v125, v125, v215
	v_mul_f32_e32 v127, v127, v217
	v_mul_f32_e32 v120, v120, v173
	v_mul_f32_e32 v121, v121, v218
	s_mov_b32 s14, 0x358637bd
	s_mov_b32 s5, 0x800000
	v_mul_f32_e32 v126, v126, v216
	s_mov_b64 s[16:17], s[10:11]
	s_mov_b32 s11, 0xc000
	s_waitcnt vmcnt(0)
	v_lshlrev_b32_e32 v173, 16, v186
	v_and_b32_e32 v186, 0xffff0000, v186
	v_lshlrev_b32_e32 v214, 16, v187
	v_and_b32_e32 v187, 0xffff0000, v187
	v_mul_f32_e32 v125, v125, v186
	v_mul_f32_e32 v127, v127, v187
	v_add_f32_e32 v186, 1.0, v212
	v_mul_f32_e32 v187, 0xbfb8aa3b, v123
	v_rcp_f32_e32 v186, v186
	v_exp_f32_e32 v187, v187
	v_mul_f32_e32 v124, v124, v173
	v_and_b32_e32 v173, 0xffff0000, v188
	v_mul_f32_e32 v122, v122, v186
	v_add_f32_e32 v186, 1.0, v187
	v_mul_f32_e32 v187, 0xbfb8aa3b, v116
	v_rcp_f32_e32 v186, v186
	v_exp_f32_e32 v187, v187
	v_mul_f32_e32 v121, v121, v173
	v_lshlrev_b32_e32 v173, 16, v189
	v_mul_f32_e32 v123, v123, v186
	v_add_f32_e32 v186, 1.0, v187
	v_mul_f32_e32 v187, 0xbfb8aa3b, v117
	v_rcp_f32_e32 v186, v186
	v_exp_f32_e32 v187, v187
	v_mul_f32_e32 v122, v122, v173
	v_and_b32_e32 v173, 0xffff0000, v189
	v_mul_f32_e32 v116, v116, v186
	v_add_f32_e32 v186, 1.0, v187
	v_mul_f32_e32 v187, 0xbfb8aa3b, v118
	v_rcp_f32_e32 v186, v186
	v_exp_f32_e32 v187, v187
	v_mul_f32_e32 v123, v123, v173
	v_lshlrev_b32_e32 v173, 16, v196
	v_mul_f32_e32 v173, v116, v173
	v_mul_f32_e32 v116, v117, v186
	v_add_f32_e32 v186, 1.0, v187
	v_mul_f32_e32 v187, 0xbfb8aa3b, v119
	v_rcp_f32_e32 v186, v186
	v_exp_f32_e32 v187, v187
	v_and_b32_e32 v117, 0xffff0000, v196
	v_lshlrev_b32_e32 v215, 16, v188
	v_mul_f32_e32 v188, v116, v117
	v_mul_f32_e32 v116, v118, v186
	v_add_f32_e32 v118, 1.0, v187
	v_rcp_f32_e32 v118, v118
	v_mul_f32_e32 v186, 0xbfb8aa3b, v112
	v_exp_f32_e32 v186, v186
	v_lshlrev_b32_e32 v117, 16, v197
	v_mul_f32_e32 v187, v116, v117
	v_mul_f32_e32 v116, v119, v118
	v_mul_f32_e32 v119, 0xbfb8aa3b, v113
	v_add_f32_e32 v118, 1.0, v186
	v_exp_f32_e32 v119, v119
	v_rcp_f32_e32 v118, v118
	v_and_b32_e32 v117, 0xffff0000, v197
	v_mul_f32_e32 v186, v116, v117
	v_add_f32_e32 v117, 1.0, v119
	v_mul_f32_e32 v112, v112, v118
	v_rcp_f32_e32 v117, v117
	v_mul_f32_e32 v118, 0xbfb8aa3b, v114
	v_exp_f32_e32 v118, v118
	v_lshlrev_b32_e32 v116, 16, v198
	v_mul_f32_e32 v189, v112, v116
	v_mul_f32_e32 v112, v113, v117
	v_and_b32_e32 v113, 0xffff0000, v198
	v_add_f32_e32 v116, 1.0, v118
	v_mul_f32_e32 v196, v112, v113
	v_mul_f32_e32 v112, 0xbfb8aa3b, v115
	v_rcp_f32_e32 v116, v116
	v_exp_f32_e32 v112, v112
	v_mov_b32_e32 v117, v206
	v_mov_b32_e32 v206, v211
	v_mul_f32_e32 v113, v114, v116
	v_lshlrev_b32_e32 v114, 16, v199
	v_add_f32_e32 v112, 1.0, v112
	v_mul_f32_e32 v197, v113, v114
	v_rcp_f32_e32 v114, v112
	v_mov_b32_e32 v112, v208
	v_mov_b32_e32 v113, v204
	v_mov_b32_e32 v204, v209
	v_pk_add_f32 v[112:113], v[112:113], v[204:205]
	v_mov_b32_e32 v116, v210
	v_pk_add_f32 v[112:113], v[116:117], v[112:113]
	v_mul_f32_e32 v114, v115, v114
	v_pk_add_f32 v[116:117], v[206:207], v[112:113]
	v_mov_b64_e32 v[112:113], s[14:15]
	s_mov_b32 s14, 0x3b000000
	v_pk_fma_f32 v[118:119], v[116:117], s[14:15], v[112:113] op_sel_hi:[1,0,0]
	v_and_b32_e32 v115, 0xffff0000, v199
	v_mul_f32_e32 v116, 0x4b800000, v119
	v_cmp_gt_f32_e32 vcc, s5, v119
	v_mul_f32_e32 v126, v126, v214
	v_mul_f32_e32 v120, v120, v215
	v_cndmask_b32_e32 v116, v119, v116, vcc
	v_rsq_f32_e32 v116, v116
	v_mul_f32_e32 v119, v114, v115
	v_mul_f32_e32 v114, 0x45800000, v116
	v_cndmask_b32_e32 v198, v116, v114, vcc
	v_mul_f32_e32 v114, v124, v198
	v_mul_f32_e32 v115, v125, v198
	v_cvt_pk_bf16_f32 v114, v114, v115
	v_mul_f32_e32 v115, v126, v198
	v_mul_f32_e32 v116, v127, v198
	v_cvt_pk_bf16_f32 v115, v115, v116
	v_mul_f32_e32 v116, v120, v198
	v_mul_f32_e32 v117, v121, v198
	v_cvt_pk_bf16_f32 v116, v116, v117
	v_mul_f32_e32 v117, v122, v198
	v_mul_f32_e32 v120, v123, v198
	v_cvt_pk_bf16_f32 v117, v117, v120
	global_store_dwordx4 v[190:191], v[114:117], off
	v_mul_f32_e32 v119, v119, v198
	v_cmp_gt_f32_e32 vcc, s5, v118
	v_mul_f32_e32 v114, v173, v198
	v_mul_f32_e32 v115, v188, v198
	v_cvt_pk_bf16_f32 v114, v114, v115
	v_mul_f32_e32 v115, v187, v198
	v_mul_f32_e32 v116, v186, v198
	v_cvt_pk_bf16_f32 v115, v115, v116
	v_mul_f32_e32 v116, v189, v198
	v_mul_f32_e32 v117, v196, v198
	v_cvt_pk_bf16_f32 v116, v116, v117
	v_mul_f32_e32 v117, v197, v198
	v_cvt_pk_bf16_f32 v117, v117, v119
	v_mul_f32_e32 v119, 0x4b800000, v118
	v_cndmask_b32_e32 v118, v118, v119, vcc
	global_store_dwordx4 v[190:191], v[114:117], off offset:256
	v_rsq_f32_e32 v118, v118
	v_mul_f32_e32 v123, 0xbfb8aa3b, v61
	v_mul_f32_e32 v114, 0xbfb8aa3b, v108
	v_exp_f32_e32 v116, v114
	v_mul_f32_e32 v114, 0x45800000, v118
	v_cndmask_b32_e32 v117, v118, v114, vcc
	v_mul_f32_e32 v118, 0xbfb8aa3b, v109
	v_add_f32_e32 v116, 1.0, v116
	v_rcp_f32_e32 v116, v116
	v_exp_f32_e32 v118, v118
	v_lshl_add_u64 v[114:115], s[2:3], 0, v[180:181]
	v_lshl_add_u64 v[114:115], v[114:115], 0, v[170:171]
	v_mul_f32_e32 v108, v108, v116
	v_lshlrev_b32_e32 v116, 16, v156
	v_mul_f32_e32 v108, v108, v116
	v_add_f32_e32 v116, 1.0, v118
	v_rcp_f32_e32 v116, v116
	v_mul_f32_e32 v118, 0xbfb8aa3b, v110
	v_exp_f32_e32 v118, v118
	v_mul_f32_e32 v108, v108, v117
	v_mul_f32_e32 v109, v109, v116
	v_and_b32_e32 v116, 0xffff0000, v156
	v_mul_f32_e32 v109, v109, v116
	v_add_f32_e32 v116, 1.0, v118
	v_mul_f32_e32 v118, 0xbfb8aa3b, v111
	v_rcp_f32_e32 v116, v116
	v_exp_f32_e32 v118, v118
	v_mul_f32_e32 v109, v109, v117
	v_cvt_pk_bf16_f32 v108, v108, v109
	v_mul_f32_e32 v109, v110, v116
	v_add_f32_e32 v110, 1.0, v118
	v_rcp_f32_e32 v110, v110
	v_lshlrev_b32_e32 v116, 16, v157
	v_mul_f32_e32 v109, v109, v116
	v_and_b32_e32 v116, 0xffff0000, v157
	v_mul_f32_e32 v110, v111, v110
	v_mul_f32_e32 v111, 0xbfb8aa3b, v104
	v_exp_f32_e32 v111, v111
	v_mul_f32_e32 v110, v110, v116
	v_mul_f32_e32 v109, v109, v117
	v_mul_f32_e32 v110, v110, v117
	v_add_f32_e32 v111, 1.0, v111
	v_cvt_pk_bf16_f32 v109, v109, v110
	v_mul_f32_e32 v110, 0xbfb8aa3b, v105
	v_rcp_f32_e32 v111, v111
	v_exp_f32_e32 v110, v110
	v_exp_f32_e32 v123, v123
	v_mul_f32_e32 v124, 0xbfb8aa3b, v62
	v_mul_f32_e32 v104, v104, v111
	v_lshlrev_b32_e32 v111, 16, v158
	v_add_f32_e32 v110, 1.0, v110
	v_mul_f32_e32 v104, v104, v111
	v_rcp_f32_e32 v110, v110
	v_mul_f32_e32 v111, 0xbfb8aa3b, v106
	v_exp_f32_e32 v111, v111
	v_mul_f32_e32 v104, v104, v117
	v_mul_f32_e32 v105, v105, v110
	v_and_b32_e32 v110, 0xffff0000, v158
	v_mul_f32_e32 v105, v105, v110
	v_add_f32_e32 v110, 1.0, v111
	v_rcp_f32_e32 v111, v110
	v_mul_f32_e32 v110, 0xbfb8aa3b, v107
	v_exp_f32_e32 v116, v110
	v_mul_f32_e32 v105, v105, v117
	v_cvt_pk_bf16_f32 v110, v104, v105
	v_mul_f32_e32 v104, v106, v111
	v_add_f32_e32 v105, 1.0, v116
	v_rcp_f32_e32 v105, v105
	v_lshlrev_b32_e32 v106, 16, v159
	v_mul_f32_e32 v104, v104, v106
	v_and_b32_e32 v106, 0xffff0000, v159
	v_mul_f32_e32 v105, v107, v105
	v_mul_f32_e32 v107, 0xbfb8aa3b, v100
	v_exp_f32_e32 v107, v107
	v_mul_f32_e32 v104, v104, v117
	v_mul_f32_e32 v105, v105, v106
	v_mul_f32_e32 v105, v105, v117
	v_cvt_pk_bf16_f32 v111, v104, v105
	v_add_f32_e32 v104, 1.0, v107
	v_rcp_f32_e32 v104, v104
	v_mul_f32_e32 v105, 0xbfb8aa3b, v101
	v_exp_f32_e32 v105, v105
	global_store_dwordx4 v[114:115], v[108:111], off
	v_mul_f32_e32 v100, v100, v104
	v_lshlrev_b32_e32 v104, 16, v152
	v_mul_f32_e32 v100, v100, v104
	v_add_f32_e32 v104, 1.0, v105
	v_rcp_f32_e32 v104, v104
	v_mul_f32_e32 v105, 0xbfb8aa3b, v102
	v_exp_f32_e32 v105, v105
	v_mul_f32_e32 v100, v100, v117
	v_mul_f32_e32 v101, v101, v104
	v_and_b32_e32 v104, 0xffff0000, v152
	v_mul_f32_e32 v101, v101, v104
	v_add_f32_e32 v104, 1.0, v105
	v_mul_f32_e32 v105, 0xbfb8aa3b, v103
	v_rcp_f32_e32 v104, v104
	v_exp_f32_e32 v105, v105
	v_mul_f32_e32 v101, v101, v117
	v_cvt_pk_bf16_f32 v100, v100, v101
	v_mul_f32_e32 v101, v102, v104
	v_add_f32_e32 v102, 1.0, v105
	v_rcp_f32_e32 v102, v102
	v_lshlrev_b32_e32 v104, 16, v153
	v_mul_f32_e32 v101, v101, v104
	v_and_b32_e32 v104, 0xffff0000, v153
	v_mul_f32_e32 v102, v103, v102
	v_mul_f32_e32 v103, 0xbfb8aa3b, v96
	v_exp_f32_e32 v103, v103
	v_mul_f32_e32 v102, v102, v104
	v_mul_f32_e32 v101, v101, v117
	v_mul_f32_e32 v102, v102, v117
	v_add_f32_e32 v103, 1.0, v103
	v_cvt_pk_bf16_f32 v101, v101, v102
	v_mul_f32_e32 v102, 0xbfb8aa3b, v97
	v_rcp_f32_e32 v103, v103
	v_exp_f32_e32 v102, v102
	v_add_f32_e32 v123, 1.0, v123
	v_rcp_f32_e32 v123, v123
	v_mul_f32_e32 v96, v96, v103
	v_lshlrev_b32_e32 v103, 16, v154
	v_add_f32_e32 v102, 1.0, v102
	v_mul_f32_e32 v96, v96, v103
	v_rcp_f32_e32 v102, v102
	v_mul_f32_e32 v103, 0xbfb8aa3b, v98
	v_exp_f32_e32 v103, v103
	v_mul_f32_e32 v96, v96, v117
	v_mul_f32_e32 v97, v97, v102
	v_and_b32_e32 v102, 0xffff0000, v154
	v_mul_f32_e32 v97, v97, v102
	v_add_f32_e32 v102, 1.0, v103
	v_rcp_f32_e32 v103, v102
	v_mul_f32_e32 v102, 0xbfb8aa3b, v99
	v_exp_f32_e32 v104, v102
	v_mul_f32_e32 v97, v97, v117
	v_cvt_pk_bf16_f32 v102, v96, v97
	v_mul_f32_e32 v96, v98, v103
	v_add_f32_e32 v97, 1.0, v104
	v_rcp_f32_e32 v97, v97
	v_lshlrev_b32_e32 v98, 16, v155
	v_mul_f32_e32 v96, v96, v98
	v_and_b32_e32 v98, 0xffff0000, v155
	v_mul_f32_e32 v97, v99, v97
	v_mul_f32_e32 v99, 0xbfb8aa3b, v93
	v_exp_f32_e32 v99, v99
	v_mul_f32_e32 v97, v97, v98
	v_mul_f32_e32 v96, v96, v117
	v_mul_f32_e32 v97, v97, v117
	v_cvt_pk_bf16_f32 v103, v96, v97
	global_store_dwordx4 v[114:115], v[100:103], off offset:256
	v_add_f32_e32 v99, 1.0, v99
	v_rcp_f32_e32 v99, v99
	v_mul_f32_e32 v100, 0xbfb8aa3b, v94
	v_exp_f32_e32 v100, v100
	v_mul_f32_e32 v98, 0xbfb8aa3b, v92
	v_mul_f32_e32 v93, v93, v99
	v_exp_f32_e32 v98, v98
	v_add_f32_e32 v99, 1.0, v100
	v_mul_f32_e32 v100, 0xbfb8aa3b, v95
	v_rcp_f32_e32 v99, v99
	v_exp_f32_e32 v100, v100
	v_add_f32_e32 v98, 1.0, v98
	v_rcp_f32_e32 v98, v98
	v_mul_f32_e32 v94, v94, v99
	v_add_f32_e32 v99, 1.0, v100
	v_mul_f32_e32 v100, 0xbfb8aa3b, v88
	v_rcp_f32_e32 v99, v99
	v_exp_f32_e32 v100, v100
	v_mul_f32_e32 v92, v92, v98
	v_lshlrev_b32_e32 v98, 16, v148
	v_mul_f32_e32 v95, v95, v99
	v_add_f32_e32 v99, 1.0, v100
	v_mul_f32_e32 v100, 0xbfb8aa3b, v89
	v_rcp_f32_e32 v99, v99
	v_exp_f32_e32 v100, v100
	v_mul_f32_e32 v92, v92, v98
	v_and_b32_e32 v98, 0xffff0000, v148
	v_mul_f32_e32 v88, v88, v99
	v_add_f32_e32 v99, 1.0, v100
	v_mul_f32_e32 v100, 0xbfb8aa3b, v90
	v_rcp_f32_e32 v99, v99
	v_exp_f32_e32 v100, v100
	v_mul_f32_e32 v93, v93, v98
	v_lshlrev_b32_e32 v98, 16, v149
	v_mul_f32_e32 v89, v89, v99
	v_add_f32_e32 v99, 1.0, v100
	v_mul_f32_e32 v100, 0xbfb8aa3b, v91
	v_rcp_f32_e32 v99, v99
	v_exp_f32_e32 v100, v100
	v_mul_f32_e32 v94, v94, v98
	v_and_b32_e32 v98, 0xffff0000, v149
	v_mul_f32_e32 v90, v90, v99
	v_add_f32_e32 v99, 1.0, v100
	v_mul_f32_e32 v100, 0xbfb8aa3b, v84
	v_rcp_f32_e32 v99, v99
	v_exp_f32_e32 v100, v100
	v_mul_f32_e32 v95, v95, v98
	v_lshlrev_b32_e32 v98, 16, v150
	v_mul_f32_e32 v91, v91, v99
	v_add_f32_e32 v99, 1.0, v100
	v_mul_f32_e32 v100, 0xbfb8aa3b, v85
	v_rcp_f32_e32 v99, v99
	v_exp_f32_e32 v100, v100
	v_mul_f32_e32 v88, v88, v98
	v_and_b32_e32 v98, 0xffff0000, v150
	v_mul_f32_e32 v84, v84, v99
	v_add_f32_e32 v99, 1.0, v100
	v_mul_f32_e32 v100, 0xbfb8aa3b, v86
	v_rcp_f32_e32 v99, v99
	v_exp_f32_e32 v100, v100
	v_mul_f32_e32 v89, v89, v98
	v_lshlrev_b32_e32 v98, 16, v151
	v_mul_f32_e32 v90, v90, v98
	v_and_b32_e32 v98, 0xffff0000, v151
	v_mul_f32_e32 v91, v91, v98
	v_lshlrev_b32_e32 v98, 16, v140
	v_mul_f32_e32 v98, v84, v98
	v_mul_f32_e32 v84, v85, v99
	v_add_f32_e32 v99, 1.0, v100
	v_mul_f32_e32 v100, 0xbfb8aa3b, v87
	v_rcp_f32_e32 v99, v99
	v_exp_f32_e32 v100, v100
	v_and_b32_e32 v85, 0xffff0000, v140
	v_mul_f32_e32 v101, v84, v85
	v_mul_f32_e32 v84, v86, v99
	v_add_f32_e32 v86, 1.0, v100
	v_rcp_f32_e32 v86, v86
	v_mul_f32_e32 v99, 0xbfb8aa3b, v80
	v_exp_f32_e32 v99, v99
	v_lshlrev_b32_e32 v85, 16, v141
	v_mul_f32_e32 v100, v84, v85
	v_mul_f32_e32 v84, v87, v86
	v_mul_f32_e32 v87, 0xbfb8aa3b, v81
	v_add_f32_e32 v86, 1.0, v99
	v_exp_f32_e32 v87, v87
	v_rcp_f32_e32 v86, v86
	v_and_b32_e32 v85, 0xffff0000, v141
	v_mul_f32_e32 v99, v84, v85
	v_add_f32_e32 v85, 1.0, v87
	v_mul_f32_e32 v80, v80, v86
	v_rcp_f32_e32 v85, v85
	v_mul_f32_e32 v86, 0xbfb8aa3b, v82
	v_exp_f32_e32 v86, v86
	v_lshlrev_b32_e32 v84, 16, v142
	v_mul_f32_e32 v87, v80, v84
	v_mul_f32_e32 v80, v81, v85
	v_and_b32_e32 v81, 0xffff0000, v142
	v_add_f32_e32 v84, 1.0, v86
	v_mul_f32_e32 v86, v80, v81
	v_mul_f32_e32 v80, 0xbfb8aa3b, v83
	v_rcp_f32_e32 v84, v84
	v_exp_f32_e32 v80, v80
	v_mov_b32_e32 v85, v138
	v_mov_b32_e32 v138, v147
	v_mul_f32_e32 v81, v82, v84
	v_lshlrev_b32_e32 v82, 16, v143
	v_add_f32_e32 v80, 1.0, v80
	v_mul_f32_e32 v102, v81, v82
	v_rcp_f32_e32 v82, v80
	v_mov_b32_e32 v80, v144
	v_mov_b32_e32 v81, v136
	v_mov_b32_e32 v136, v145
	v_pk_add_f32 v[80:81], v[80:81], v[136:137]
	v_mov_b32_e32 v84, v146
	v_pk_add_f32 v[80:81], v[84:85], v[80:81]
	v_lshl_add_u64 v[96:97], s[2:3], 0, v[178:179]
	v_pk_add_f32 v[80:81], v[138:139], v[80:81]
	v_lshl_add_u64 v[96:97], v[96:97], 0, v[170:171]
	v_pk_fma_f32 v[84:85], v[80:81], s[14:15], v[112:113] op_sel_hi:[1,0,0]
	v_mul_f32_e32 v81, v83, v82
	v_mul_f32_e32 v80, 0x4b800000, v85
	v_cmp_gt_f32_e32 vcc, s5, v85
	v_and_b32_e32 v82, 0xffff0000, v143
	v_exp_f32_e32 v124, v124
	v_cndmask_b32_e32 v80, v85, v80, vcc
	v_rsq_f32_e32 v80, v80
	v_mul_f32_e32 v85, v81, v82
	v_mul_f32_e32 v61, v61, v123
	v_mul_f32_e32 v123, 0xbfb8aa3b, v63
	v_mul_f32_e32 v81, 0x45800000, v80
	v_cndmask_b32_e32 v103, v80, v81, vcc
	v_mul_f32_e32 v80, v92, v103
	v_mul_f32_e32 v81, v93, v103
	v_cvt_pk_bf16_f32 v80, v80, v81
	v_mul_f32_e32 v81, v94, v103
	v_mul_f32_e32 v82, v95, v103
	v_cvt_pk_bf16_f32 v81, v81, v82
	v_mul_f32_e32 v82, v88, v103
	v_mul_f32_e32 v83, v89, v103
	v_cvt_pk_bf16_f32 v82, v82, v83
	v_mul_f32_e32 v83, v90, v103
	v_mul_f32_e32 v88, v91, v103
	v_cvt_pk_bf16_f32 v83, v83, v88
	global_store_dwordx4 v[96:97], v[80:83], off
	v_mul_f32_e32 v85, v85, v103
	v_cmp_gt_f32_e32 vcc, s5, v84
	v_mul_f32_e32 v80, v98, v103
	v_mul_f32_e32 v81, v101, v103
	v_cvt_pk_bf16_f32 v80, v80, v81
	v_mul_f32_e32 v81, v100, v103
	v_mul_f32_e32 v82, v99, v103
	v_cvt_pk_bf16_f32 v81, v81, v82
	v_mul_f32_e32 v82, v87, v103
	v_mul_f32_e32 v83, v86, v103
	v_cvt_pk_bf16_f32 v82, v82, v83
	v_mul_f32_e32 v83, v102, v103
	v_cvt_pk_bf16_f32 v83, v83, v85
	v_mul_f32_e32 v85, 0x4b800000, v84
	v_cndmask_b32_e32 v84, v84, v85, vcc
	global_store_dwordx4 v[96:97], v[80:83], off offset:256
	v_rsq_f32_e32 v84, v84
	v_exp_f32_e32 v123, v123
	v_mul_f32_e32 v80, 0xbfb8aa3b, v76
	v_exp_f32_e32 v82, v80
	v_mul_f32_e32 v80, 0x45800000, v84
	v_cndmask_b32_e32 v83, v84, v80, vcc
	v_mul_f32_e32 v84, 0xbfb8aa3b, v77
	v_add_f32_e32 v82, 1.0, v82
	v_rcp_f32_e32 v82, v82
	v_exp_f32_e32 v84, v84
	v_lshl_add_u64 v[80:81], s[2:3], 0, v[176:177]
	v_lshl_add_u64 v[80:81], v[80:81], 0, v[170:171]
	v_mul_f32_e32 v76, v76, v82
	v_lshlrev_b32_e32 v82, 16, v132
	v_mul_f32_e32 v76, v76, v82
	v_add_f32_e32 v82, 1.0, v84
	v_rcp_f32_e32 v82, v82
	v_mul_f32_e32 v84, 0xbfb8aa3b, v78
	v_exp_f32_e32 v84, v84
	v_mul_f32_e32 v76, v76, v83
	v_mul_f32_e32 v77, v77, v82
	v_and_b32_e32 v82, 0xffff0000, v132
	v_mul_f32_e32 v77, v77, v82
	v_add_f32_e32 v82, 1.0, v84
	v_mul_f32_e32 v84, 0xbfb8aa3b, v79
	v_rcp_f32_e32 v82, v82
	v_exp_f32_e32 v84, v84
	v_mul_f32_e32 v77, v77, v83
	v_cvt_pk_bf16_f32 v76, v76, v77
	v_mul_f32_e32 v77, v78, v82
	v_add_f32_e32 v78, 1.0, v84
	v_rcp_f32_e32 v78, v78
	v_lshlrev_b32_e32 v82, 16, v133
	v_mul_f32_e32 v77, v77, v82
	v_and_b32_e32 v82, 0xffff0000, v133
	v_mul_f32_e32 v78, v79, v78
	v_mul_f32_e32 v79, 0xbfb8aa3b, v72
	v_exp_f32_e32 v79, v79
	v_mul_f32_e32 v78, v78, v82
	v_mul_f32_e32 v77, v77, v83
	v_mul_f32_e32 v78, v78, v83
	v_add_f32_e32 v79, 1.0, v79
	v_cvt_pk_bf16_f32 v77, v77, v78
	v_mul_f32_e32 v78, 0xbfb8aa3b, v73
	v_rcp_f32_e32 v79, v79
	v_exp_f32_e32 v78, v78
	v_mul_f32_e32 v72, v72, v79
	v_lshlrev_b32_e32 v79, 16, v134
	v_add_f32_e32 v78, 1.0, v78
	v_mul_f32_e32 v72, v72, v79
	v_rcp_f32_e32 v78, v78
	v_mul_f32_e32 v79, 0xbfb8aa3b, v74
	v_exp_f32_e32 v79, v79
	v_mul_f32_e32 v72, v72, v83
	v_mul_f32_e32 v73, v73, v78
	v_and_b32_e32 v78, 0xffff0000, v134
	v_mul_f32_e32 v73, v73, v78
	v_add_f32_e32 v78, 1.0, v79
	v_rcp_f32_e32 v79, v78
	v_mul_f32_e32 v78, 0xbfb8aa3b, v75
	v_exp_f32_e32 v82, v78
	v_mul_f32_e32 v73, v73, v83
	v_cvt_pk_bf16_f32 v78, v72, v73
	v_mul_f32_e32 v72, v74, v79
	v_add_f32_e32 v73, 1.0, v82
	v_rcp_f32_e32 v73, v73
	v_lshlrev_b32_e32 v74, 16, v135
	v_mul_f32_e32 v72, v72, v74
	v_and_b32_e32 v74, 0xffff0000, v135
	v_mul_f32_e32 v73, v75, v73
	v_mul_f32_e32 v75, 0xbfb8aa3b, v68
	v_exp_f32_e32 v75, v75
	v_mul_f32_e32 v72, v72, v83
	v_mul_f32_e32 v73, v73, v74
	v_mul_f32_e32 v73, v73, v83
	v_cvt_pk_bf16_f32 v79, v72, v73
	v_add_f32_e32 v72, 1.0, v75
	v_rcp_f32_e32 v72, v72
	v_mul_f32_e32 v73, 0xbfb8aa3b, v69
	v_exp_f32_e32 v73, v73
	global_store_dwordx4 v[80:81], v[76:79], off
	v_mul_f32_e32 v68, v68, v72
	v_lshlrev_b32_e32 v72, 16, v128
	v_mul_f32_e32 v68, v68, v72
	v_add_f32_e32 v72, 1.0, v73
	v_rcp_f32_e32 v72, v72
	v_mul_f32_e32 v73, 0xbfb8aa3b, v70
	v_exp_f32_e32 v73, v73
	v_mul_f32_e32 v68, v68, v83
	v_mul_f32_e32 v69, v69, v72
	v_and_b32_e32 v72, 0xffff0000, v128
	v_mul_f32_e32 v69, v69, v72
	v_add_f32_e32 v72, 1.0, v73
	v_mul_f32_e32 v73, 0xbfb8aa3b, v71
	v_rcp_f32_e32 v72, v72
	v_exp_f32_e32 v73, v73
	v_mul_f32_e32 v69, v69, v83
	v_cvt_pk_bf16_f32 v68, v68, v69
	v_mul_f32_e32 v69, v70, v72
	v_add_f32_e32 v70, 1.0, v73
	v_rcp_f32_e32 v70, v70
	v_lshlrev_b32_e32 v72, 16, v129
	v_mul_f32_e32 v69, v69, v72
	v_and_b32_e32 v72, 0xffff0000, v129
	v_mul_f32_e32 v70, v71, v70
	v_mul_f32_e32 v71, 0xbfb8aa3b, v64
	v_exp_f32_e32 v71, v71
	v_mul_f32_e32 v70, v70, v72
	v_mul_f32_e32 v69, v69, v83
	v_mul_f32_e32 v70, v70, v83
	v_add_f32_e32 v71, 1.0, v71
	v_cvt_pk_bf16_f32 v69, v69, v70
	v_mul_f32_e32 v70, 0xbfb8aa3b, v65
	v_rcp_f32_e32 v71, v71
	v_exp_f32_e32 v70, v70
	v_mul_f32_e32 v64, v64, v71
	v_lshlrev_b32_e32 v71, 16, v130
	v_add_f32_e32 v70, 1.0, v70
	v_mul_f32_e32 v64, v64, v71
	v_rcp_f32_e32 v70, v70
	v_mul_f32_e32 v71, 0xbfb8aa3b, v66
	v_exp_f32_e32 v71, v71
	v_mul_f32_e32 v64, v64, v83
	v_mul_f32_e32 v65, v65, v70
	v_and_b32_e32 v70, 0xffff0000, v130
	v_mul_f32_e32 v65, v65, v70
	v_add_f32_e32 v70, 1.0, v71
	v_rcp_f32_e32 v71, v70
	v_mul_f32_e32 v70, 0xbfb8aa3b, v67
	v_exp_f32_e32 v72, v70
	v_mul_f32_e32 v65, v65, v83
	v_cvt_pk_bf16_f32 v70, v64, v65
	v_mul_f32_e32 v64, v66, v71
	v_add_f32_e32 v65, 1.0, v72
	v_rcp_f32_e32 v65, v65
	v_lshlrev_b32_e32 v66, 16, v131
	v_mul_f32_e32 v64, v64, v66
	v_and_b32_e32 v66, 0xffff0000, v131
	v_mul_f32_e32 v65, v67, v65
	v_mul_f32_e32 v64, v64, v83
	v_mul_f32_e32 v65, v65, v66
	v_mul_f32_e32 v65, v65, v83
	v_cvt_pk_bf16_f32 v71, v64, v65
	v_add_u32_e32 v64, 0x80, v172
	v_ashrrev_i32_e32 v65, 31, v64
	v_lshlrev_b64 v[110:111], 13, v[64:65]
	v_lshl_add_u64 v[66:67], v[174:175], 0, v[110:111]
	global_load_dwordx4 v[102:105], v[66:67], off
	v_lshlrev_b64 v[64:65], 7, v[64:65]
	global_store_dwordx4 v[80:81], v[68:71], off offset:256
	v_lshl_add_u64 v[64:65], s[12:13], 0, v[64:65]
	global_load_dwordx4 v[106:109], v[64:65], off
	v_add_u32_e32 v64, 0x90, v172
	v_ashrrev_i32_e32 v65, 31, v64
	v_lshlrev_b64 v[68:69], 7, v[64:65]
	v_lshl_add_u64 v[68:69], s[12:13], 0, v[68:69]
	global_load_dwordx4 v[114:117], v[66:67], off offset:256
	global_load_dwordx4 v[118:121], v[68:69], off
	v_lshlrev_b64 v[100:101], 13, v[64:65]
	v_lshl_add_u64 v[64:65], v[174:175], 0, v[100:101]
	global_load_dwordx4 v[92:95], v[64:65], off
	global_load_dwordx4 v[88:91], v[64:65], off offset:256
	v_add_u32_e32 v64, 0xa0, v172
	v_ashrrev_i32_e32 v65, 31, v64
	v_lshlrev_b64 v[66:67], 7, v[64:65]
	v_lshl_add_u64 v[66:67], s[12:13], 0, v[66:67]
	v_lshlrev_b64 v[98:99], 13, v[64:65]
	v_lshl_add_u64 v[64:65], v[174:175], 0, v[98:99]
	global_load_dwordx4 v[72:75], v[66:67], off
	global_load_dwordx4 v[84:87], v[64:65], off
	v_add_u32_e32 v66, 0xb0, v172
	v_ashrrev_i32_e32 v67, 31, v66
	v_lshlrev_b64 v[68:69], 7, v[66:67]
	v_lshlrev_b64 v[96:97], 13, v[66:67]
	v_mul_f32_e32 v66, 0xbfb8aa3b, v60
	v_exp_f32_e32 v122, v66
	v_lshl_add_u64 v[68:69], s[12:13], 0, v[68:69]
	global_load_dwordx4 v[76:79], v[64:65], off offset:256
	global_load_dwordx4 v[80:83], v[68:69], off
	v_lshl_add_u64 v[64:65], v[174:175], 0, v[96:97]
	v_add_f32_e32 v122, 1.0, v122
	v_rcp_f32_e32 v122, v122
	global_load_dwordx4 v[68:71], v[64:65], off
	s_nop 0
	global_load_dwordx4 v[64:67], v[64:65], off offset:256
	v_lshl_add_u64 v[110:111], s[2:3], 0, v[110:111]
	v_lshl_add_u64 v[110:111], v[110:111], 0, v[170:171]
	v_mul_f32_e32 v60, v60, v122
	s_mov_b32 s13, s4
	s_mov_b32 s12, s6
	s_waitcnt vmcnt(0)
	v_lshlrev_b32_e32 v122, 16, v102
	v_mul_f32_e32 v60, v60, v122
	v_add_f32_e32 v122, 1.0, v124
	v_rcp_f32_e32 v122, v122
	v_and_b32_e32 v102, 0xffff0000, v102
	v_mul_f32_e32 v61, v61, v102
	v_lshlrev_b32_e32 v102, 16, v103
	v_mul_f32_e32 v62, v62, v122
	v_add_f32_e32 v122, 1.0, v123
	v_mul_f32_e32 v123, 0xbfb8aa3b, v56
	v_rcp_f32_e32 v122, v122
	v_exp_f32_e32 v123, v123
	v_mul_f32_e32 v62, v62, v102
	v_and_b32_e32 v102, 0xffff0000, v103
	v_mul_f32_e32 v63, v63, v122
	v_add_f32_e32 v103, 1.0, v123
	v_mul_f32_e32 v122, 0xbfb8aa3b, v57
	v_rcp_f32_e32 v103, v103
	v_exp_f32_e32 v122, v122
	v_mul_f32_e32 v63, v63, v102
	v_lshlrev_b32_e32 v102, 16, v104
	v_mul_f32_e32 v56, v56, v103
	v_add_f32_e32 v103, 1.0, v122
	v_mul_f32_e32 v122, 0xbfb8aa3b, v58
	v_rcp_f32_e32 v103, v103
	v_exp_f32_e32 v122, v122
	v_mul_f32_e32 v56, v56, v102
	v_and_b32_e32 v102, 0xffff0000, v104
	v_mul_f32_e32 v57, v57, v103
	v_add_f32_e32 v103, 1.0, v122
	v_mul_f32_e32 v104, 0xbfb8aa3b, v59
	v_rcp_f32_e32 v103, v103
	v_exp_f32_e32 v104, v104
	v_mul_f32_e32 v57, v57, v102
	v_lshlrev_b32_e32 v102, 16, v105
	v_mul_f32_e32 v58, v58, v103
	v_add_f32_e32 v103, 1.0, v104
	v_mul_f32_e32 v104, 0xbfb8aa3b, v52
	v_rcp_f32_e32 v103, v103
	v_exp_f32_e32 v104, v104
	v_mul_f32_e32 v58, v58, v102
	v_and_b32_e32 v102, 0xffff0000, v105
	v_mul_f32_e32 v59, v59, v103
	v_add_f32_e32 v103, 1.0, v104
	v_mul_f32_e32 v104, 0xbfb8aa3b, v53
	v_rcp_f32_e32 v103, v103
	v_exp_f32_e32 v104, v104
	v_mul_f32_e32 v59, v59, v102
	v_lshlrev_b32_e32 v102, 16, v114
	v_mul_f32_e32 v52, v52, v103
	v_add_f32_e32 v103, 1.0, v104
	v_mul_f32_e32 v104, 0xbfb8aa3b, v54
	v_rcp_f32_e32 v103, v103
	v_exp_f32_e32 v104, v104
	v_mul_f32_e32 v102, v52, v102
	v_mul_f32_e32 v52, v53, v103
	v_add_f32_e32 v103, 1.0, v104
	v_mul_f32_e32 v104, 0xbfb8aa3b, v55
	v_rcp_f32_e32 v103, v103
	v_exp_f32_e32 v104, v104
	v_and_b32_e32 v53, 0xffff0000, v114
	v_mul_f32_e32 v105, v52, v53
	v_mul_f32_e32 v52, v54, v103
	v_add_f32_e32 v54, 1.0, v104
	v_rcp_f32_e32 v54, v54
	v_mul_f32_e32 v103, 0xbfb8aa3b, v48
	v_exp_f32_e32 v103, v103
	v_lshlrev_b32_e32 v53, 16, v115
	v_mul_f32_e32 v104, v52, v53
	v_mul_f32_e32 v52, v55, v54
	v_mul_f32_e32 v55, 0xbfb8aa3b, v49
	v_add_f32_e32 v54, 1.0, v103
	v_exp_f32_e32 v55, v55
	v_rcp_f32_e32 v54, v54
	v_and_b32_e32 v53, 0xffff0000, v115
	v_mul_f32_e32 v103, v52, v53
	v_add_f32_e32 v53, 1.0, v55
	v_mul_f32_e32 v48, v48, v54
	v_rcp_f32_e32 v53, v53
	v_mul_f32_e32 v54, 0xbfb8aa3b, v50
	v_exp_f32_e32 v54, v54
	v_lshlrev_b32_e32 v52, 16, v116
	v_mul_f32_e32 v55, v48, v52
	v_mul_f32_e32 v48, v49, v53
	v_and_b32_e32 v49, 0xffff0000, v116
	v_add_f32_e32 v52, 1.0, v54
	v_mul_f32_e32 v54, v48, v49
	v_mul_f32_e32 v48, 0xbfb8aa3b, v51
	v_rcp_f32_e32 v52, v52
	v_exp_f32_e32 v48, v48
	v_mov_b32_e32 v53, v108
	v_mov_b32_e32 v108, v121
	v_mul_f32_e32 v49, v50, v52
	v_lshlrev_b32_e32 v50, 16, v117
	v_add_f32_e32 v48, 1.0, v48
	v_mul_f32_e32 v114, v49, v50
	v_rcp_f32_e32 v50, v48
	v_mov_b32_e32 v48, v118
	v_mov_b32_e32 v49, v106
	v_mov_b32_e32 v106, v119
	v_pk_add_f32 v[48:49], v[48:49], v[106:107]
	v_mov_b32_e32 v52, v120
	v_pk_add_f32 v[48:49], v[52:53], v[48:49]
	s_nop 0
	v_pk_add_f32 v[48:49], v[108:109], v[48:49]
	s_nop 0
	v_pk_fma_f32 v[52:53], v[48:49], s[14:15], v[112:113] op_sel_hi:[1,0,0]
	v_mul_f32_e32 v49, v51, v50
	v_mul_f32_e32 v48, 0x4b800000, v53
	v_cmp_gt_f32_e32 vcc, s5, v53
	v_and_b32_e32 v50, 0xffff0000, v117
	s_nop 0
	v_cndmask_b32_e32 v48, v53, v48, vcc
	v_rsq_f32_e32 v48, v48
	v_mul_f32_e32 v53, v49, v50
	v_mul_f32_e32 v49, 0x45800000, v48
	v_cndmask_b32_e32 v106, v48, v49, vcc
	v_mul_f32_e32 v48, v60, v106
	v_mul_f32_e32 v49, v61, v106
	v_cvt_pk_bf16_f32 v48, v48, v49
	v_mul_f32_e32 v49, v62, v106
	v_mul_f32_e32 v50, v63, v106
	v_cvt_pk_bf16_f32 v49, v49, v50
	v_mul_f32_e32 v50, v56, v106
	v_mul_f32_e32 v51, v57, v106
	v_cvt_pk_bf16_f32 v50, v50, v51
	v_mul_f32_e32 v51, v58, v106
	v_mul_f32_e32 v56, v59, v106
	v_cvt_pk_bf16_f32 v51, v51, v56
	global_store_dwordx4 v[110:111], v[48:51], off
	v_mul_f32_e32 v53, v53, v106
	v_cmp_gt_f32_e32 vcc, s5, v52
	v_mul_f32_e32 v48, v102, v106
	v_mul_f32_e32 v49, v105, v106
	v_cvt_pk_bf16_f32 v48, v48, v49
	v_mul_f32_e32 v49, v104, v106
	v_mul_f32_e32 v50, v103, v106
	v_cvt_pk_bf16_f32 v49, v49, v50
	v_mul_f32_e32 v50, v55, v106
	v_mul_f32_e32 v51, v54, v106
	v_cvt_pk_bf16_f32 v50, v50, v51
	v_mul_f32_e32 v51, v114, v106
	v_cvt_pk_bf16_f32 v51, v51, v53
	v_mul_f32_e32 v53, 0x4b800000, v52
	v_cndmask_b32_e32 v52, v52, v53, vcc
	global_store_dwordx4 v[110:111], v[48:51], off offset:256
	v_rsq_f32_e32 v52, v52
	s_nop 0
	v_mul_f32_e32 v48, 0xbfb8aa3b, v44
	v_exp_f32_e32 v50, v48
	v_mul_f32_e32 v48, 0x45800000, v52
	v_cndmask_b32_e32 v51, v52, v48, vcc
	v_mul_f32_e32 v52, 0xbfb8aa3b, v45
	v_add_f32_e32 v50, 1.0, v50
	v_rcp_f32_e32 v50, v50
	v_exp_f32_e32 v52, v52
	v_lshl_add_u64 v[48:49], s[2:3], 0, v[100:101]
	v_lshl_add_u64 v[48:49], v[48:49], 0, v[170:171]
	v_mul_f32_e32 v44, v44, v50
	v_lshlrev_b32_e32 v50, 16, v92
	v_mul_f32_e32 v44, v44, v50
	v_add_f32_e32 v50, 1.0, v52
	v_rcp_f32_e32 v50, v50
	v_mul_f32_e32 v52, 0xbfb8aa3b, v46
	v_exp_f32_e32 v52, v52
	v_mul_f32_e32 v44, v44, v51
	v_mul_f32_e32 v45, v45, v50
	v_and_b32_e32 v50, 0xffff0000, v92
	v_mul_f32_e32 v45, v45, v50
	v_add_f32_e32 v50, 1.0, v52
	v_mul_f32_e32 v52, 0xbfb8aa3b, v47
	v_rcp_f32_e32 v50, v50
	v_exp_f32_e32 v52, v52
	v_mul_f32_e32 v45, v45, v51
	v_cvt_pk_bf16_f32 v44, v44, v45
	v_mul_f32_e32 v45, v46, v50
	v_add_f32_e32 v46, 1.0, v52
	v_rcp_f32_e32 v46, v46
	v_lshlrev_b32_e32 v50, 16, v93
	v_mul_f32_e32 v45, v45, v50
	v_and_b32_e32 v50, 0xffff0000, v93
	v_mul_f32_e32 v46, v47, v46
	v_mul_f32_e32 v47, 0xbfb8aa3b, v40
	v_exp_f32_e32 v47, v47
	v_mul_f32_e32 v46, v46, v50
	v_mul_f32_e32 v45, v45, v51
	v_mul_f32_e32 v46, v46, v51
	v_add_f32_e32 v47, 1.0, v47
	v_cvt_pk_bf16_f32 v45, v45, v46
	v_mul_f32_e32 v46, 0xbfb8aa3b, v41
	v_rcp_f32_e32 v47, v47
	v_exp_f32_e32 v46, v46
	v_mul_f32_e32 v40, v40, v47
	v_lshlrev_b32_e32 v47, 16, v94
	v_add_f32_e32 v46, 1.0, v46
	v_mul_f32_e32 v40, v40, v47
	v_rcp_f32_e32 v46, v46
	v_mul_f32_e32 v47, 0xbfb8aa3b, v42
	v_exp_f32_e32 v47, v47
	v_mul_f32_e32 v40, v40, v51
	v_mul_f32_e32 v41, v41, v46
	v_and_b32_e32 v46, 0xffff0000, v94
	v_mul_f32_e32 v41, v41, v46
	v_add_f32_e32 v46, 1.0, v47
	v_rcp_f32_e32 v47, v46
	v_mul_f32_e32 v46, 0xbfb8aa3b, v43
	v_exp_f32_e32 v50, v46
	v_mul_f32_e32 v41, v41, v51
	v_cvt_pk_bf16_f32 v46, v40, v41
	v_mul_f32_e32 v40, v42, v47
	v_add_f32_e32 v41, 1.0, v50
	v_rcp_f32_e32 v41, v41
	v_lshlrev_b32_e32 v42, 16, v95
	v_mul_f32_e32 v40, v40, v42
	v_and_b32_e32 v42, 0xffff0000, v95
	v_mul_f32_e32 v41, v43, v41
	v_mul_f32_e32 v43, 0xbfb8aa3b, v36
	v_exp_f32_e32 v43, v43
	v_mul_f32_e32 v40, v40, v51
	v_mul_f32_e32 v41, v41, v42
	v_mul_f32_e32 v41, v41, v51
	v_cvt_pk_bf16_f32 v47, v40, v41
	v_add_f32_e32 v40, 1.0, v43
	v_rcp_f32_e32 v40, v40
	v_mul_f32_e32 v41, 0xbfb8aa3b, v37
	v_exp_f32_e32 v41, v41
	global_store_dwordx4 v[48:49], v[44:47], off
	v_mul_f32_e32 v36, v36, v40
	v_lshlrev_b32_e32 v40, 16, v88
	v_mul_f32_e32 v36, v36, v40
	v_add_f32_e32 v40, 1.0, v41
	v_rcp_f32_e32 v40, v40
	v_mul_f32_e32 v41, 0xbfb8aa3b, v38
	v_exp_f32_e32 v41, v41
	v_mul_f32_e32 v36, v36, v51
	v_mul_f32_e32 v37, v37, v40
	v_and_b32_e32 v40, 0xffff0000, v88
	v_mul_f32_e32 v37, v37, v40
	v_add_f32_e32 v40, 1.0, v41
	v_mul_f32_e32 v41, 0xbfb8aa3b, v39
	v_rcp_f32_e32 v40, v40
	v_exp_f32_e32 v41, v41
	v_mul_f32_e32 v37, v37, v51
	v_cvt_pk_bf16_f32 v36, v36, v37
	v_mul_f32_e32 v37, v38, v40
	v_add_f32_e32 v38, 1.0, v41
	v_rcp_f32_e32 v38, v38
	v_lshlrev_b32_e32 v40, 16, v89
	v_mul_f32_e32 v37, v37, v40
	v_and_b32_e32 v40, 0xffff0000, v89
	v_mul_f32_e32 v38, v39, v38
	v_mul_f32_e32 v39, 0xbfb8aa3b, v32
	v_exp_f32_e32 v39, v39
	v_mul_f32_e32 v38, v38, v40
	v_mul_f32_e32 v37, v37, v51
	v_mul_f32_e32 v38, v38, v51
	v_add_f32_e32 v39, 1.0, v39
	v_cvt_pk_bf16_f32 v37, v37, v38
	v_mul_f32_e32 v38, 0xbfb8aa3b, v33
	v_rcp_f32_e32 v39, v39
	v_exp_f32_e32 v38, v38
	v_mul_f32_e32 v32, v32, v39
	v_lshlrev_b32_e32 v39, 16, v90
	v_add_f32_e32 v38, 1.0, v38
	v_mul_f32_e32 v32, v32, v39
	v_rcp_f32_e32 v38, v38
	v_mul_f32_e32 v39, 0xbfb8aa3b, v34
	v_exp_f32_e32 v39, v39
	v_mul_f32_e32 v32, v32, v51
	v_mul_f32_e32 v33, v33, v38
	v_and_b32_e32 v38, 0xffff0000, v90
	v_mul_f32_e32 v33, v33, v38
	v_add_f32_e32 v38, 1.0, v39
	v_rcp_f32_e32 v39, v38
	v_mul_f32_e32 v38, 0xbfb8aa3b, v35
	v_exp_f32_e32 v40, v38
	v_mul_f32_e32 v33, v33, v51
	v_cvt_pk_bf16_f32 v38, v32, v33
	v_mul_f32_e32 v32, v34, v39
	v_add_f32_e32 v33, 1.0, v40
	v_rcp_f32_e32 v33, v33
	v_lshlrev_b32_e32 v34, 16, v91
	v_mul_f32_e32 v32, v32, v34
	v_and_b32_e32 v34, 0xffff0000, v91
	v_mul_f32_e32 v33, v35, v33
	v_mul_f32_e32 v35, 0xbfb8aa3b, v29
	v_exp_f32_e32 v35, v35
	v_mul_f32_e32 v33, v33, v34
	v_mul_f32_e32 v32, v32, v51
	v_mul_f32_e32 v33, v33, v51
	v_cvt_pk_bf16_f32 v39, v32, v33
	global_store_dwordx4 v[48:49], v[36:39], off offset:256
	v_add_f32_e32 v35, 1.0, v35
	v_rcp_f32_e32 v35, v35
	v_mul_f32_e32 v36, 0xbfb8aa3b, v30
	v_exp_f32_e32 v36, v36
	v_mul_f32_e32 v34, 0xbfb8aa3b, v28
	v_mul_f32_e32 v29, v29, v35
	v_exp_f32_e32 v34, v34
	v_add_f32_e32 v35, 1.0, v36
	v_mul_f32_e32 v36, 0xbfb8aa3b, v31
	v_rcp_f32_e32 v35, v35
	v_exp_f32_e32 v36, v36
	v_add_f32_e32 v34, 1.0, v34
	v_rcp_f32_e32 v34, v34
	v_mul_f32_e32 v30, v30, v35
	v_add_f32_e32 v35, 1.0, v36
	v_mul_f32_e32 v36, 0xbfb8aa3b, v24
	v_rcp_f32_e32 v35, v35
	v_exp_f32_e32 v36, v36
	v_mul_f32_e32 v28, v28, v34
	v_lshlrev_b32_e32 v34, 16, v84
	v_mul_f32_e32 v31, v31, v35
	v_add_f32_e32 v35, 1.0, v36
	v_mul_f32_e32 v36, 0xbfb8aa3b, v25
	v_rcp_f32_e32 v35, v35
	v_exp_f32_e32 v36, v36
	v_mul_f32_e32 v28, v28, v34
	v_and_b32_e32 v34, 0xffff0000, v84
	v_mul_f32_e32 v24, v24, v35
	v_add_f32_e32 v35, 1.0, v36
	v_mul_f32_e32 v36, 0xbfb8aa3b, v26
	v_rcp_f32_e32 v35, v35
	v_exp_f32_e32 v36, v36
	v_mul_f32_e32 v29, v29, v34
	v_lshlrev_b32_e32 v34, 16, v85
	v_mul_f32_e32 v25, v25, v35
	v_add_f32_e32 v35, 1.0, v36
	v_mul_f32_e32 v36, 0xbfb8aa3b, v27
	v_rcp_f32_e32 v35, v35
	v_exp_f32_e32 v36, v36
	v_mul_f32_e32 v30, v30, v34
	v_and_b32_e32 v34, 0xffff0000, v85
	v_mul_f32_e32 v26, v26, v35
	v_add_f32_e32 v35, 1.0, v36
	v_mul_f32_e32 v36, 0xbfb8aa3b, v20
	v_rcp_f32_e32 v35, v35
	v_exp_f32_e32 v36, v36
	v_mul_f32_e32 v31, v31, v34
	v_lshlrev_b32_e32 v34, 16, v86
	v_mul_f32_e32 v27, v27, v35
	v_add_f32_e32 v35, 1.0, v36
	v_mul_f32_e32 v36, 0xbfb8aa3b, v21
	v_rcp_f32_e32 v35, v35
	v_exp_f32_e32 v36, v36
	v_mul_f32_e32 v24, v24, v34
	v_and_b32_e32 v34, 0xffff0000, v86
	v_mul_f32_e32 v20, v20, v35
	v_add_f32_e32 v35, 1.0, v36
	v_mul_f32_e32 v36, 0xbfb8aa3b, v22
	v_rcp_f32_e32 v35, v35
	v_exp_f32_e32 v36, v36
	v_mul_f32_e32 v25, v25, v34
	v_lshlrev_b32_e32 v34, 16, v87
	v_mul_f32_e32 v26, v26, v34
	v_and_b32_e32 v34, 0xffff0000, v87
	v_mul_f32_e32 v27, v27, v34
	v_lshlrev_b32_e32 v34, 16, v76
	v_mul_f32_e32 v34, v20, v34
	v_mul_f32_e32 v20, v21, v35
	v_add_f32_e32 v35, 1.0, v36
	v_mul_f32_e32 v36, 0xbfb8aa3b, v23
	v_rcp_f32_e32 v35, v35
	v_exp_f32_e32 v36, v36
	v_and_b32_e32 v21, 0xffff0000, v76
	v_mul_f32_e32 v37, v20, v21
	v_mul_f32_e32 v20, v22, v35
	v_add_f32_e32 v22, 1.0, v36
	v_rcp_f32_e32 v22, v22
	v_mul_f32_e32 v35, 0xbfb8aa3b, v16
	v_exp_f32_e32 v35, v35
	v_lshlrev_b32_e32 v21, 16, v77
	v_mul_f32_e32 v36, v20, v21
	v_mul_f32_e32 v20, v23, v22
	v_mul_f32_e32 v23, 0xbfb8aa3b, v17
	v_add_f32_e32 v22, 1.0, v35
	v_exp_f32_e32 v23, v23
	v_rcp_f32_e32 v22, v22
	v_and_b32_e32 v21, 0xffff0000, v77
	v_mul_f32_e32 v35, v20, v21
	v_add_f32_e32 v21, 1.0, v23
	v_mul_f32_e32 v16, v16, v22
	v_rcp_f32_e32 v21, v21
	v_mul_f32_e32 v22, 0xbfb8aa3b, v18
	v_exp_f32_e32 v22, v22
	v_lshlrev_b32_e32 v20, 16, v78
	v_mul_f32_e32 v23, v16, v20
	v_mul_f32_e32 v16, v17, v21
	v_and_b32_e32 v17, 0xffff0000, v78
	v_add_f32_e32 v20, 1.0, v22
	v_mul_f32_e32 v22, v16, v17
	v_mul_f32_e32 v16, 0xbfb8aa3b, v19
	v_rcp_f32_e32 v20, v20
	v_exp_f32_e32 v16, v16
	v_mov_b32_e32 v21, v74
	v_mov_b32_e32 v74, v83
	v_mul_f32_e32 v17, v18, v20
	v_lshlrev_b32_e32 v18, 16, v79
	v_add_f32_e32 v16, 1.0, v16
	v_mul_f32_e32 v38, v17, v18
	v_rcp_f32_e32 v18, v16
	v_mov_b32_e32 v16, v80
	v_mov_b32_e32 v17, v72
	v_mov_b32_e32 v72, v81
	v_pk_add_f32 v[16:17], v[16:17], v[72:73]
	v_mov_b32_e32 v20, v82
	v_pk_add_f32 v[16:17], v[20:21], v[16:17]
	v_lshl_add_u64 v[32:33], s[2:3], 0, v[98:99]
	v_pk_add_f32 v[16:17], v[74:75], v[16:17]
	v_lshl_add_u64 v[32:33], v[32:33], 0, v[170:171]
	v_pk_fma_f32 v[20:21], v[16:17], s[14:15], v[112:113] op_sel_hi:[1,0,0]
	v_mul_f32_e32 v17, v19, v18
	v_mul_f32_e32 v16, 0x4b800000, v21
	v_cmp_gt_f32_e32 vcc, s5, v21
	v_and_b32_e32 v18, 0xffff0000, v79
	s_mov_b64 s[14:15], s[8:9]
	v_cndmask_b32_e32 v16, v21, v16, vcc
	v_rsq_f32_e32 v16, v16
	v_mul_f32_e32 v21, v17, v18
	v_mul_f32_e32 v17, 0x45800000, v16
	v_cndmask_b32_e32 v39, v16, v17, vcc
	v_mul_f32_e32 v16, v28, v39
	v_mul_f32_e32 v17, v29, v39
	v_cvt_pk_bf16_f32 v16, v16, v17
	v_mul_f32_e32 v17, v30, v39
	v_mul_f32_e32 v18, v31, v39
	v_cvt_pk_bf16_f32 v17, v17, v18
	v_mul_f32_e32 v18, v24, v39
	v_mul_f32_e32 v19, v25, v39
	v_cvt_pk_bf16_f32 v18, v18, v19
	v_mul_f32_e32 v19, v26, v39
	v_mul_f32_e32 v24, v27, v39
	v_cvt_pk_bf16_f32 v19, v19, v24
	global_store_dwordx4 v[32:33], v[16:19], off
	v_mul_f32_e32 v21, v21, v39
	v_cmp_gt_f32_e32 vcc, s5, v20
	v_mul_f32_e32 v16, v34, v39
	v_mul_f32_e32 v17, v37, v39
	v_cvt_pk_bf16_f32 v16, v16, v17
	v_mul_f32_e32 v17, v36, v39
	v_mul_f32_e32 v18, v35, v39
	v_cvt_pk_bf16_f32 v17, v17, v18
	v_mul_f32_e32 v18, v23, v39
	v_mul_f32_e32 v19, v22, v39
	v_cvt_pk_bf16_f32 v18, v18, v19
	v_mul_f32_e32 v19, v38, v39
	v_cvt_pk_bf16_f32 v19, v19, v21
	v_mul_f32_e32 v21, 0x4b800000, v20
	v_cndmask_b32_e32 v20, v20, v21, vcc
	global_store_dwordx4 v[32:33], v[16:19], off offset:256
	v_rsq_f32_e32 v20, v20
	s_nop 0
	v_mul_f32_e32 v16, 0xbfb8aa3b, v12
	v_exp_f32_e32 v18, v16
	v_mul_f32_e32 v16, 0x45800000, v20
	v_cndmask_b32_e32 v19, v20, v16, vcc
	v_mul_f32_e32 v20, 0xbfb8aa3b, v13
	v_add_f32_e32 v18, 1.0, v18
	v_rcp_f32_e32 v18, v18
	v_exp_f32_e32 v20, v20
	v_lshl_add_u64 v[16:17], s[2:3], 0, v[96:97]
	v_lshl_add_u64 v[16:17], v[16:17], 0, v[170:171]
	v_mul_f32_e32 v12, v12, v18
	v_lshlrev_b32_e32 v18, 16, v68
	v_mul_f32_e32 v12, v12, v18
	v_add_f32_e32 v18, 1.0, v20
	v_rcp_f32_e32 v18, v18
	v_mul_f32_e32 v20, 0xbfb8aa3b, v14
	v_exp_f32_e32 v20, v20
	v_mul_f32_e32 v12, v12, v19
	v_mul_f32_e32 v13, v13, v18
	v_and_b32_e32 v18, 0xffff0000, v68
	v_mul_f32_e32 v13, v13, v18
	v_add_f32_e32 v18, 1.0, v20
	v_mul_f32_e32 v20, 0xbfb8aa3b, v15
	v_rcp_f32_e32 v18, v18
	v_exp_f32_e32 v20, v20
	v_mul_f32_e32 v13, v13, v19
	v_cvt_pk_bf16_f32 v12, v12, v13
	v_mul_f32_e32 v13, v14, v18
	v_add_f32_e32 v14, 1.0, v20
	v_rcp_f32_e32 v14, v14
	v_lshlrev_b32_e32 v18, 16, v69
	v_mul_f32_e32 v13, v13, v18
	v_and_b32_e32 v18, 0xffff0000, v69
	v_mul_f32_e32 v14, v15, v14
	v_mul_f32_e32 v15, 0xbfb8aa3b, v8
	v_exp_f32_e32 v15, v15
	v_mul_f32_e32 v14, v14, v18
	v_mul_f32_e32 v13, v13, v19
	v_mul_f32_e32 v14, v14, v19
	v_add_f32_e32 v15, 1.0, v15
	v_cvt_pk_bf16_f32 v13, v13, v14
	v_mul_f32_e32 v14, 0xbfb8aa3b, v9
	v_rcp_f32_e32 v15, v15
	v_exp_f32_e32 v14, v14
	s_and_b64 vcc, exec, s[0:1]
	v_mul_f32_e32 v8, v8, v15
	v_lshlrev_b32_e32 v15, 16, v70
	v_add_f32_e32 v14, 1.0, v14
	v_mul_f32_e32 v8, v8, v15
	v_rcp_f32_e32 v14, v14
	v_mul_f32_e32 v15, 0xbfb8aa3b, v10
	v_exp_f32_e32 v15, v15
	v_mul_f32_e32 v8, v8, v19
	v_mul_f32_e32 v9, v9, v14
	v_and_b32_e32 v14, 0xffff0000, v70
	v_mul_f32_e32 v9, v9, v14
	v_add_f32_e32 v14, 1.0, v15
	v_rcp_f32_e32 v15, v14
	v_mul_f32_e32 v14, 0xbfb8aa3b, v11
	v_exp_f32_e32 v18, v14
	v_mul_f32_e32 v9, v9, v19
	v_cvt_pk_bf16_f32 v14, v8, v9
	v_mul_f32_e32 v8, v10, v15
	v_add_f32_e32 v9, 1.0, v18
	v_rcp_f32_e32 v9, v9
	v_lshlrev_b32_e32 v10, 16, v71
	v_mul_f32_e32 v8, v8, v10
	v_and_b32_e32 v10, 0xffff0000, v71
	v_mul_f32_e32 v9, v11, v9
	v_mul_f32_e32 v11, 0xbfb8aa3b, v4
	v_exp_f32_e32 v11, v11
	v_mul_f32_e32 v8, v8, v19
	v_mul_f32_e32 v9, v9, v10
	v_mul_f32_e32 v9, v9, v19
	v_cvt_pk_bf16_f32 v15, v8, v9
	v_add_f32_e32 v8, 1.0, v11
	v_rcp_f32_e32 v8, v8
	v_mul_f32_e32 v9, 0xbfb8aa3b, v5
	v_exp_f32_e32 v9, v9
	global_store_dwordx4 v[16:17], v[12:15], off
	v_mul_f32_e32 v4, v4, v8
	v_lshlrev_b32_e32 v8, 16, v64
	v_mul_f32_e32 v4, v4, v8
	v_add_f32_e32 v8, 1.0, v9
	v_rcp_f32_e32 v8, v8
	v_mul_f32_e32 v9, 0xbfb8aa3b, v6
	v_exp_f32_e32 v9, v9
	v_mul_f32_e32 v4, v4, v19
	v_mul_f32_e32 v5, v5, v8
	v_and_b32_e32 v8, 0xffff0000, v64
	v_mul_f32_e32 v5, v5, v8
	v_add_f32_e32 v8, 1.0, v9
	v_mul_f32_e32 v9, 0xbfb8aa3b, v7
	v_rcp_f32_e32 v8, v8
	v_exp_f32_e32 v9, v9
	v_mul_f32_e32 v5, v5, v19
	v_cvt_pk_bf16_f32 v4, v4, v5
	v_mul_f32_e32 v5, v6, v8
	v_add_f32_e32 v6, 1.0, v9
	v_rcp_f32_e32 v6, v6
	v_lshlrev_b32_e32 v8, 16, v65
	v_mul_f32_e32 v5, v5, v8
	v_and_b32_e32 v8, 0xffff0000, v65
	v_mul_f32_e32 v6, v7, v6
	v_mul_f32_e32 v7, 0xbfb8aa3b, v0
	v_exp_f32_e32 v7, v7
	v_mul_f32_e32 v6, v6, v8
	v_mul_f32_e32 v5, v5, v19
	v_mul_f32_e32 v6, v6, v19
	v_add_f32_e32 v7, 1.0, v7
	v_cvt_pk_bf16_f32 v5, v5, v6
	v_mul_f32_e32 v6, 0xbfb8aa3b, v1
	v_rcp_f32_e32 v7, v7
	v_exp_f32_e32 v6, v6
	v_mul_f32_e32 v0, v0, v7
	v_lshlrev_b32_e32 v7, 16, v66
	v_add_f32_e32 v6, 1.0, v6
	v_mul_f32_e32 v0, v0, v7
	v_rcp_f32_e32 v6, v6
	v_mul_f32_e32 v7, 0xbfb8aa3b, v2
	v_exp_f32_e32 v7, v7
	v_mul_f32_e32 v0, v0, v19
	v_mul_f32_e32 v1, v1, v6
	v_and_b32_e32 v6, 0xffff0000, v66
	v_mul_f32_e32 v1, v1, v6
	v_add_f32_e32 v6, 1.0, v7
	v_rcp_f32_e32 v7, v6
	v_mul_f32_e32 v6, 0xbfb8aa3b, v3
	v_exp_f32_e32 v8, v6
	v_mul_f32_e32 v1, v1, v19
	v_cvt_pk_bf16_f32 v6, v0, v1
	v_mul_f32_e32 v0, v2, v7
	v_add_f32_e32 v1, 1.0, v8
	v_rcp_f32_e32 v1, v1
	v_lshlrev_b32_e32 v2, 16, v67
	v_mul_f32_e32 v0, v0, v2
	v_and_b32_e32 v2, 0xffff0000, v67
	v_mul_f32_e32 v1, v3, v1
	v_mul_f32_e32 v1, v1, v2
	v_mul_f32_e32 v0, v0, v19
	v_mul_f32_e32 v1, v1, v19
	v_cvt_pk_bf16_f32 v7, v0, v1
	global_store_dwordx4 v[16:17], v[4:7], off offset:256
	s_cbranch_vccz .LBB0_80
	s_waitcnt vmcnt(0)
	s_cmpk_gt_u32 s21, 0xff
	s_cbranch_scc1 .LBB0_91
	s_barrier

.LBB0_200:
	s_add_u32 s16, s14, 0xfff80080
	s_addc_u32 s17, s15, -1
	s_add_i32 s41, 0, 0x10000
	v_add_u32_e32 v140, s41, v238
	ds_read_b128 v[128:131], v140
	ds_read_b128 v[132:135], v140 offset:1024
	ds_read_b128 v[136:139], v140 offset:2048
	ds_read_b128 v[140:143], v140 offset:3072
	s_cmp_eq_u32 s40, 28
	s_cselect_b32 s19, s5, s17
	s_cselect_b32 s18, s9, s16
	s_cselect_b32 s17, s7, s39
	s_cselect_b32 s16, s37, s38
	v_lshl_add_u64 v[176:177], s[14:15], 0, v[218:219]
	s_add_i32 m0, s28, 0xc000
	ds_read_b128 v[144:147], v240
	ds_read_b128 v[148:151], v240 offset:1024
	ds_read_b128 v[152:155], v240 offset:2048
	ds_read_b128 v[156:159], v240 offset:3072
	ds_read_b128 v[160:163], v240 offset:4096
	ds_read_b128 v[164:167], v240 offset:5120
	ds_read_b128 v[168:171], v240 offset:6144
	ds_read_b128 v[172:175], v240 offset:7168
	global_load_lds_dwordx4 v[176:177], off
	v_lshl_add_u64 v[176:177], s[14:15], 0, v[220:221]
	s_add_i32 m0, s28, 0xe000
	s_nop 0
	global_load_lds_dwordx4 v[176:177], off
	s_waitcnt lgkmcnt(8)
	s_barrier
	s_waitcnt lgkmcnt(0)
	s_waitcnt lgkmcnt(0)
	v_mfma_f32_16x16x32_bf16 v[124:127], v[128:131], v[144:147], v[124:127]
	v_mfma_f32_16x16x32_bf16 v[120:123], v[136:139], v[144:147], v[120:123]
	v_mfma_f32_16x16x32_bf16 v[116:119], v[128:131], v[152:155], v[116:119]
	v_mfma_f32_16x16x32_bf16 v[108:111], v[136:139], v[152:155], v[108:111]
	v_mfma_f32_16x16x32_bf16 v[100:103], v[128:131], v[160:163], v[100:103]
	v_mfma_f32_16x16x32_bf16 v[92:95], v[136:139], v[160:163], v[92:95]
	v_mfma_f32_16x16x32_bf16 v[84:87], v[128:131], v[168:171], v[84:87]
	v_mfma_f32_16x16x32_bf16 v[76:79], v[136:139], v[168:171], v[76:79]
	v_mfma_f32_16x16x32_bf16 v[124:127], v[132:135], v[148:151], v[124:127]
	v_mfma_f32_16x16x32_bf16 v[120:123], v[140:143], v[148:151], v[120:123]
	v_mfma_f32_16x16x32_bf16 v[116:119], v[132:135], v[156:159], v[116:119]
	v_mfma_f32_16x16x32_bf16 v[108:111], v[140:143], v[156:159], v[108:111]
	v_mfma_f32_16x16x32_bf16 v[100:103], v[132:135], v[164:167], v[100:103]
	v_mfma_f32_16x16x32_bf16 v[92:95], v[140:143], v[164:167], v[92:95]
	v_mfma_f32_16x16x32_bf16 v[84:87], v[132:135], v[172:175], v[84:87]
	v_mfma_f32_16x16x32_bf16 v[76:79], v[140:143], v[172:175], v[76:79]
	s_barrier
	s_add_i32 s44, 0, 0x14000
	s_add_i32 s41, s41, s27
	v_add_u32_e32 v188, s44, v238
	v_lshl_add_u64 v[196:197], s[16:17], 0, v[206:207]
	s_mov_b32 m0, s41
	ds_read_b128 v[176:179], v188
	ds_read_b128 v[180:183], v188 offset:1024
	ds_read_b128 v[184:187], v188 offset:2048
	ds_read_b128 v[188:191], v188 offset:3072
	global_load_lds_dwordx4 v[196:197], off
	v_lshl_add_u64 v[198:199], s[16:17], 0, v[210:211]
	s_add_i32 m0, s41, 0x2000
	s_nop 0
	global_load_lds_dwordx4 v[198:199], off
	s_barrier
	s_waitcnt lgkmcnt(0)
	s_waitcnt lgkmcnt(0)
	v_mfma_f32_16x16x32_bf16 v[112:115], v[176:179], v[144:147], v[112:115]
	v_mfma_f32_16x16x32_bf16 v[104:107], v[184:187], v[144:147], v[104:107]
	v_mfma_f32_16x16x32_bf16 v[96:99], v[176:179], v[152:155], v[96:99]
	v_mfma_f32_16x16x32_bf16 v[88:91], v[184:187], v[152:155], v[88:91]
	v_mfma_f32_16x16x32_bf16 v[80:83], v[176:179], v[160:163], v[80:83]
	v_mfma_f32_16x16x32_bf16 v[72:75], v[184:187], v[160:163], v[72:75]
	v_mfma_f32_16x16x32_bf16 v[68:71], v[176:179], v[168:171], v[68:71]
	v_mfma_f32_16x16x32_bf16 v[64:67], v[184:187], v[168:171], v[64:67]
	v_mfma_f32_16x16x32_bf16 v[112:115], v[180:183], v[148:151], v[112:115]
	v_mfma_f32_16x16x32_bf16 v[104:107], v[188:191], v[148:151], v[104:107]
	v_mfma_f32_16x16x32_bf16 v[96:99], v[180:183], v[156:159], v[96:99]
	v_mfma_f32_16x16x32_bf16 v[88:91], v[188:191], v[156:159], v[88:91]
	v_mfma_f32_16x16x32_bf16 v[80:83], v[180:183], v[164:167], v[80:83]
	v_mfma_f32_16x16x32_bf16 v[72:75], v[188:191], v[164:167], v[72:75]
	v_mfma_f32_16x16x32_bf16 v[68:71], v[180:183], v[172:175], v[68:71]
	v_mfma_f32_16x16x32_bf16 v[64:67], v[188:191], v[172:175], v[64:67]
	s_mov_b32 m0, s28
	v_lshl_add_u64 v[222:223], s[18:19], 0, v[204:205]
	s_barrier
	ds_read_b128 v[144:147], v240 offset:16384
	ds_read_b128 v[148:151], v240 offset:17408
	ds_read_b128 v[152:155], v240 offset:18432
	ds_read_b128 v[156:159], v240 offset:19456
	ds_read_b128 v[160:163], v240 offset:20480
	ds_read_b128 v[164:167], v240 offset:21504
	ds_read_b128 v[168:171], v240 offset:22528
	ds_read_b128 v[172:175], v240 offset:23552
	global_load_lds_dwordx4 v[222:223], off
	v_lshl_add_u64 v[224:225], s[18:19], 0, v[208:209]
	s_mov_b32 m0, s29
	s_nop 0
	global_load_lds_dwordx4 v[224:225], off
	s_barrier
	s_waitcnt lgkmcnt(0)
	s_waitcnt lgkmcnt(0)
	v_mfma_f32_16x16x32_bf16 v[60:63], v[128:131], v[144:147], v[60:63]
	v_mfma_f32_16x16x32_bf16 v[56:59], v[136:139], v[144:147], v[56:59]
	v_mfma_f32_16x16x32_bf16 v[52:55], v[128:131], v[152:155], v[52:55]
	v_mfma_f32_16x16x32_bf16 v[44:47], v[136:139], v[152:155], v[44:47]
	v_mfma_f32_16x16x32_bf16 v[36:39], v[128:131], v[160:163], v[36:39]
	v_mfma_f32_16x16x32_bf16 v[28:31], v[136:139], v[160:163], v[28:31]
	v_mfma_f32_16x16x32_bf16 v[20:23], v[128:131], v[168:171], v[20:23]
	v_mfma_f32_16x16x32_bf16 v[12:15], v[136:139], v[168:171], v[12:15]
	v_mfma_f32_16x16x32_bf16 v[60:63], v[132:135], v[148:151], v[60:63]
	v_mfma_f32_16x16x32_bf16 v[56:59], v[140:143], v[148:151], v[56:59]
	v_mfma_f32_16x16x32_bf16 v[52:55], v[132:135], v[156:159], v[52:55]
	v_mfma_f32_16x16x32_bf16 v[44:47], v[140:143], v[156:159], v[44:47]
	v_mfma_f32_16x16x32_bf16 v[36:39], v[132:135], v[164:167], v[36:39]
	v_mfma_f32_16x16x32_bf16 v[28:31], v[140:143], v[164:167], v[28:31]
	v_mfma_f32_16x16x32_bf16 v[20:23], v[132:135], v[172:175], v[20:23]
	v_mfma_f32_16x16x32_bf16 v[12:15], v[140:143], v[172:175], v[12:15]
	s_barrier
	s_add_u32 s42, s16, 0x80000
	s_addc_u32 s43, s17, 0
	s_add_i32 s41, s44, s27
	v_lshl_add_u64 v[128:129], s[42:43], 0, v[206:207]
	s_mov_b32 m0, s41
	s_nop 0
	global_load_lds_dwordx4 v[128:129], off
	v_lshl_add_u64 v[128:129], s[42:43], 0, v[210:211]
	s_add_i32 m0, s41, 0x2000
	s_nop 0
	global_load_lds_dwordx4 v[128:129], off
	s_waitcnt vmcnt(6)
	s_barrier
	v_mfma_f32_16x16x32_bf16 v[48:51], v[176:179], v[144:147], v[48:51]
	v_mfma_f32_16x16x32_bf16 v[40:43], v[184:187], v[144:147], v[40:43]
	v_mfma_f32_16x16x32_bf16 v[32:35], v[176:179], v[152:155], v[32:35]
	v_mfma_f32_16x16x32_bf16 v[24:27], v[184:187], v[152:155], v[24:27]
	v_mfma_f32_16x16x32_bf16 v[16:19], v[176:179], v[160:163], v[16:19]
	v_mfma_f32_16x16x32_bf16 v[8:11], v[184:187], v[160:163], v[8:11]
	v_mfma_f32_16x16x32_bf16 v[4:7], v[176:179], v[168:171], v[4:7]
	v_mfma_f32_16x16x32_bf16 v[0:3], v[184:187], v[168:171], v[0:3]
	v_mfma_f32_16x16x32_bf16 v[48:51], v[180:183], v[148:151], v[48:51]
	v_mfma_f32_16x16x32_bf16 v[40:43], v[188:191], v[148:151], v[40:43]
	v_mfma_f32_16x16x32_bf16 v[32:35], v[180:183], v[156:159], v[32:35]
	v_mfma_f32_16x16x32_bf16 v[24:27], v[188:191], v[156:159], v[24:27]
	v_mfma_f32_16x16x32_bf16 v[16:19], v[180:183], v[164:167], v[16:19]
	v_mfma_f32_16x16x32_bf16 v[8:11], v[188:191], v[164:167], v[8:11]
	v_mfma_f32_16x16x32_bf16 v[4:7], v[180:183], v[172:175], v[4:7]
	v_mfma_f32_16x16x32_bf16 v[0:3], v[188:191], v[172:175], v[0:3]
	s_add_i32 s41, 0, 0x18000
	v_add_u32_e32 v140, s41, v238
	s_barrier
	ds_read_b128 v[128:131], v140
	ds_read_b128 v[132:135], v140 offset:1024
	ds_read_b128 v[136:139], v140 offset:2048
	ds_read_b128 v[140:143], v140 offset:3072
	s_add_u32 s18, s18, 0x80000
	s_addc_u32 s19, s19, 0
	s_mov_b32 m0, s30
	v_lshl_add_u64 v[176:177], s[18:19], 0, v[204:205]
	ds_read_b128 v[144:147], v240 offset:32768
	ds_read_b128 v[148:151], v240 offset:33792
	ds_read_b128 v[152:155], v240 offset:34816
	ds_read_b128 v[156:159], v240 offset:35840
	ds_read_b128 v[160:163], v240 offset:36864
	ds_read_b128 v[164:167], v240 offset:37888
	ds_read_b128 v[168:171], v240 offset:38912
	ds_read_b128 v[172:175], v240 offset:39936
	global_load_lds_dwordx4 v[176:177], off
	v_lshl_add_u64 v[176:177], s[18:19], 0, v[208:209]
	s_mov_b32 m0, s31
	s_nop 0
	global_load_lds_dwordx4 v[176:177], off
	s_waitcnt lgkmcnt(8)
	s_barrier
	s_waitcnt lgkmcnt(0)
	s_waitcnt lgkmcnt(0)
	v_mfma_f32_16x16x32_bf16 v[124:127], v[128:131], v[144:147], v[124:127]
	v_mfma_f32_16x16x32_bf16 v[120:123], v[136:139], v[144:147], v[120:123]
	v_mfma_f32_16x16x32_bf16 v[116:119], v[128:131], v[152:155], v[116:119]
	v_mfma_f32_16x16x32_bf16 v[108:111], v[136:139], v[152:155], v[108:111]
	v_mfma_f32_16x16x32_bf16 v[100:103], v[128:131], v[160:163], v[100:103]
	v_mfma_f32_16x16x32_bf16 v[92:95], v[136:139], v[160:163], v[92:95]
	v_mfma_f32_16x16x32_bf16 v[84:87], v[128:131], v[168:171], v[84:87]
	v_mfma_f32_16x16x32_bf16 v[76:79], v[136:139], v[168:171], v[76:79]
	v_mfma_f32_16x16x32_bf16 v[124:127], v[132:135], v[148:151], v[124:127]
	v_mfma_f32_16x16x32_bf16 v[120:123], v[140:143], v[148:151], v[120:123]
	v_mfma_f32_16x16x32_bf16 v[116:119], v[132:135], v[156:159], v[116:119]
	v_mfma_f32_16x16x32_bf16 v[108:111], v[140:143], v[156:159], v[108:111]
	v_mfma_f32_16x16x32_bf16 v[100:103], v[132:135], v[164:167], v[100:103]
	v_mfma_f32_16x16x32_bf16 v[92:95], v[140:143], v[164:167], v[92:95]
	v_mfma_f32_16x16x32_bf16 v[84:87], v[132:135], v[172:175], v[84:87]
	v_mfma_f32_16x16x32_bf16 v[76:79], v[140:143], v[172:175], v[76:79]
	s_barrier
	s_add_i32 s18, 0, 0x1c000
	s_add_i32 s19, s41, s27
	v_add_u32_e32 v188, s18, v238
	v_lshl_add_u64 v[196:197], v[196:197], 0, s[48:49]
	s_mov_b32 m0, s19
	ds_read_b128 v[176:179], v188
	ds_read_b128 v[180:183], v188 offset:1024
	ds_read_b128 v[184:187], v188 offset:2048
	ds_read_b128 v[188:191], v188 offset:3072
	global_load_lds_dwordx4 v[196:197], off
	v_lshl_add_u64 v[196:197], v[198:199], 0, s[48:49]
	s_add_i32 m0, s19, 0x2000
	s_nop 0
	global_load_lds_dwordx4 v[196:197], off
	s_barrier
	s_waitcnt lgkmcnt(0)
	s_waitcnt lgkmcnt(0)
	v_mfma_f32_16x16x32_bf16 v[112:115], v[176:179], v[144:147], v[112:115]
	v_mfma_f32_16x16x32_bf16 v[104:107], v[184:187], v[144:147], v[104:107]
	v_mfma_f32_16x16x32_bf16 v[96:99], v[176:179], v[152:155], v[96:99]
	v_mfma_f32_16x16x32_bf16 v[88:91], v[184:187], v[152:155], v[88:91]
	v_mfma_f32_16x16x32_bf16 v[80:83], v[176:179], v[160:163], v[80:83]
	v_mfma_f32_16x16x32_bf16 v[72:75], v[184:187], v[160:163], v[72:75]
	v_mfma_f32_16x16x32_bf16 v[68:71], v[176:179], v[168:171], v[68:71]
	v_mfma_f32_16x16x32_bf16 v[64:67], v[184:187], v[168:171], v[64:67]
	v_mfma_f32_16x16x32_bf16 v[112:115], v[180:183], v[148:151], v[112:115]
	v_mfma_f32_16x16x32_bf16 v[104:107], v[188:191], v[148:151], v[104:107]
	v_mfma_f32_16x16x32_bf16 v[96:99], v[180:183], v[156:159], v[96:99]
	v_mfma_f32_16x16x32_bf16 v[88:91], v[188:191], v[156:159], v[88:91]
	v_mfma_f32_16x16x32_bf16 v[80:83], v[180:183], v[164:167], v[80:83]
	v_mfma_f32_16x16x32_bf16 v[72:75], v[188:191], v[164:167], v[72:75]
	v_mfma_f32_16x16x32_bf16 v[68:71], v[180:183], v[172:175], v[68:71]
	v_mfma_f32_16x16x32_bf16 v[64:67], v[188:191], v[172:175], v[64:67]
	s_mov_b32 m0, s33
	v_lshl_add_u64 v[196:197], v[222:223], 0, s[48:49]
	s_barrier
	ds_read_b128 v[144:147], v240 offset:49152
	ds_read_b128 v[148:151], v240 offset:50176
	ds_read_b128 v[152:155], v240 offset:51200
	ds_read_b128 v[156:159], v240 offset:52224
	ds_read_b128 v[160:163], v240 offset:53248
	ds_read_b128 v[164:167], v240 offset:54272
	ds_read_b128 v[168:171], v240 offset:55296
	ds_read_b128 v[172:175], v240 offset:56320
	global_load_lds_dwordx4 v[196:197], off
	v_lshl_add_u64 v[196:197], v[224:225], 0, s[48:49]
	s_mov_b32 m0, s34
	s_nop 0
	global_load_lds_dwordx4 v[196:197], off
	s_barrier
	s_waitcnt lgkmcnt(0)
	s_waitcnt lgkmcnt(0)
	v_mfma_f32_16x16x32_bf16 v[60:63], v[128:131], v[144:147], v[60:63]
	v_mfma_f32_16x16x32_bf16 v[56:59], v[136:139], v[144:147], v[56:59]
	v_mfma_f32_16x16x32_bf16 v[52:55], v[128:131], v[152:155], v[52:55]
	v_mfma_f32_16x16x32_bf16 v[44:47], v[136:139], v[152:155], v[44:47]
	v_mfma_f32_16x16x32_bf16 v[36:39], v[128:131], v[160:163], v[36:39]
	v_mfma_f32_16x16x32_bf16 v[28:31], v[136:139], v[160:163], v[28:31]
	v_mfma_f32_16x16x32_bf16 v[20:23], v[128:131], v[168:171], v[20:23]
	v_mfma_f32_16x16x32_bf16 v[12:15], v[136:139], v[168:171], v[12:15]
	v_mfma_f32_16x16x32_bf16 v[60:63], v[132:135], v[148:151], v[60:63]
	v_mfma_f32_16x16x32_bf16 v[56:59], v[140:143], v[148:151], v[56:59]
	v_mfma_f32_16x16x32_bf16 v[52:55], v[132:135], v[156:159], v[52:55]
	v_mfma_f32_16x16x32_bf16 v[44:47], v[140:143], v[156:159], v[44:47]
	v_mfma_f32_16x16x32_bf16 v[36:39], v[132:135], v[164:167], v[36:39]
	v_mfma_f32_16x16x32_bf16 v[28:31], v[140:143], v[164:167], v[28:31]
	v_mfma_f32_16x16x32_bf16 v[20:23], v[132:135], v[172:175], v[20:23]
	v_mfma_f32_16x16x32_bf16 v[12:15], v[140:143], v[172:175], v[12:15]
	s_barrier
	s_add_u32 s16, s16, 0x80080
	s_addc_u32 s17, s17, 0
	s_add_i32 s18, s18, s27
	v_lshl_add_u64 v[128:129], s[16:17], 0, v[206:207]
	s_mov_b32 m0, s18
	s_nop 0
	global_load_lds_dwordx4 v[128:129], off
	v_lshl_add_u64 v[128:129], s[16:17], 0, v[210:211]
	s_add_i32 m0, s18, 0x2000
	s_nop 0
	global_load_lds_dwordx4 v[128:129], off
	s_waitcnt vmcnt(6)
	s_barrier
	v_mfma_f32_16x16x32_bf16 v[48:51], v[176:179], v[144:147], v[48:51]
	v_mfma_f32_16x16x32_bf16 v[40:43], v[184:187], v[144:147], v[40:43]
	v_mfma_f32_16x16x32_bf16 v[32:35], v[176:179], v[152:155], v[32:35]
	v_mfma_f32_16x16x32_bf16 v[24:27], v[184:187], v[152:155], v[24:27]
	v_mfma_f32_16x16x32_bf16 v[16:19], v[176:179], v[160:163], v[16:19]
	v_mfma_f32_16x16x32_bf16 v[8:11], v[184:187], v[160:163], v[8:11]
	v_mfma_f32_16x16x32_bf16 v[4:7], v[176:179], v[168:171], v[4:7]
	v_mfma_f32_16x16x32_bf16 v[0:3], v[184:187], v[168:171], v[0:3]
	v_mfma_f32_16x16x32_bf16 v[48:51], v[180:183], v[148:151], v[48:51]
	v_mfma_f32_16x16x32_bf16 v[40:43], v[188:191], v[148:151], v[40:43]
	v_mfma_f32_16x16x32_bf16 v[32:35], v[180:183], v[156:159], v[32:35]
	v_mfma_f32_16x16x32_bf16 v[24:27], v[188:191], v[156:159], v[24:27]
	v_mfma_f32_16x16x32_bf16 v[16:19], v[180:183], v[164:167], v[16:19]
	v_mfma_f32_16x16x32_bf16 v[8:11], v[188:191], v[164:167], v[8:11]
	v_mfma_f32_16x16x32_bf16 v[4:7], v[180:183], v[172:175], v[4:7]
	v_mfma_f32_16x16x32_bf16 v[0:3], v[188:191], v[172:175], v[0:3]
	s_add_i32 s40, s40, 2
	s_add_u32 s14, s14, 0x100
	s_addc_u32 s15, s15, 0
	s_add_u32 s38, s38, 0x100
	s_addc_u32 s39, s39, 0
	s_cmp_gt_u32 s40, 29
	s_barrier
	s_cbranch_scc0 .LBB0_200
	v_lshl_add_u32 v228, s4, 8, v237
	v_or_b32_e32 v226, 16, v228
	s_mov_b64 s[4:5], -1
	s_cmp_lt_i32 s36, 16
	v_ashrrev_i32_e32 v229, 31, v228
	v_lshlrev_b32_e32 v192, 1, v212
	v_ashrrev_i32_e32 v227, 31, v226
	v_or_b32_e32 v224, 32, v228
	v_or_b32_e32 v222, 48, v228
	s_cbranch_scc0 .LBB0_203
	s_and_b32 s7, s36, 7
	s_cmp_gt_i32 s36, 7
	s_cselect_b64 vcc, -1, 0
	s_and_b64 s[4:5], vcc, exec
	s_mov_b32 s4, 0x15000000
	s_cselect_b32 s4, s4, 0xd000000
	s_add_u32 s4, s50, s4
	s_addc_u32 s5, s51, 0
	s_lshl_b32 s9, s7, 9
	s_add_u32 s4, s4, s9
	v_cvt_f32_ubyte0_e32 v128, s7
	s_addc_u32 s5, s5, 0
	v_sub_f32_e32 v128, 0xc0a00000, v128
	s_mov_b32 s7, 0xc2fc0000
	v_lshl_add_u64 v[230:231], s[4:5], 0, v[192:193]
	v_cmp_gt_f32_e64 s[4:5], s7, v128
	v_ashrrev_i32_e32 v225, 31, v224
	s_nop 0
	v_cndmask_b32_e64 v129, 0, v234, s[4:5]
	v_add_f32_e32 v128, v128, v129
	v_exp_f32_e32 v128, v128
	s_and_b64 s[4:5], s[4:5], exec
	s_cselect_b32 s4, 0xffffffc0, 0
	v_mov_b32_e32 v129, v193
	v_ldexp_f32 v128, v128, s4
	v_sub_f32_e32 v128, 1.0, v128
	v_log_f32_e32 v241, v128
	v_lshlrev_b32_e32 v128, 9, v228
	v_and_b32_e32 v128, 0x1f9e00, v128
	v_lshl_add_u64 v[130:131], v[214:215], 0, v[128:129]
	v_lshl_add_u64 v[132:133], v[216:217], 0, v[128:129]
	global_load_dwordx4 v[180:183], v[130:131], off offset:16
	global_load_dwordx4 v[188:191], v[130:131], off
	global_load_dwordx4 v[176:179], v[132:133], off offset:16
	global_load_dwordx4 v[184:187], v[132:133], off
	v_or_b32_e32 v130, 0x2000, v128
	v_mov_b32_e32 v131, v193
	v_lshl_add_u64 v[132:133], v[214:215], 0, v[130:131]
	v_lshl_add_u64 v[130:131], v[216:217], 0, v[130:131]
	global_load_dwordx4 v[164:167], v[132:133], off offset:16
	global_load_dwordx4 v[172:175], v[132:133], off
	global_load_dwordx4 v[160:163], v[130:131], off offset:16
	global_load_dwordx4 v[168:171], v[130:131], off
	v_mul_f32_e64 v196, v241, -v239
	v_cmp_gt_f32_e64 s[4:5], s7, v196
	v_or_b32_e32 v130, 0x4000, v128
	v_mov_b32_e32 v131, v193
	v_cndmask_b32_e64 v196, 0, v234, s[4:5]
	v_fma_f32 v196, v241, -v239, v196
	v_exp_f32_e32 v196, v196
	v_cndmask_b32_e64 v197, 0, v235, s[4:5]
	v_lshl_add_u64 v[132:133], v[214:215], 0, v[130:131]
	v_lshl_add_u64 v[130:131], v[216:217], 0, v[130:131]
	v_ldexp_f32 v196, v196, v197
	v_mul_f32_e32 v196, 0x3d800000, v196
	v_cndmask_b32_e32 v242, 1.0, v196, vcc
	v_mov_b32_e32 v196, v124
	v_mov_b32_e32 v197, v112
	global_load_dwordx4 v[148:151], v[132:133], off offset:16
	global_load_dwordx4 v[156:159], v[132:133], off
	global_load_dwordx4 v[144:147], v[130:131], off offset:16
	global_load_dwordx4 v[152:155], v[130:131], off
	v_or_b32_e32 v128, 0x6000, v128
	v_lshl_add_u64 v[130:131], v[214:215], 0, v[128:129]
	v_lshl_add_u64 v[136:137], v[216:217], 0, v[128:129]
	global_load_dwordx4 v[132:135], v[130:131], off offset:16
	global_load_dwordx4 v[140:143], v[130:131], off
	s_nop 0
	global_load_dwordx4 v[128:131], v[136:137], off offset:16
	s_nop 0
	global_load_dwordx4 v[136:139], v[136:137], off
	s_movk_i32 s4, 0x5f
	s_waitcnt vmcnt(0)
	v_mov_b32_e32 v198, v188
	v_mov_b32_e32 v199, v184
	v_pk_mul_f32 v[196:197], v[196:197], v[198:199]
	s_nop 0
	v_sub_f32_e32 v184, v196, v197
	v_mov_b32_e32 v196, v112
	v_mov_b32_e32 v197, v124
	v_pk_mul_f32 v[196:197], v[196:197], v[198:199]
	v_mul_f32_e32 v223, v242, v184
	v_add_f32_e32 v184, v196, v197
	v_mul_f32_e32 v198, v242, v184
	v_mov_b32_e32 v196, v125
	v_mov_b32_e32 v197, v113
	v_mov_b32_e32 v184, v189
	v_pk_mul_f32 v[188:189], v[196:197], v[184:185]
	s_nop 0
	v_sub_f32_e32 v188, v188, v189
	v_mul_f32_e32 v196, v242, v188
	v_mov_b32_e32 v188, v113
	v_mov_b32_e32 v189, v125
	v_pk_mul_f32 v[184:185], v[188:189], v[184:185]
	v_mov_b32_e32 v188, v190
	v_add_f32_e32 v184, v184, v185
	v_mul_f32_e32 v197, v242, v184
	v_mov_b32_e32 v184, v126
	v_mov_b32_e32 v185, v114
	v_mov_b32_e32 v189, v186
	v_pk_mul_f32 v[184:185], v[184:185], v[188:189]
	v_mov_b32_e32 v186, v191
	v_sub_f32_e32 v184, v184, v185
	v_mul_f32_e32 v190, v242, v184
	v_mov_b32_e32 v184, v114
	v_mov_b32_e32 v185, v126
	v_pk_mul_f32 v[184:185], v[184:185], v[188:189]
	s_nop 0
	v_add_f32_e32 v184, v184, v185
	v_mul_f32_e32 v188, v242, v184
	v_mov_b32_e32 v184, v127
	v_mov_b32_e32 v185, v115
	v_pk_mul_f32 v[184:185], v[184:185], v[186:187]
	s_nop 0
	v_sub_f32_e32 v184, v184, v185
	v_mul_f32_e32 v189, v242, v184
	v_mov_b32_e32 v184, v115
	v_mov_b32_e32 v185, v127
	v_pk_mul_f32 v[184:185], v[184:185], v[186:187]
	v_mov_b32_e32 v186, v180
	v_add_f32_e32 v184, v184, v185
	v_mul_f32_e32 v191, v242, v184
	v_mov_b32_e32 v184, v120
	v_mov_b32_e32 v185, v104
	v_mov_b32_e32 v187, v176
	v_pk_mul_f32 v[184:185], v[184:185], v[186:187]
	s_nop 0
	v_sub_f32_e32 v176, v184, v185
	v_mov_b32_e32 v184, v104
	v_mov_b32_e32 v185, v120
	v_pk_mul_f32 v[184:185], v[184:185], v[186:187]
	v_mul_f32_e32 v199, v242, v176
	v_add_f32_e32 v176, v184, v185
	v_mul_f32_e32 v186, v242, v176
	v_mov_b32_e32 v184, v121
	v_mov_b32_e32 v185, v105
	v_mov_b32_e32 v176, v181
	v_pk_mul_f32 v[180:181], v[184:185], v[176:177]
	s_nop 0
	v_sub_f32_e32 v180, v180, v181
	v_mul_f32_e32 v184, v242, v180
	v_mov_b32_e32 v180, v105
	v_mov_b32_e32 v181, v121
	v_pk_mul_f32 v[176:177], v[180:181], v[176:177]
	v_mov_b32_e32 v180, v182
	v_add_f32_e32 v176, v176, v177
	v_mul_f32_e32 v185, v242, v176
	v_mov_b32_e32 v176, v122
	v_mov_b32_e32 v177, v106
	v_mov_b32_e32 v181, v178
	v_pk_mul_f32 v[176:177], v[176:177], v[180:181]
	v_mov_b32_e32 v178, v183
	v_sub_f32_e32 v176, v176, v177
	v_mul_f32_e32 v182, v242, v176
	v_mov_b32_e32 v176, v106
	v_mov_b32_e32 v177, v122
	v_pk_mul_f32 v[176:177], v[176:177], v[180:181]
	s_nop 0
	v_add_f32_e32 v176, v176, v177
	v_mul_f32_e32 v187, v242, v176
	v_mov_b32_e32 v176, v123
	v_mov_b32_e32 v177, v107
	v_pk_mul_f32 v[176:177], v[176:177], v[178:179]
	s_nop 0
	v_sub_f32_e32 v176, v176, v177
	v_mul_f32_e32 v181, v242, v176
	v_mov_b32_e32 v176, v107
	v_mov_b32_e32 v177, v123
	v_pk_mul_f32 v[176:177], v[176:177], v[178:179]
	v_cvt_pk_bf16_f32 v178, v223, v196
	v_cvt_pk_bf16_f32 v179, v190, v189
	v_cvt_pk_bf16_f32 v180, v199, v184
	v_cvt_pk_bf16_f32 v181, v182, v181
	v_cvt_pk_bf16_f32 v182, v198, v197
	s_nop 0
	v_add_f32_e32 v176, v176, v177
	v_mul_f32_e32 v176, v242, v176
	v_cvt_pk_bf16_f32 v183, v188, v191
	v_cvt_pk_bf16_f32 v184, v186, v185
	v_cvt_pk_bf16_f32 v185, v187, v176
	v_lshlrev_b64 v[176:177], 12, v[228:229]
	v_lshl_add_u64 v[176:177], v[230:231], 0, v[176:177]
	global_store_dwordx4 v[176:177], v[178:181], off
	global_store_dwordx4 v[176:177], v[182:185], off offset:256
	v_ashrrev_i32_e32 v223, 31, v222
	v_bitop3_b32 v178, v228, s4, 16 bitop3:0xc8
	v_add_u32_e32 v178, 1, v178
	v_cvt_f32_ubyte0_e32 v178, v178
	v_mul_f32_e64 v179, v241, -v178
	v_cmp_gt_f32_e64 s[4:5], s7, v179
	v_mov_b32_e32 v181, v168
	v_mov_b32_e32 v190, v60
	v_cndmask_b32_e64 v180, 0, v234, s[4:5]
	v_fma_f32 v178, v241, -v178, v180
	v_exp_f32_e32 v178, v178
	v_cndmask_b32_e64 v179, 0, v235, s[4:5]
	v_mov_b32_e32 v180, v172
	s_movk_i32 s4, 0x6f
	v_ldexp_f32 v178, v178, v179
	v_mul_f32_e32 v178, 0x3d800000, v178
	v_cndmask_b32_e32 v182, 1.0, v178, vcc
	v_mov_b32_e32 v178, v116
	v_mov_b32_e32 v179, v96
	v_pk_mul_f32 v[178:179], v[178:179], v[180:181]
	v_mov_b32_e32 v191, v48
	v_sub_f32_e32 v168, v178, v179
	v_mov_b32_e32 v178, v96
	v_mov_b32_e32 v179, v116
	v_pk_mul_f32 v[178:179], v[178:179], v[180:181]
	v_mul_f32_e32 v183, v182, v168
	v_add_f32_e32 v168, v178, v179
	v_mul_f32_e32 v180, v182, v168
	v_mov_b32_e32 v178, v117
	v_mov_b32_e32 v179, v97
	v_mov_b32_e32 v168, v173
	v_pk_mul_f32 v[172:173], v[178:179], v[168:169]
	s_nop 0
	v_sub_f32_e32 v172, v172, v173
	v_mul_f32_e32 v178, v182, v172
	v_mov_b32_e32 v172, v97
	v_mov_b32_e32 v173, v117
	v_pk_mul_f32 v[168:169], v[172:173], v[168:169]
	v_mov_b32_e32 v172, v174
	v_add_f32_e32 v168, v168, v169
	v_mul_f32_e32 v179, v182, v168
	v_mov_b32_e32 v168, v118
	v_mov_b32_e32 v169, v98
	v_mov_b32_e32 v173, v170
	v_pk_mul_f32 v[168:169], v[168:169], v[172:173]
	v_mov_b32_e32 v170, v175
	v_sub_f32_e32 v168, v168, v169
	v_mul_f32_e32 v174, v182, v168
	v_mov_b32_e32 v168, v98
	v_mov_b32_e32 v169, v118
	v_pk_mul_f32 v[168:169], v[168:169], v[172:173]
	s_nop 0
	v_add_f32_e32 v168, v168, v169
	v_mul_f32_e32 v172, v182, v168
	v_mov_b32_e32 v168, v119
	v_mov_b32_e32 v169, v99
	v_pk_mul_f32 v[168:169], v[168:169], v[170:171]
	s_nop 0
	v_sub_f32_e32 v168, v168, v169
	v_mul_f32_e32 v173, v182, v168
	v_mov_b32_e32 v168, v99
	v_mov_b32_e32 v169, v119
	v_pk_mul_f32 v[168:169], v[168:169], v[170:171]
	v_mov_b32_e32 v170, v164
	v_add_f32_e32 v168, v168, v169
	v_mul_f32_e32 v175, v182, v168
	v_mov_b32_e32 v168, v108
	v_mov_b32_e32 v169, v88
	v_mov_b32_e32 v171, v160
	v_pk_mul_f32 v[168:169], v[168:169], v[170:171]
	s_nop 0
	v_sub_f32_e32 v160, v168, v169
	v_mov_b32_e32 v168, v88
	v_mov_b32_e32 v169, v108
	v_pk_mul_f32 v[168:169], v[168:169], v[170:171]
	v_mul_f32_e32 v181, v182, v160
	v_add_f32_e32 v160, v168, v169
	v_mul_f32_e32 v170, v182, v160
	v_mov_b32_e32 v168, v109
	v_mov_b32_e32 v169, v89
	v_mov_b32_e32 v160, v165
	v_pk_mul_f32 v[164:165], v[168:169], v[160:161]
	s_nop 0
	v_sub_f32_e32 v164, v164, v165
	v_mul_f32_e32 v168, v182, v164
	v_mov_b32_e32 v164, v89
	v_mov_b32_e32 v165, v109
	v_pk_mul_f32 v[160:161], v[164:165], v[160:161]
	v_mov_b32_e32 v164, v166
	v_add_f32_e32 v160, v160, v161
	v_mul_f32_e32 v169, v182, v160
	v_mov_b32_e32 v160, v110
	v_mov_b32_e32 v161, v90
	v_mov_b32_e32 v165, v162
	v_pk_mul_f32 v[160:161], v[160:161], v[164:165]
	v_mov_b32_e32 v162, v167
	v_sub_f32_e32 v160, v160, v161
	v_mul_f32_e32 v166, v182, v160
	v_mov_b32_e32 v160, v90
	v_mov_b32_e32 v161, v110
	v_pk_mul_f32 v[160:161], v[160:161], v[164:165]
	s_nop 0
	v_add_f32_e32 v160, v160, v161
	v_mul_f32_e32 v171, v182, v160
	v_mov_b32_e32 v160, v111
	v_mov_b32_e32 v161, v91
	v_pk_mul_f32 v[160:161], v[160:161], v[162:163]
	s_nop 0
	v_sub_f32_e32 v160, v160, v161
	v_mul_f32_e32 v164, v182, v160
	v_mov_b32_e32 v160, v91
	v_mov_b32_e32 v161, v111
	v_pk_mul_f32 v[160:161], v[160:161], v[162:163]
	s_nop 0
	v_add_f32_e32 v160, v160, v161
	v_mul_f32_e32 v167, v182, v160
	v_cvt_pk_bf16_f32 v160, v183, v178
	v_cvt_pk_bf16_f32 v161, v174, v173
	v_cvt_pk_bf16_f32 v162, v181, v168
	v_cvt_pk_bf16_f32 v163, v166, v164
	v_cvt_pk_bf16_f32 v164, v180, v179
	v_cvt_pk_bf16_f32 v165, v172, v175
	v_cvt_pk_bf16_f32 v166, v170, v169
	v_lshlrev_b64 v[168:169], 12, v[226:227]
	v_lshl_add_u64 v[168:169], v[230:231], 0, v[168:169]
	v_cvt_pk_bf16_f32 v167, v171, v167
	global_store_dwordx4 v[168:169], v[160:163], off
	global_store_dwordx4 v[168:169], v[164:167], off offset:256
	s_nop 0
	v_bitop3_b32 v160, v228, s4, 32 bitop3:0xc8
	v_add_u32_e32 v160, 1, v160
	v_cvt_f32_ubyte0_e32 v160, v160
	v_mul_f32_e64 v161, v241, -v160
	v_cmp_gt_f32_e64 s[4:5], s7, v161
	v_mov_b32_e32 v163, v152
	s_nop 0
	v_cndmask_b32_e64 v162, 0, v234, s[4:5]
	v_fma_f32 v160, v241, -v160, v162
	v_exp_f32_e32 v160, v160
	v_cndmask_b32_e64 v161, 0, v235, s[4:5]
	v_mov_b32_e32 v162, v156
	s_movk_i32 s4, 0x7f
	v_ldexp_f32 v160, v160, v161
	v_mul_f32_e32 v160, 0x3d800000, v160
	v_cndmask_b32_e32 v164, 1.0, v160, vcc
	v_mov_b32_e32 v160, v100
	v_mov_b32_e32 v161, v80
	v_pk_mul_f32 v[160:161], v[160:161], v[162:163]
	s_nop 0
	v_sub_f32_e32 v152, v160, v161
	v_mov_b32_e32 v160, v80
	v_mov_b32_e32 v161, v100
	v_pk_mul_f32 v[160:161], v[160:161], v[162:163]
	v_mul_f32_e32 v165, v164, v152
	v_add_f32_e32 v152, v160, v161
	v_mul_f32_e32 v162, v164, v152
	v_mov_b32_e32 v160, v101
	v_mov_b32_e32 v161, v81
	v_mov_b32_e32 v152, v157
	v_pk_mul_f32 v[156:157], v[160:161], v[152:153]
	s_nop 0
	v_sub_f32_e32 v156, v156, v157
	v_mul_f32_e32 v160, v164, v156
	v_mov_b32_e32 v156, v81
	v_mov_b32_e32 v157, v101
	v_pk_mul_f32 v[152:153], v[156:157], v[152:153]
	v_mov_b32_e32 v156, v158
	v_add_f32_e32 v152, v152, v153
	v_mul_f32_e32 v161, v164, v152
	v_mov_b32_e32 v152, v102
	v_mov_b32_e32 v153, v82
	v_mov_b32_e32 v157, v154
	v_pk_mul_f32 v[152:153], v[152:153], v[156:157]
	v_mov_b32_e32 v154, v159
	v_sub_f32_e32 v152, v152, v153
	v_mul_f32_e32 v158, v164, v152
	v_mov_b32_e32 v152, v82
	v_mov_b32_e32 v153, v102
	v_pk_mul_f32 v[152:153], v[152:153], v[156:157]
	s_nop 0
	v_add_f32_e32 v152, v152, v153
	v_mul_f32_e32 v156, v164, v152
	v_mov_b32_e32 v152, v103
	v_mov_b32_e32 v153, v83
	v_pk_mul_f32 v[152:153], v[152:153], v[154:155]
	s_nop 0
	v_sub_f32_e32 v152, v152, v153
	v_mul_f32_e32 v157, v164, v152
	v_mov_b32_e32 v152, v83
	v_mov_b32_e32 v153, v103
	v_pk_mul_f32 v[152:153], v[152:153], v[154:155]
	v_mov_b32_e32 v154, v148
	v_add_f32_e32 v152, v152, v153
	v_mul_f32_e32 v159, v164, v152
	v_mov_b32_e32 v152, v92
	v_mov_b32_e32 v153, v72
	v_mov_b32_e32 v155, v144
	v_pk_mul_f32 v[152:153], v[152:153], v[154:155]
	s_nop 0
	v_sub_f32_e32 v144, v152, v153
	v_mov_b32_e32 v152, v72
	v_mov_b32_e32 v153, v92
	v_pk_mul_f32 v[152:153], v[152:153], v[154:155]
	v_mul_f32_e32 v163, v164, v144
	v_add_f32_e32 v144, v152, v153
	v_mul_f32_e32 v154, v164, v144
	v_mov_b32_e32 v152, v93
	v_mov_b32_e32 v153, v73
	v_mov_b32_e32 v144, v149
	v_pk_mul_f32 v[148:149], v[152:153], v[144:145]
	s_nop 0
	v_sub_f32_e32 v148, v148, v149
	v_mul_f32_e32 v152, v164, v148
	v_mov_b32_e32 v148, v73
	v_mov_b32_e32 v149, v93
	v_pk_mul_f32 v[144:145], v[148:149], v[144:145]
	v_mov_b32_e32 v148, v150
	v_add_f32_e32 v144, v144, v145
	v_mul_f32_e32 v153, v164, v144
	v_mov_b32_e32 v144, v94
	v_mov_b32_e32 v145, v74
	v_mov_b32_e32 v149, v146
	v_pk_mul_f32 v[144:145], v[144:145], v[148:149]
	v_mov_b32_e32 v146, v151
	v_sub_f32_e32 v144, v144, v145
	v_mul_f32_e32 v150, v164, v144
	v_mov_b32_e32 v144, v74
	v_mov_b32_e32 v145, v94
	v_pk_mul_f32 v[144:145], v[144:145], v[148:149]
	s_nop 0
	v_add_f32_e32 v144, v144, v145
	v_mul_f32_e32 v155, v164, v144
	v_mov_b32_e32 v144, v95
	v_mov_b32_e32 v145, v75
	v_pk_mul_f32 v[144:145], v[144:145], v[146:147]
	s_nop 0
	v_sub_f32_e32 v144, v144, v145
	v_mul_f32_e32 v148, v164, v144
	v_mov_b32_e32 v144, v75
	v_mov_b32_e32 v145, v95
	v_pk_mul_f32 v[144:145], v[144:145], v[146:147]
	s_nop 0
	v_add_f32_e32 v144, v144, v145
	v_mul_f32_e32 v151, v164, v144
	v_cvt_pk_bf16_f32 v144, v165, v160
	v_cvt_pk_bf16_f32 v145, v158, v157
	v_cvt_pk_bf16_f32 v146, v163, v152
	v_cvt_pk_bf16_f32 v147, v150, v148
	v_cvt_pk_bf16_f32 v148, v162, v161
	v_cvt_pk_bf16_f32 v149, v156, v159
	v_cvt_pk_bf16_f32 v150, v154, v153
	v_lshlrev_b64 v[152:153], 12, v[224:225]
	v_lshl_add_u64 v[152:153], v[230:231], 0, v[152:153]
	v_cvt_pk_bf16_f32 v151, v155, v151
	global_store_dwordx4 v[152:153], v[144:147], off
	global_store_dwordx4 v[152:153], v[148:151], off offset:256
	s_nop 0
	v_bitop3_b32 v144, v228, s4, 48 bitop3:0xc8
	v_add_u32_e32 v144, 1, v144
	v_cvt_f32_ubyte0_e32 v144, v144
	v_mul_f32_e64 v145, v241, -v144
	v_cmp_gt_f32_e64 s[4:5], s7, v145
	v_mov_b32_e32 v147, v136
	s_nop 0
	v_cndmask_b32_e64 v146, 0, v234, s[4:5]
	v_fma_f32 v144, v241, -v144, v146
	v_exp_f32_e32 v144, v144
	v_cndmask_b32_e64 v145, 0, v235, s[4:5]
	v_mov_b32_e32 v146, v140
	s_mov_b64 s[4:5], 0x80000
	v_ldexp_f32 v144, v144, v145
	v_mul_f32_e32 v144, 0x3d800000, v144
	v_cndmask_b32_e32 v148, 1.0, v144, vcc
	v_mov_b32_e32 v144, v84
	v_mov_b32_e32 v145, v68
	v_pk_mul_f32 v[144:145], v[144:145], v[146:147]
	s_nop 0
	v_sub_f32_e32 v136, v144, v145
	v_mov_b32_e32 v144, v68
	v_mov_b32_e32 v145, v84
	v_pk_mul_f32 v[144:145], v[144:145], v[146:147]
	v_mul_f32_e32 v149, v148, v136
	v_add_f32_e32 v136, v144, v145
	v_mul_f32_e32 v146, v148, v136
	v_mov_b32_e32 v144, v85
	v_mov_b32_e32 v145, v69
	v_mov_b32_e32 v136, v141
	v_pk_mul_f32 v[140:141], v[144:145], v[136:137]
	s_nop 0
	v_sub_f32_e32 v140, v140, v141
	v_mul_f32_e32 v144, v148, v140
	v_mov_b32_e32 v140, v69
	v_mov_b32_e32 v141, v85
	v_pk_mul_f32 v[136:137], v[140:141], v[136:137]
	v_mov_b32_e32 v140, v142
	v_add_f32_e32 v136, v136, v137
	v_mul_f32_e32 v145, v148, v136
	v_mov_b32_e32 v136, v86
	v_mov_b32_e32 v137, v70
	v_mov_b32_e32 v141, v138
	v_pk_mul_f32 v[136:137], v[136:137], v[140:141]
	v_mov_b32_e32 v138, v143
	v_sub_f32_e32 v136, v136, v137
	v_mul_f32_e32 v142, v148, v136
	v_mov_b32_e32 v136, v70
	v_mov_b32_e32 v137, v86
	v_pk_mul_f32 v[136:137], v[136:137], v[140:141]
	s_nop 0
	v_add_f32_e32 v136, v136, v137
	v_mul_f32_e32 v140, v148, v136
	v_mov_b32_e32 v136, v87
	v_mov_b32_e32 v137, v71
	v_pk_mul_f32 v[136:137], v[136:137], v[138:139]
	s_nop 0
	v_sub_f32_e32 v136, v136, v137
	v_mul_f32_e32 v141, v148, v136
	v_mov_b32_e32 v136, v71
	v_mov_b32_e32 v137, v87
	v_pk_mul_f32 v[136:137], v[136:137], v[138:139]
	v_mov_b32_e32 v138, v132
	v_add_f32_e32 v136, v136, v137
	v_mul_f32_e32 v143, v148, v136
	v_mov_b32_e32 v136, v76
	v_mov_b32_e32 v137, v64
	v_mov_b32_e32 v139, v128
	v_pk_mul_f32 v[136:137], v[136:137], v[138:139]
	s_nop 0
	v_sub_f32_e32 v128, v136, v137
	v_mov_b32_e32 v136, v64
	v_mov_b32_e32 v137, v76
	v_pk_mul_f32 v[136:137], v[136:137], v[138:139]
	v_mul_f32_e32 v147, v148, v128
	v_add_f32_e32 v128, v136, v137
	v_mul_f32_e32 v138, v148, v128
	v_mov_b32_e32 v136, v77
	v_mov_b32_e32 v137, v65
	v_mov_b32_e32 v128, v133
	v_pk_mul_f32 v[132:133], v[136:137], v[128:129]
	s_nop 0
	v_sub_f32_e32 v132, v132, v133
	v_mul_f32_e32 v136, v148, v132
	v_mov_b32_e32 v132, v65
	v_mov_b32_e32 v133, v77
	v_pk_mul_f32 v[128:129], v[132:133], v[128:129]
	v_mov_b32_e32 v132, v134
	v_add_f32_e32 v128, v128, v129
	v_mul_f32_e32 v137, v148, v128
	v_mov_b32_e32 v128, v78
	v_mov_b32_e32 v129, v66
	v_mov_b32_e32 v133, v130
	v_pk_mul_f32 v[128:129], v[128:129], v[132:133]
	v_mov_b32_e32 v130, v135
	v_sub_f32_e32 v128, v128, v129
	v_mul_f32_e32 v134, v148, v128
	v_mov_b32_e32 v128, v66
	v_mov_b32_e32 v129, v78
	v_pk_mul_f32 v[128:129], v[128:129], v[132:133]
	s_nop 0
	v_add_f32_e32 v128, v128, v129
	v_mul_f32_e32 v139, v148, v128
	v_mov_b32_e32 v128, v79
	v_mov_b32_e32 v129, v67
	v_pk_mul_f32 v[128:129], v[128:129], v[130:131]
	s_nop 0
	v_sub_f32_e32 v128, v128, v129
	v_mul_f32_e32 v132, v148, v128
	v_mov_b32_e32 v128, v67
	v_mov_b32_e32 v129, v79
	v_pk_mul_f32 v[128:129], v[128:129], v[130:131]
	s_nop 0
	v_add_f32_e32 v128, v128, v129
	v_mul_f32_e32 v135, v148, v128
	v_cvt_pk_bf16_f32 v128, v149, v144
	v_cvt_pk_bf16_f32 v129, v142, v141
	v_cvt_pk_bf16_f32 v130, v147, v136
	v_cvt_pk_bf16_f32 v131, v134, v132
	v_cvt_pk_bf16_f32 v132, v146, v145
	v_cvt_pk_bf16_f32 v133, v140, v143
	v_cvt_pk_bf16_f32 v134, v138, v137
	v_lshlrev_b64 v[136:137], 12, v[222:223]
	v_lshl_add_u64 v[136:137], v[230:231], 0, v[136:137]
	v_cvt_pk_bf16_f32 v135, v139, v135
	global_store_dwordx4 v[136:137], v[128:131], off
	global_store_dwordx4 v[136:137], v[132:135], off offset:256
	s_nop 0
	v_mov_b32_e32 v128, 0x4000
	v_lshl_add_u32 v128, v228, 7, v128
	v_and_b32_e32 v128, 0x7e780, v128
	v_lshlrev_b32_e32 v128, 2, v128
	v_mov_b32_e32 v129, v193
	v_lshl_add_u64 v[130:131], v[214:215], 0, v[128:129]
	v_lshl_add_u64 v[132:133], v[216:217], 0, v[128:129]
	global_load_dwordx4 v[168:171], v[130:131], off offset:16
	global_load_dwordx4 v[172:175], v[130:131], off
	global_load_dwordx4 v[178:181], v[132:133], off offset:16
	global_load_dwordx4 v[182:185], v[132:133], off
	v_or_b32_e32 v130, 0x2000, v128
	v_mov_b32_e32 v131, v193
	v_lshl_add_u64 v[132:133], v[214:215], 0, v[130:131]
	v_lshl_add_u64 v[130:131], v[216:217], 0, v[130:131]
	global_load_dwordx4 v[164:167], v[132:133], off offset:16
	global_load_dwordx4 v[186:189], v[132:133], off
	global_load_dwordx4 v[160:163], v[130:131], off offset:16
	global_load_dwordx4 v[196:199], v[130:131], off
	v_or_b32_e32 v130, 0x4000, v128
	v_mov_b32_e32 v131, v193
	v_lshl_add_u64 v[132:133], v[214:215], 0, v[130:131]
	v_lshl_add_u64 v[130:131], v[216:217], 0, v[130:131]
	global_load_dwordx4 v[148:151], v[132:133], off offset:16
	global_load_dwordx4 v[156:159], v[132:133], off
	global_load_dwordx4 v[144:147], v[130:131], off offset:16
	global_load_dwordx4 v[152:155], v[130:131], off
	v_or_b32_e32 v128, 0x6000, v128
	v_lshl_add_u64 v[130:131], v[214:215], 0, v[128:129]
	v_lshl_add_u64 v[136:137], v[216:217], 0, v[128:129]
	global_load_dwordx4 v[132:135], v[130:131], off offset:16
	global_load_dwordx4 v[140:143], v[130:131], off
	s_nop 0
	global_load_dwordx4 v[128:131], v[136:137], off offset:16
	s_nop 0
	global_load_dwordx4 v[136:139], v[136:137], off
	s_waitcnt vmcnt(0)
	v_mov_b32_e32 v244, v172
	v_mov_b32_e32 v245, v182
	v_pk_mul_f32 v[190:191], v[190:191], v[244:245]
	v_mov_b32_e32 v182, v173
	v_sub_f32_e32 v172, v190, v191
	v_mov_b32_e32 v190, v48
	v_mov_b32_e32 v191, v60
	v_pk_mul_f32 v[190:191], v[190:191], v[244:245]
	v_mul_f32_e32 v223, v242, v172
	v_add_f32_e32 v172, v190, v191
	v_mov_b32_e32 v190, v61
	v_mov_b32_e32 v191, v49
	v_mul_f32_e32 v225, v242, v172
	v_pk_mul_f32 v[172:173], v[190:191], v[182:183]
	s_nop 0
	v_sub_f32_e32 v172, v172, v173
	v_mul_f32_e32 v190, v242, v172
	v_mov_b32_e32 v172, v49
	v_mov_b32_e32 v173, v61
	v_pk_mul_f32 v[172:173], v[172:173], v[182:183]
	v_mov_b32_e32 v182, v174
	v_add_f32_e32 v172, v172, v173
	v_mul_f32_e32 v191, v242, v172
	v_mov_b32_e32 v172, v62
	v_mov_b32_e32 v173, v50
	v_mov_b32_e32 v183, v184
	v_pk_mul_f32 v[172:173], v[172:173], v[182:183]
	v_mov_b32_e32 v184, v175
	v_sub_f32_e32 v172, v172, v173
	v_mul_f32_e32 v243, v242, v172
	v_mov_b32_e32 v172, v50
	v_mov_b32_e32 v173, v62
	v_pk_mul_f32 v[172:173], v[172:173], v[182:183]
	v_mov_b32_e32 v174, v168
	v_add_f32_e32 v172, v172, v173
	v_mul_f32_e32 v182, v242, v172
	v_mov_b32_e32 v172, v63
	v_mov_b32_e32 v173, v51
	v_pk_mul_f32 v[172:173], v[172:173], v[184:185]
	v_mov_b32_e32 v175, v178
	v_sub_f32_e32 v172, v172, v173
	v_mul_f32_e32 v183, v242, v172
	v_mov_b32_e32 v172, v51
	v_mov_b32_e32 v173, v63
	v_pk_mul_f32 v[172:173], v[172:173], v[184:185]
	v_mov_b32_e32 v178, v169
	v_add_f32_e32 v172, v172, v173
	v_mul_f32_e32 v184, v242, v172
	v_mov_b32_e32 v172, v56
	v_mov_b32_e32 v173, v40
	v_pk_mul_f32 v[172:173], v[172:173], v[174:175]
	s_nop 0
	v_sub_f32_e32 v168, v172, v173
	v_mov_b32_e32 v172, v40
	v_mov_b32_e32 v173, v56
	v_pk_mul_f32 v[172:173], v[172:173], v[174:175]
	v_mul_f32_e32 v185, v242, v168
	v_add_f32_e32 v168, v172, v173
	v_mov_b32_e32 v172, v57
	v_mov_b32_e32 v173, v41
	v_mul_f32_e32 v174, v242, v168
	v_pk_mul_f32 v[168:169], v[172:173], v[178:179]
	v_mov_b32_e32 v172, v170
	v_sub_f32_e32 v168, v168, v169
	v_mul_f32_e32 v175, v242, v168
	v_mov_b32_e32 v168, v41
	v_mov_b32_e32 v169, v57
	v_pk_mul_f32 v[168:169], v[168:169], v[178:179]
	v_mov_b32_e32 v173, v180
	v_add_f32_e32 v168, v168, v169
	v_mul_f32_e32 v178, v242, v168
	v_mov_b32_e32 v168, v58
	v_mov_b32_e32 v169, v42
	v_pk_mul_f32 v[168:169], v[168:169], v[172:173]
	v_mov_b32_e32 v180, v171
	v_sub_f32_e32 v168, v168, v169
	v_mul_f32_e32 v179, v242, v168
	v_mov_b32_e32 v168, v42
	v_mov_b32_e32 v169, v58
	v_pk_mul_f32 v[168:169], v[168:169], v[172:173]
	s_nop 0
	v_add_f32_e32 v168, v168, v169
	v_mul_f32_e32 v244, v242, v168
	v_mov_b32_e32 v168, v59
	v_mov_b32_e32 v169, v43
	v_pk_mul_f32 v[168:169], v[168:169], v[180:181]
	s_nop 0
	v_sub_f32_e32 v168, v168, v169
	v_mul_f32_e32 v171, v242, v168
	v_mov_b32_e32 v168, v43
	v_mov_b32_e32 v169, v59
	v_pk_mul_f32 v[168:169], v[168:169], v[180:181]
	s_nop 0
	v_add_f32_e32 v168, v168, v169
	v_mul_f32_e32 v180, v242, v168
	v_cvt_pk_bf16_f32 v168, v223, v190
	v_cvt_pk_bf16_f32 v169, v243, v183
	v_cvt_pk_bf16_f32 v170, v185, v175
	v_cvt_pk_bf16_f32 v171, v179, v171
	v_cvt_pk_bf16_f32 v172, v225, v191
	v_cvt_pk_bf16_f32 v173, v182, v184
	v_cvt_pk_bf16_f32 v174, v174, v178
	v_lshl_add_u64 v[178:179], v[176:177], 0, s[4:5]
	s_mov_b32 s4, 0x80000
	v_add_co_u32_e64 v176, s[4:5], s4, v176
	v_cvt_pk_bf16_f32 v175, v244, v180
	s_nop 1
	v_addc_co_u32_e64 v177, s[4:5], 0, v177, s[4:5]
	global_store_dwordx4 v[176:177], v[168:171], off
	global_store_dwordx4 v[178:179], v[172:175], off offset:256
	s_nop 0
	v_add_u32_e32 v168, 0x90, v228
	v_and_b32_e32 v169, 0x5f, v168
	v_add_u32_e32 v169, 1, v169
	v_cvt_f32_ubyte0_e32 v169, v169
	v_mul_f32_e64 v170, v241, -v169
	v_cmp_gt_f32_e64 s[4:5], s7, v170
	v_mov_b32_e32 v171, v32
	v_mov_b32_e32 v172, v186
	v_cndmask_b32_e64 v170, 0, v234, s[4:5]
	v_fma_f32 v169, v241, -v169, v170
	v_exp_f32_e32 v169, v169
	v_cndmask_b32_e64 v170, 0, v235, s[4:5]
	v_mov_b32_e32 v173, v196
	v_mov_b32_e32 v196, v187
	v_ldexp_f32 v169, v169, v170
	v_mov_b32_e32 v170, v52
	v_mul_f32_e32 v169, 0x3d800000, v169
	v_pk_mul_f32 v[170:171], v[170:171], v[172:173]
	v_cndmask_b32_e32 v169, 1.0, v169, vcc
	v_sub_f32_e32 v170, v170, v171
	v_mul_f32_e32 v174, v169, v170
	v_mov_b32_e32 v170, v32
	v_mov_b32_e32 v171, v52
	v_pk_mul_f32 v[170:171], v[170:171], v[172:173]
	v_mov_b32_e32 v172, v188
	v_add_f32_e32 v170, v170, v171
	v_mul_f32_e32 v175, v169, v170
	v_mov_b32_e32 v170, v53
	v_mov_b32_e32 v171, v33
	v_pk_mul_f32 v[170:171], v[170:171], v[196:197]
	v_mov_b32_e32 v173, v198
	v_sub_f32_e32 v170, v170, v171
	v_mul_f32_e32 v176, v169, v170
	v_mov_b32_e32 v170, v33
	v_mov_b32_e32 v171, v53
	v_pk_mul_f32 v[170:171], v[170:171], v[196:197]
	v_mov_b32_e32 v198, v189
	v_add_f32_e32 v170, v170, v171
	v_mul_f32_e32 v177, v169, v170
	v_mov_b32_e32 v170, v54
	v_mov_b32_e32 v171, v34
	v_pk_mul_f32 v[170:171], v[170:171], v[172:173]
	s_nop 0
	v_sub_f32_e32 v170, v170, v171
	v_mul_f32_e32 v178, v169, v170
	v_mov_b32_e32 v170, v34
	v_mov_b32_e32 v171, v54
	v_pk_mul_f32 v[170:171], v[170:171], v[172:173]
	v_mov_b32_e32 v172, v164
	v_add_f32_e32 v170, v170, v171
	v_mul_f32_e32 v179, v169, v170
	v_mov_b32_e32 v170, v55
	v_mov_b32_e32 v171, v35
	v_pk_mul_f32 v[170:171], v[170:171], v[198:199]
	v_mov_b32_e32 v173, v160
	v_sub_f32_e32 v170, v170, v171
	v_mul_f32_e32 v180, v169, v170
	v_mov_b32_e32 v170, v35
	v_mov_b32_e32 v171, v55
	v_pk_mul_f32 v[170:171], v[170:171], v[198:199]
	s_nop 0
	v_add_f32_e32 v170, v170, v171
	v_mul_f32_e32 v181, v169, v170
	v_mov_b32_e32 v170, v44
	v_mov_b32_e32 v171, v24
	v_pk_mul_f32 v[170:171], v[170:171], v[172:173]
	s_nop 0
	v_sub_f32_e32 v160, v170, v171
	v_mov_b32_e32 v170, v24
	v_mov_b32_e32 v171, v44
	v_pk_mul_f32 v[170:171], v[170:171], v[172:173]
	v_mul_f32_e32 v182, v169, v160
	v_add_f32_e32 v160, v170, v171
	v_mul_f32_e32 v172, v169, v160
	v_mov_b32_e32 v170, v45
	v_mov_b32_e32 v171, v25
	v_mov_b32_e32 v160, v165
	v_pk_mul_f32 v[164:165], v[170:171], v[160:161]
	s_nop 0
	v_sub_f32_e32 v164, v164, v165
	v_mul_f32_e32 v170, v169, v164
	v_mov_b32_e32 v164, v25
	v_mov_b32_e32 v165, v45
	v_pk_mul_f32 v[160:161], v[164:165], v[160:161]
	v_mov_b32_e32 v164, v166
	v_add_f32_e32 v160, v160, v161
	v_mul_f32_e32 v171, v169, v160
	v_mov_b32_e32 v160, v46
	v_mov_b32_e32 v161, v26
	v_mov_b32_e32 v165, v162
	v_pk_mul_f32 v[160:161], v[160:161], v[164:165]
	v_mov_b32_e32 v162, v167
	v_sub_f32_e32 v160, v160, v161
	v_mul_f32_e32 v166, v169, v160
	v_mov_b32_e32 v160, v26
	v_mov_b32_e32 v161, v46
	v_pk_mul_f32 v[160:161], v[160:161], v[164:165]
	s_nop 0
	v_add_f32_e32 v160, v160, v161
	v_mul_f32_e32 v173, v169, v160
	v_mov_b32_e32 v160, v47
	v_mov_b32_e32 v161, v27
	v_pk_mul_f32 v[160:161], v[160:161], v[162:163]
	s_nop 0
	v_sub_f32_e32 v160, v160, v161
	v_mul_f32_e32 v164, v169, v160
	v_mov_b32_e32 v160, v27
	v_mov_b32_e32 v161, v47
	v_pk_mul_f32 v[160:161], v[160:161], v[162:163]
	s_nop 0
	v_add_f32_e32 v160, v160, v161
	v_mul_f32_e32 v167, v169, v160
	v_ashrrev_i32_e32 v169, 31, v168
	v_lshlrev_b64 v[168:169], 12, v[168:169]
	v_cvt_pk_bf16_f32 v160, v174, v176
	v_cvt_pk_bf16_f32 v161, v178, v180
	v_cvt_pk_bf16_f32 v162, v182, v170
	v_cvt_pk_bf16_f32 v163, v166, v164
	v_lshl_add_u64 v[168:169], v[230:231], 0, v[168:169]
	v_cvt_pk_bf16_f32 v164, v175, v177
	v_cvt_pk_bf16_f32 v165, v179, v181
	v_cvt_pk_bf16_f32 v166, v172, v171
	v_cvt_pk_bf16_f32 v167, v173, v167
	global_store_dwordx4 v[168:169], v[160:163], off
	global_store_dwordx4 v[168:169], v[164:167], off offset:256
	s_nop 0
	v_add_u32_e32 v160, 0xa0, v228
	v_and_b32_e32 v161, 0x6f, v160
	v_add_u32_e32 v161, 1, v161
	v_cvt_f32_ubyte0_e32 v161, v161
	v_mul_f32_e64 v162, v241, -v161
	v_cmp_gt_f32_e64 s[4:5], s7, v162
	v_mov_b32_e32 v163, v16
	v_mov_b32_e32 v164, v156
	v_cndmask_b32_e64 v162, 0, v234, s[4:5]
	v_fma_f32 v161, v241, -v161, v162
	v_exp_f32_e32 v161, v161
	v_cndmask_b32_e64 v162, 0, v235, s[4:5]
	v_mov_b32_e32 v165, v152
	v_ldexp_f32 v161, v161, v162
	v_mov_b32_e32 v162, v36
	v_pk_mul_f32 v[162:163], v[162:163], v[164:165]
	v_mul_f32_e32 v161, 0x3d800000, v161
	v_sub_f32_e32 v152, v162, v163
	v_mov_b32_e32 v162, v16
	v_mov_b32_e32 v163, v36
	v_cndmask_b32_e32 v161, 1.0, v161, vcc
	v_pk_mul_f32 v[162:163], v[162:163], v[164:165]
	v_mul_f32_e32 v166, v161, v152
	v_add_f32_e32 v152, v162, v163
	v_mul_f32_e32 v164, v161, v152
	v_mov_b32_e32 v162, v37
	v_mov_b32_e32 v163, v17
	v_mov_b32_e32 v152, v157
	v_pk_mul_f32 v[156:157], v[162:163], v[152:153]
	s_nop 0
	v_sub_f32_e32 v156, v156, v157
	v_mul_f32_e32 v162, v161, v156
	v_mov_b32_e32 v156, v17
	v_mov_b32_e32 v157, v37
	v_pk_mul_f32 v[152:153], v[156:157], v[152:153]
	v_mov_b32_e32 v156, v158
	v_add_f32_e32 v152, v152, v153
	v_mul_f32_e32 v163, v161, v152
	v_mov_b32_e32 v152, v38
	v_mov_b32_e32 v153, v18
	v_mov_b32_e32 v157, v154
	v_pk_mul_f32 v[152:153], v[152:153], v[156:157]
	v_mov_b32_e32 v154, v159
	v_sub_f32_e32 v152, v152, v153
	v_mul_f32_e32 v158, v161, v152
	v_mov_b32_e32 v152, v18
	v_mov_b32_e32 v153, v38
	v_pk_mul_f32 v[152:153], v[152:153], v[156:157]
	s_nop 0
	v_add_f32_e32 v152, v152, v153
	v_mul_f32_e32 v156, v161, v152
	v_mov_b32_e32 v152, v39
	v_mov_b32_e32 v153, v19
	v_pk_mul_f32 v[152:153], v[152:153], v[154:155]
	s_nop 0
	v_sub_f32_e32 v152, v152, v153
	v_mul_f32_e32 v157, v161, v152
	v_mov_b32_e32 v152, v19
	v_mov_b32_e32 v153, v39
	v_pk_mul_f32 v[152:153], v[152:153], v[154:155]
	v_mov_b32_e32 v154, v148
	v_add_f32_e32 v152, v152, v153
	v_mul_f32_e32 v159, v161, v152
	v_mov_b32_e32 v152, v28
	v_mov_b32_e32 v153, v8
	v_mov_b32_e32 v155, v144
	v_pk_mul_f32 v[152:153], v[152:153], v[154:155]
	s_nop 0
	v_sub_f32_e32 v144, v152, v153
	v_mov_b32_e32 v152, v8
	v_mov_b32_e32 v153, v28
	v_pk_mul_f32 v[152:153], v[152:153], v[154:155]
	v_mul_f32_e32 v165, v161, v144
	v_add_f32_e32 v144, v152, v153
	v_mul_f32_e32 v154, v161, v144
	v_mov_b32_e32 v152, v29
	v_mov_b32_e32 v153, v9
	v_mov_b32_e32 v144, v149
	v_pk_mul_f32 v[148:149], v[152:153], v[144:145]
	s_nop 0
	v_sub_f32_e32 v148, v148, v149
	v_mul_f32_e32 v152, v161, v148
	v_mov_b32_e32 v148, v9
	v_mov_b32_e32 v149, v29
	v_pk_mul_f32 v[144:145], v[148:149], v[144:145]
	v_mov_b32_e32 v148, v150
	v_add_f32_e32 v144, v144, v145
	v_mul_f32_e32 v153, v161, v144
	v_mov_b32_e32 v144, v30
	v_mov_b32_e32 v145, v10
	v_mov_b32_e32 v149, v146
	v_pk_mul_f32 v[144:145], v[144:145], v[148:149]
	v_mov_b32_e32 v146, v151
	v_sub_f32_e32 v144, v144, v145
	v_mul_f32_e32 v150, v161, v144
	v_mov_b32_e32 v144, v10
	v_mov_b32_e32 v145, v30
	v_pk_mul_f32 v[144:145], v[144:145], v[148:149]
	s_nop 0
	v_add_f32_e32 v144, v144, v145
	v_mul_f32_e32 v155, v161, v144
	v_mov_b32_e32 v144, v31
	v_mov_b32_e32 v145, v11
	v_pk_mul_f32 v[144:145], v[144:145], v[146:147]
	s_nop 0
	v_sub_f32_e32 v144, v144, v145
	v_mul_f32_e32 v148, v161, v144
	v_mov_b32_e32 v144, v11
	v_mov_b32_e32 v145, v31
	v_pk_mul_f32 v[144:145], v[144:145], v[146:147]
	s_nop 0
	v_add_f32_e32 v144, v144, v145
	v_mul_f32_e32 v151, v161, v144
	v_ashrrev_i32_e32 v161, 31, v160
	v_cvt_pk_bf16_f32 v144, v166, v162
	v_cvt_pk_bf16_f32 v145, v158, v157
	v_cvt_pk_bf16_f32 v146, v165, v152
	v_cvt_pk_bf16_f32 v147, v150, v148
	v_cvt_pk_bf16_f32 v148, v164, v163
	v_cvt_pk_bf16_f32 v149, v156, v159
	v_cvt_pk_bf16_f32 v150, v154, v153
	v_lshlrev_b64 v[152:153], 12, v[160:161]
	v_lshl_add_u64 v[152:153], v[230:231], 0, v[152:153]
	v_cvt_pk_bf16_f32 v151, v155, v151
	global_store_dwordx4 v[152:153], v[144:147], off
	global_store_dwordx4 v[152:153], v[148:151], off offset:256
	s_nop 0
	v_add_u32_e32 v144, 0xb0, v228
	v_and_b32_e32 v145, 0x7f, v144
	v_add_u32_e32 v145, 1, v145
	v_cvt_f32_ubyte0_e32 v145, v145
	v_mul_f32_e64 v146, v241, -v145
	v_cmp_gt_f32_e64 s[4:5], s7, v146
	v_mov_b32_e32 v147, v4
	v_mov_b32_e32 v148, v140
	v_cndmask_b32_e64 v146, 0, v234, s[4:5]
	v_fma_f32 v145, v241, -v145, v146
	v_exp_f32_e32 v145, v145
	v_cndmask_b32_e64 v146, 0, v235, s[4:5]
	v_mov_b32_e32 v149, v136
	s_mov_b64 s[4:5], 0
	v_ldexp_f32 v145, v145, v146
	v_mov_b32_e32 v146, v20
	v_pk_mul_f32 v[146:147], v[146:147], v[148:149]
	v_mul_f32_e32 v145, 0x3d800000, v145
	v_sub_f32_e32 v136, v146, v147
	v_mov_b32_e32 v146, v4
	v_mov_b32_e32 v147, v20
	v_cndmask_b32_e32 v145, 1.0, v145, vcc
	v_pk_mul_f32 v[146:147], v[146:147], v[148:149]
	v_mul_f32_e32 v150, v145, v136
	v_add_f32_e32 v136, v146, v147
	v_mul_f32_e32 v148, v145, v136
	v_mov_b32_e32 v146, v21
	v_mov_b32_e32 v147, v5
	v_mov_b32_e32 v136, v141
	v_pk_mul_f32 v[140:141], v[146:147], v[136:137]
	s_nop 0
	v_sub_f32_e32 v140, v140, v141
	v_mul_f32_e32 v146, v145, v140
	v_mov_b32_e32 v140, v5
	v_mov_b32_e32 v141, v21
	v_pk_mul_f32 v[136:137], v[140:141], v[136:137]
	v_mov_b32_e32 v140, v142
	v_add_f32_e32 v136, v136, v137
	v_mul_f32_e32 v147, v145, v136
	v_mov_b32_e32 v136, v22
	v_mov_b32_e32 v137, v6
	v_mov_b32_e32 v141, v138
	v_pk_mul_f32 v[136:137], v[136:137], v[140:141]
	v_mov_b32_e32 v138, v143
	v_sub_f32_e32 v136, v136, v137
	v_mul_f32_e32 v142, v145, v136
	v_mov_b32_e32 v136, v6
	v_mov_b32_e32 v137, v22
	v_pk_mul_f32 v[136:137], v[136:137], v[140:141]
	s_nop 0
	v_add_f32_e32 v136, v136, v137
	v_mul_f32_e32 v140, v145, v136
	v_mov_b32_e32 v136, v23
	v_mov_b32_e32 v137, v7
	v_pk_mul_f32 v[136:137], v[136:137], v[138:139]
	s_nop 0
	v_sub_f32_e32 v136, v136, v137
	v_mul_f32_e32 v141, v145, v136
	v_mov_b32_e32 v136, v7
	v_mov_b32_e32 v137, v23
	v_pk_mul_f32 v[136:137], v[136:137], v[138:139]
	v_mov_b32_e32 v138, v132
	v_add_f32_e32 v136, v136, v137
	v_mul_f32_e32 v143, v145, v136
	v_mov_b32_e32 v136, v12
	v_mov_b32_e32 v137, v0
	v_mov_b32_e32 v139, v128
	v_pk_mul_f32 v[136:137], v[136:137], v[138:139]
	s_nop 0
	v_sub_f32_e32 v128, v136, v137
	v_mov_b32_e32 v136, v0
	v_mov_b32_e32 v137, v12
	v_pk_mul_f32 v[136:137], v[136:137], v[138:139]
	v_mul_f32_e32 v149, v145, v128
	v_add_f32_e32 v128, v136, v137
	v_mul_f32_e32 v138, v145, v128
	v_mov_b32_e32 v136, v13
	v_mov_b32_e32 v137, v1
	v_mov_b32_e32 v128, v133
	v_pk_mul_f32 v[132:133], v[136:137], v[128:129]
	s_nop 0
	v_sub_f32_e32 v132, v132, v133
	v_mul_f32_e32 v136, v145, v132
	v_mov_b32_e32 v132, v1
	v_mov_b32_e32 v133, v13
	v_pk_mul_f32 v[128:129], v[132:133], v[128:129]
	v_mov_b32_e32 v132, v134
	v_add_f32_e32 v128, v128, v129
	v_mul_f32_e32 v139, v145, v128
	v_mov_b32_e32 v128, v14
	v_mov_b32_e32 v129, v2
	v_mov_b32_e32 v133, v130
	v_pk_mul_f32 v[128:129], v[128:129], v[132:133]
	v_mov_b32_e32 v130, v135
	v_sub_f32_e32 v128, v128, v129
	v_mul_f32_e32 v137, v145, v128
	v_mov_b32_e32 v128, v2
	v_mov_b32_e32 v129, v14
	v_pk_mul_f32 v[128:129], v[128:129], v[132:133]
	v_cvt_pk_bf16_f32 v134, v150, v146
	v_cvt_pk_bf16_f32 v135, v142, v141
	v_cvt_pk_bf16_f32 v136, v149, v136
	s_nop 0
	v_add_f32_e32 v128, v128, v129
	v_mul_f32_e32 v132, v145, v128
	v_mov_b32_e32 v128, v15
	v_mov_b32_e32 v129, v3
	v_pk_mul_f32 v[128:129], v[128:129], v[130:131]
	s_nop 0
	v_sub_f32_e32 v128, v128, v129
	v_mul_f32_e32 v133, v145, v128
	v_mov_b32_e32 v128, v3
	v_mov_b32_e32 v129, v15
	v_pk_mul_f32 v[128:129], v[128:129], v[130:131]
	v_cvt_pk_bf16_f32 v137, v137, v133
	s_nop 0
	v_add_f32_e32 v128, v128, v129
	v_mul_f32_e32 v131, v145, v128
	v_ashrrev_i32_e32 v145, 31, v144
	v_cvt_pk_bf16_f32 v128, v148, v147
	v_cvt_pk_bf16_f32 v129, v140, v143
	v_cvt_pk_bf16_f32 v130, v138, v139
	v_cvt_pk_bf16_f32 v131, v132, v131
	v_lshlrev_b64 v[132:133], 12, v[144:145]
	v_lshl_add_u64 v[132:133], v[230:231], 0, v[132:133]
	global_store_dwordx4 v[132:133], v[134:137], off

.LBB0_217:
	s_add_u32 s16, s14, 0xfff80080
	s_addc_u32 s17, s15, -1
	s_add_i32 s41, 0, 0x10000
	v_add_u32_e32 v138, s41, v141
	ds_read_b128 v[144:147], v138
	ds_read_b128 v[148:151], v138 offset:1024
	ds_read_b128 v[152:155], v138 offset:2048
	ds_read_b128 v[156:159], v138 offset:3072
	s_cmp_eq_u32 s40, 28
	s_cselect_b32 s19, s7, s17
	s_cselect_b32 s18, s36, s16
	s_cselect_b32 s17, s5, s39
	s_cselect_b32 s16, s37, s38
	v_lshl_add_u64 v[138:139], s[14:15], 0, v[134:135]
	s_add_i32 m0, s13, 0xc000
	ds_read_b128 v[160:163], v143
	ds_read_b128 v[164:167], v143 offset:1024
	ds_read_b128 v[168:171], v143 offset:2048
	ds_read_b128 v[172:175], v143 offset:3072
	ds_read_b128 v[176:179], v143 offset:4096
	ds_read_b128 v[180:183], v143 offset:5120
	ds_read_b128 v[184:187], v143 offset:6144
	ds_read_b128 v[188:191], v143 offset:7168
	global_load_lds_dwordx4 v[138:139], off
	v_lshl_add_u64 v[138:139], s[14:15], 0, v[136:137]
	s_add_i32 m0, s13, 0xe000
	s_nop 0
	global_load_lds_dwordx4 v[138:139], off
	s_waitcnt lgkmcnt(8)
	s_barrier
	s_waitcnt lgkmcnt(0)
	s_waitcnt lgkmcnt(0)
	v_mfma_f32_16x16x32_bf16 v[124:127], v[144:147], v[160:163], v[124:127]
	v_mfma_f32_16x16x32_bf16 v[116:119], v[152:155], v[160:163], v[116:119]
	v_mfma_f32_16x16x32_bf16 v[108:111], v[144:147], v[168:171], v[108:111]
	v_mfma_f32_16x16x32_bf16 v[100:103], v[152:155], v[168:171], v[100:103]
	v_mfma_f32_16x16x32_bf16 v[92:95], v[144:147], v[176:179], v[92:95]
	v_mfma_f32_16x16x32_bf16 v[84:87], v[152:155], v[176:179], v[84:87]
	v_mfma_f32_16x16x32_bf16 v[76:79], v[144:147], v[184:187], v[76:79]
	v_mfma_f32_16x16x32_bf16 v[68:71], v[152:155], v[184:187], v[68:71]
	v_mfma_f32_16x16x32_bf16 v[124:127], v[148:151], v[164:167], v[124:127]
	v_mfma_f32_16x16x32_bf16 v[116:119], v[156:159], v[164:167], v[116:119]
	v_mfma_f32_16x16x32_bf16 v[108:111], v[148:151], v[172:175], v[108:111]
	v_mfma_f32_16x16x32_bf16 v[100:103], v[156:159], v[172:175], v[100:103]
	v_mfma_f32_16x16x32_bf16 v[92:95], v[148:151], v[180:183], v[92:95]
	v_mfma_f32_16x16x32_bf16 v[84:87], v[156:159], v[180:183], v[84:87]
	v_mfma_f32_16x16x32_bf16 v[76:79], v[148:151], v[188:191], v[76:79]
	v_mfma_f32_16x16x32_bf16 v[68:71], v[156:159], v[188:191], v[68:71]
	s_barrier
	s_add_i32 s44, 0, 0x14000
	v_add_u32_e32 v138, s44, v141
	s_add_i32 s41, s41, s26
	ds_read_b128 v[196:199], v138
	ds_read_b128 v[204:207], v138 offset:1024
	ds_read_b128 v[208:211], v138 offset:2048
	ds_read_b128 v[214:217], v138 offset:3072
	v_lshl_add_u64 v[138:139], s[16:17], 0, v[192:193]
	s_mov_b32 m0, s41
	v_lshl_add_u64 v[218:219], s[16:17], 0, v[128:129]
	global_load_lds_dwordx4 v[138:139], off
	s_add_i32 m0, s41, 0x2000
	s_nop 0
	global_load_lds_dwordx4 v[218:219], off
	s_barrier
	s_waitcnt lgkmcnt(0)
	s_waitcnt lgkmcnt(0)
	v_mfma_f32_16x16x32_bf16 v[120:123], v[196:199], v[160:163], v[120:123]
	v_mfma_f32_16x16x32_bf16 v[112:115], v[208:211], v[160:163], v[112:115]
	v_mfma_f32_16x16x32_bf16 v[104:107], v[196:199], v[168:171], v[104:107]
	v_mfma_f32_16x16x32_bf16 v[96:99], v[208:211], v[168:171], v[96:99]
	v_mfma_f32_16x16x32_bf16 v[88:91], v[196:199], v[176:179], v[88:91]
	v_mfma_f32_16x16x32_bf16 v[80:83], v[208:211], v[176:179], v[80:83]
	v_mfma_f32_16x16x32_bf16 v[72:75], v[196:199], v[184:187], v[72:75]
	v_mfma_f32_16x16x32_bf16 v[64:67], v[208:211], v[184:187], v[64:67]
	v_mfma_f32_16x16x32_bf16 v[120:123], v[204:207], v[164:167], v[120:123]
	v_mfma_f32_16x16x32_bf16 v[112:115], v[214:217], v[164:167], v[112:115]
	v_mfma_f32_16x16x32_bf16 v[104:107], v[204:207], v[172:175], v[104:107]
	v_mfma_f32_16x16x32_bf16 v[96:99], v[214:217], v[172:175], v[96:99]
	v_mfma_f32_16x16x32_bf16 v[88:91], v[204:207], v[180:183], v[88:91]
	v_mfma_f32_16x16x32_bf16 v[80:83], v[214:217], v[180:183], v[80:83]
	v_mfma_f32_16x16x32_bf16 v[72:75], v[204:207], v[188:191], v[72:75]
	v_mfma_f32_16x16x32_bf16 v[64:67], v[214:217], v[188:191], v[64:67]
	s_mov_b32 m0, s13
	v_lshl_add_u64 v[220:221], s[18:19], 0, v[132:133]
	s_barrier
	ds_read_b128 v[160:163], v143 offset:16384
	ds_read_b128 v[164:167], v143 offset:17408
	ds_read_b128 v[168:171], v143 offset:18432
	ds_read_b128 v[172:175], v143 offset:19456
	ds_read_b128 v[176:179], v143 offset:20480
	ds_read_b128 v[180:183], v143 offset:21504
	ds_read_b128 v[184:187], v143 offset:22528
	ds_read_b128 v[188:191], v143 offset:23552
	global_load_lds_dwordx4 v[220:221], off
	v_lshl_add_u64 v[222:223], s[18:19], 0, v[130:131]
	s_mov_b32 m0, s28
	s_nop 0
	global_load_lds_dwordx4 v[222:223], off
	s_barrier
	s_waitcnt lgkmcnt(0)
	s_waitcnt lgkmcnt(0)
	v_mfma_f32_16x16x32_bf16 v[60:63], v[144:147], v[160:163], v[60:63]
	v_mfma_f32_16x16x32_bf16 v[52:55], v[152:155], v[160:163], v[52:55]
	v_mfma_f32_16x16x32_bf16 v[44:47], v[144:147], v[168:171], v[44:47]
	v_mfma_f32_16x16x32_bf16 v[36:39], v[152:155], v[168:171], v[36:39]
	v_mfma_f32_16x16x32_bf16 v[28:31], v[144:147], v[176:179], v[28:31]
	v_mfma_f32_16x16x32_bf16 v[20:23], v[152:155], v[176:179], v[20:23]
	v_mfma_f32_16x16x32_bf16 v[12:15], v[144:147], v[184:187], v[12:15]
	v_mfma_f32_16x16x32_bf16 v[4:7], v[152:155], v[184:187], v[4:7]
	v_mfma_f32_16x16x32_bf16 v[60:63], v[148:151], v[164:167], v[60:63]
	v_mfma_f32_16x16x32_bf16 v[52:55], v[156:159], v[164:167], v[52:55]
	v_mfma_f32_16x16x32_bf16 v[44:47], v[148:151], v[172:175], v[44:47]
	v_mfma_f32_16x16x32_bf16 v[36:39], v[156:159], v[172:175], v[36:39]
	v_mfma_f32_16x16x32_bf16 v[28:31], v[148:151], v[180:183], v[28:31]
	v_mfma_f32_16x16x32_bf16 v[20:23], v[156:159], v[180:183], v[20:23]
	v_mfma_f32_16x16x32_bf16 v[12:15], v[148:151], v[188:191], v[12:15]
	v_mfma_f32_16x16x32_bf16 v[4:7], v[156:159], v[188:191], v[4:7]
	s_barrier
	s_add_u32 s42, s16, 0x80000
	s_addc_u32 s43, s17, 0
	s_add_i32 s41, s44, s26
	v_lshl_add_u64 v[144:145], s[42:43], 0, v[192:193]
	s_mov_b32 m0, s41
	s_nop 0
	global_load_lds_dwordx4 v[144:145], off
	v_lshl_add_u64 v[144:145], s[42:43], 0, v[128:129]
	s_add_i32 m0, s41, 0x2000
	s_nop 0
	global_load_lds_dwordx4 v[144:145], off
	s_waitcnt vmcnt(6)
	s_barrier
	v_mfma_f32_16x16x32_bf16 v[56:59], v[196:199], v[160:163], v[56:59]
	v_mfma_f32_16x16x32_bf16 v[48:51], v[208:211], v[160:163], v[48:51]
	v_mfma_f32_16x16x32_bf16 v[40:43], v[196:199], v[168:171], v[40:43]
	v_mfma_f32_16x16x32_bf16 v[32:35], v[208:211], v[168:171], v[32:35]
	v_mfma_f32_16x16x32_bf16 v[24:27], v[196:199], v[176:179], v[24:27]
	v_mfma_f32_16x16x32_bf16 v[16:19], v[208:211], v[176:179], v[16:19]
	v_mfma_f32_16x16x32_bf16 v[8:11], v[196:199], v[184:187], v[8:11]
	v_mfma_f32_16x16x32_bf16 v[0:3], v[208:211], v[184:187], v[0:3]
	v_mfma_f32_16x16x32_bf16 v[56:59], v[204:207], v[164:167], v[56:59]
	v_mfma_f32_16x16x32_bf16 v[48:51], v[214:217], v[164:167], v[48:51]
	v_mfma_f32_16x16x32_bf16 v[40:43], v[204:207], v[172:175], v[40:43]
	v_mfma_f32_16x16x32_bf16 v[32:35], v[214:217], v[172:175], v[32:35]
	v_mfma_f32_16x16x32_bf16 v[24:27], v[204:207], v[180:183], v[24:27]
	v_mfma_f32_16x16x32_bf16 v[16:19], v[214:217], v[180:183], v[16:19]
	v_mfma_f32_16x16x32_bf16 v[8:11], v[204:207], v[188:191], v[8:11]
	v_mfma_f32_16x16x32_bf16 v[0:3], v[214:217], v[188:191], v[0:3]
	s_add_i32 s41, 0, 0x18000
	v_add_u32_e32 v156, s41, v141
	s_barrier
	ds_read_b128 v[144:147], v156
	ds_read_b128 v[148:151], v156 offset:1024
	ds_read_b128 v[152:155], v156 offset:2048
	ds_read_b128 v[156:159], v156 offset:3072
	s_add_u32 s18, s18, 0x80000
	s_addc_u32 s19, s19, 0
	s_mov_b32 m0, s29
	v_lshl_add_u64 v[196:197], s[18:19], 0, v[132:133]
	ds_read_b128 v[160:163], v143 offset:32768
	ds_read_b128 v[164:167], v143 offset:33792
	ds_read_b128 v[168:171], v143 offset:34816
	ds_read_b128 v[172:175], v143 offset:35840
	ds_read_b128 v[176:179], v143 offset:36864
	ds_read_b128 v[180:183], v143 offset:37888
	ds_read_b128 v[184:187], v143 offset:38912
	ds_read_b128 v[188:191], v143 offset:39936
	global_load_lds_dwordx4 v[196:197], off
	v_lshl_add_u64 v[196:197], s[18:19], 0, v[130:131]
	s_mov_b32 m0, s30
	s_nop 0
	global_load_lds_dwordx4 v[196:197], off
	s_waitcnt lgkmcnt(8)
	s_barrier
	s_waitcnt lgkmcnt(0)
	s_waitcnt lgkmcnt(0)
	v_mfma_f32_16x16x32_bf16 v[124:127], v[144:147], v[160:163], v[124:127]
	v_mfma_f32_16x16x32_bf16 v[116:119], v[152:155], v[160:163], v[116:119]
	v_mfma_f32_16x16x32_bf16 v[108:111], v[144:147], v[168:171], v[108:111]
	v_mfma_f32_16x16x32_bf16 v[100:103], v[152:155], v[168:171], v[100:103]
	v_mfma_f32_16x16x32_bf16 v[92:95], v[144:147], v[176:179], v[92:95]
	v_mfma_f32_16x16x32_bf16 v[84:87], v[152:155], v[176:179], v[84:87]
	v_mfma_f32_16x16x32_bf16 v[76:79], v[144:147], v[184:187], v[76:79]
	v_mfma_f32_16x16x32_bf16 v[68:71], v[152:155], v[184:187], v[68:71]
	v_mfma_f32_16x16x32_bf16 v[124:127], v[148:151], v[164:167], v[124:127]
	v_mfma_f32_16x16x32_bf16 v[116:119], v[156:159], v[164:167], v[116:119]
	v_mfma_f32_16x16x32_bf16 v[108:111], v[148:151], v[172:175], v[108:111]
	v_mfma_f32_16x16x32_bf16 v[100:103], v[156:159], v[172:175], v[100:103]
	v_mfma_f32_16x16x32_bf16 v[92:95], v[148:151], v[180:183], v[92:95]
	v_mfma_f32_16x16x32_bf16 v[84:87], v[156:159], v[180:183], v[84:87]
	v_mfma_f32_16x16x32_bf16 v[76:79], v[148:151], v[188:191], v[76:79]
	v_mfma_f32_16x16x32_bf16 v[68:71], v[156:159], v[188:191], v[68:71]
	s_barrier
	s_add_i32 s18, 0, 0x1c000
	s_add_i32 s19, s41, s26
	v_add_u32_e32 v212, s18, v141
	v_lshl_add_u64 v[138:139], v[138:139], 0, s[48:49]
	s_mov_b32 m0, s19
	ds_read_b128 v[196:199], v212
	ds_read_b128 v[204:207], v212 offset:1024
	ds_read_b128 v[208:211], v212 offset:2048
	ds_read_b128 v[214:217], v212 offset:3072
	global_load_lds_dwordx4 v[138:139], off
	v_lshl_add_u64 v[138:139], v[218:219], 0, s[48:49]
	s_add_i32 m0, s19, 0x2000
	s_nop 0
	global_load_lds_dwordx4 v[138:139], off
	s_barrier
	s_waitcnt lgkmcnt(0)
	s_waitcnt lgkmcnt(0)
	v_mfma_f32_16x16x32_bf16 v[120:123], v[196:199], v[160:163], v[120:123]
	v_mfma_f32_16x16x32_bf16 v[112:115], v[208:211], v[160:163], v[112:115]
	v_mfma_f32_16x16x32_bf16 v[104:107], v[196:199], v[168:171], v[104:107]
	v_mfma_f32_16x16x32_bf16 v[96:99], v[208:211], v[168:171], v[96:99]
	v_mfma_f32_16x16x32_bf16 v[88:91], v[196:199], v[176:179], v[88:91]
	v_mfma_f32_16x16x32_bf16 v[80:83], v[208:211], v[176:179], v[80:83]
	v_mfma_f32_16x16x32_bf16 v[72:75], v[196:199], v[184:187], v[72:75]
	v_mfma_f32_16x16x32_bf16 v[64:67], v[208:211], v[184:187], v[64:67]
	v_mfma_f32_16x16x32_bf16 v[120:123], v[204:207], v[164:167], v[120:123]
	v_mfma_f32_16x16x32_bf16 v[112:115], v[214:217], v[164:167], v[112:115]
	v_mfma_f32_16x16x32_bf16 v[104:107], v[204:207], v[172:175], v[104:107]
	v_mfma_f32_16x16x32_bf16 v[96:99], v[214:217], v[172:175], v[96:99]
	v_mfma_f32_16x16x32_bf16 v[88:91], v[204:207], v[180:183], v[88:91]
	v_mfma_f32_16x16x32_bf16 v[80:83], v[214:217], v[180:183], v[80:83]
	v_mfma_f32_16x16x32_bf16 v[72:75], v[204:207], v[188:191], v[72:75]
	v_mfma_f32_16x16x32_bf16 v[64:67], v[214:217], v[188:191], v[64:67]
	s_mov_b32 m0, s33
	v_lshl_add_u64 v[138:139], v[220:221], 0, s[48:49]
	s_barrier
	ds_read_b128 v[160:163], v143 offset:49152
	ds_read_b128 v[164:167], v143 offset:50176
	ds_read_b128 v[168:171], v143 offset:51200
	ds_read_b128 v[172:175], v143 offset:52224
	ds_read_b128 v[176:179], v143 offset:53248
	ds_read_b128 v[180:183], v143 offset:54272
	ds_read_b128 v[184:187], v143 offset:55296
	ds_read_b128 v[188:191], v143 offset:56320
	global_load_lds_dwordx4 v[138:139], off
	v_lshl_add_u64 v[138:139], v[222:223], 0, s[48:49]
	s_mov_b32 m0, s34
	s_nop 0
	global_load_lds_dwordx4 v[138:139], off
	s_barrier
	s_waitcnt lgkmcnt(0)
	s_waitcnt lgkmcnt(0)
	v_mfma_f32_16x16x32_bf16 v[60:63], v[144:147], v[160:163], v[60:63]
	v_mfma_f32_16x16x32_bf16 v[52:55], v[152:155], v[160:163], v[52:55]
	v_mfma_f32_16x16x32_bf16 v[44:47], v[144:147], v[168:171], v[44:47]
	v_mfma_f32_16x16x32_bf16 v[36:39], v[152:155], v[168:171], v[36:39]
	v_mfma_f32_16x16x32_bf16 v[28:31], v[144:147], v[176:179], v[28:31]
	v_mfma_f32_16x16x32_bf16 v[20:23], v[152:155], v[176:179], v[20:23]
	v_mfma_f32_16x16x32_bf16 v[12:15], v[144:147], v[184:187], v[12:15]
	v_mfma_f32_16x16x32_bf16 v[4:7], v[152:155], v[184:187], v[4:7]
	v_mfma_f32_16x16x32_bf16 v[60:63], v[148:151], v[164:167], v[60:63]
	v_mfma_f32_16x16x32_bf16 v[52:55], v[156:159], v[164:167], v[52:55]
	v_mfma_f32_16x16x32_bf16 v[44:47], v[148:151], v[172:175], v[44:47]
	v_mfma_f32_16x16x32_bf16 v[36:39], v[156:159], v[172:175], v[36:39]
	v_mfma_f32_16x16x32_bf16 v[28:31], v[148:151], v[180:183], v[28:31]
	v_mfma_f32_16x16x32_bf16 v[20:23], v[156:159], v[180:183], v[20:23]
	v_mfma_f32_16x16x32_bf16 v[12:15], v[148:151], v[188:191], v[12:15]
	v_mfma_f32_16x16x32_bf16 v[4:7], v[156:159], v[188:191], v[4:7]
	s_barrier
	s_add_u32 s16, s16, 0x80080
	s_addc_u32 s17, s17, 0
	s_add_i32 s18, s18, s26
	v_lshl_add_u64 v[138:139], s[16:17], 0, v[192:193]
	s_mov_b32 m0, s18
	s_nop 0
	global_load_lds_dwordx4 v[138:139], off
	v_lshl_add_u64 v[138:139], s[16:17], 0, v[128:129]
	s_add_i32 m0, s18, 0x2000
	s_nop 0
	global_load_lds_dwordx4 v[138:139], off
	s_waitcnt vmcnt(6)
	s_barrier
	v_mfma_f32_16x16x32_bf16 v[56:59], v[196:199], v[160:163], v[56:59]
	v_mfma_f32_16x16x32_bf16 v[48:51], v[208:211], v[160:163], v[48:51]
	v_mfma_f32_16x16x32_bf16 v[40:43], v[196:199], v[168:171], v[40:43]
	v_mfma_f32_16x16x32_bf16 v[32:35], v[208:211], v[168:171], v[32:35]
	v_mfma_f32_16x16x32_bf16 v[24:27], v[196:199], v[176:179], v[24:27]
	v_mfma_f32_16x16x32_bf16 v[16:19], v[208:211], v[176:179], v[16:19]
	v_mfma_f32_16x16x32_bf16 v[8:11], v[196:199], v[184:187], v[8:11]
	v_mfma_f32_16x16x32_bf16 v[0:3], v[208:211], v[184:187], v[0:3]
	v_mfma_f32_16x16x32_bf16 v[56:59], v[204:207], v[164:167], v[56:59]
	v_mfma_f32_16x16x32_bf16 v[48:51], v[214:217], v[164:167], v[48:51]
	v_mfma_f32_16x16x32_bf16 v[40:43], v[204:207], v[172:175], v[40:43]
	v_mfma_f32_16x16x32_bf16 v[32:35], v[214:217], v[172:175], v[32:35]
	v_mfma_f32_16x16x32_bf16 v[24:27], v[204:207], v[180:183], v[24:27]
	v_mfma_f32_16x16x32_bf16 v[16:19], v[214:217], v[180:183], v[16:19]
	v_mfma_f32_16x16x32_bf16 v[8:11], v[204:207], v[188:191], v[8:11]
	v_mfma_f32_16x16x32_bf16 v[0:3], v[214:217], v[188:191], v[0:3]
	s_add_i32 s40, s40, 2
	s_add_u32 s14, s14, 0x100
	s_addc_u32 s15, s15, 0
	s_add_u32 s38, s38, 0x100
	s_addc_u32 s39, s39, 0
	s_cmp_gt_u32 s40, 29
	s_barrier
	s_cbranch_scc0 .LBB0_217
	v_mul_f32_e32 v145, 0xbfb8aa3b, v124
	v_exp_f32_e32 v145, v145
	v_lshl_or_b32 v146, s35, 7, v142
	v_lshl_add_u32 v144, s12, 8, v140
	v_ashrrev_i32_e32 v147, 31, v146
	v_add_f32_e32 v145, 1.0, v145
	v_rcp_f32_e32 v145, v145
	v_mov_b64_e32 v[138:139], s[2:3]
	s_movk_i32 s5, 0x2c00
	v_mad_i64_i32 v[148:149], s[14:15], v144, s5, v[138:139]
	v_mul_f32_e32 v124, v124, v145
	v_mul_f32_e32 v120, v124, v120
	v_mul_f32_e32 v124, 0xbfb8aa3b, v125
	v_exp_f32_e32 v124, v124
	s_and_b64 vcc, exec, s[0:1]
	s_mov_b32 s35, s4
	s_mov_b32 s12, s6
	v_add_f32_e32 v124, 1.0, v124
	v_rcp_f32_e32 v124, v124
	s_mov_b64 s[16:17], s[10:11]
	v_mul_f32_e32 v124, v125, v124
	v_mul_f32_e32 v121, v124, v121
	v_mul_f32_e32 v124, 0xbfb8aa3b, v126
	v_exp_f32_e32 v124, v124
	s_nop 0
	v_add_f32_e32 v124, 1.0, v124
	v_rcp_f32_e32 v124, v124
	s_nop 0
	v_mul_f32_e32 v124, v126, v124
	v_mul_f32_e32 v122, v124, v122
	v_mul_f32_e32 v124, 0xbfb8aa3b, v127
	v_exp_f32_e32 v124, v124
	s_nop 0
	v_add_f32_e32 v124, 1.0, v124
	v_rcp_f32_e32 v124, v124
	s_nop 0
	v_mul_f32_e32 v124, v127, v124
	v_mul_f32_e32 v123, v124, v123
	v_mul_f32_e32 v124, 0xbfb8aa3b, v116
	v_exp_f32_e32 v124, v124
	s_nop 0
	v_add_f32_e32 v124, 1.0, v124
	v_rcp_f32_e32 v124, v124
	s_nop 0
	v_mul_f32_e32 v116, v116, v124
	v_mul_f32_e32 v116, v116, v112
	v_mul_f32_e32 v112, 0xbfb8aa3b, v117
	v_exp_f32_e32 v112, v112
	s_nop 0
	v_add_f32_e32 v112, 1.0, v112
	v_rcp_f32_e32 v112, v112
	s_nop 0
	v_mul_f32_e32 v112, v117, v112
	v_mul_f32_e32 v117, v112, v113
	v_mul_f32_e32 v112, 0xbfb8aa3b, v118
	v_exp_f32_e32 v112, v112
	s_nop 0
	v_add_f32_e32 v112, 1.0, v112
	v_rcp_f32_e32 v112, v112
	s_nop 0
	v_mul_f32_e32 v112, v118, v112
	v_mul_f32_e32 v124, v112, v114
	v_mul_f32_e32 v112, 0xbfb8aa3b, v119
	v_exp_f32_e32 v112, v112
	v_cvt_pk_bf16_f32 v114, v120, v121
	s_nop 0
	v_add_f32_e32 v112, 1.0, v112
	v_rcp_f32_e32 v112, v112
	s_nop 0
	v_mul_f32_e32 v112, v119, v112
	v_mul_f32_e32 v125, v112, v115
	v_lshlrev_b64 v[112:113], 1, v[146:147]
	v_lshl_add_u64 v[118:119], v[148:149], 0, v[112:113]
	v_cvt_pk_bf16_f32 v115, v122, v123
	v_cvt_pk_bf16_f32 v116, v116, v117
	v_cvt_pk_bf16_f32 v117, v124, v125
	global_store_dwordx4 v[118:119], v[114:117], off
	s_nop 1
	v_mul_f32_e32 v116, 0xbfb8aa3b, v108
	v_exp_f32_e32 v116, v116
	v_or_b32_e32 v114, 16, v144
	v_mad_i64_i32 v[114:115], s[14:15], v114, s5, v[138:139]
	v_add_f32_e32 v116, 1.0, v116
	v_rcp_f32_e32 v116, v116
	s_nop 0
	v_mul_f32_e32 v108, v108, v116
	v_mul_f32_e32 v104, v108, v104
	v_mul_f32_e32 v108, 0xbfb8aa3b, v109
	v_exp_f32_e32 v108, v108
	s_nop 0
	v_add_f32_e32 v108, 1.0, v108
	v_rcp_f32_e32 v108, v108
	s_nop 0
	v_mul_f32_e32 v108, v109, v108
	v_mul_f32_e32 v105, v108, v105
	v_mul_f32_e32 v108, 0xbfb8aa3b, v110
	v_exp_f32_e32 v108, v108
	s_nop 0
	v_add_f32_e32 v108, 1.0, v108
	v_rcp_f32_e32 v108, v108
	s_nop 0
	v_mul_f32_e32 v108, v110, v108
	v_mul_f32_e32 v106, v108, v106
	v_mul_f32_e32 v108, 0xbfb8aa3b, v111
	v_exp_f32_e32 v108, v108
	s_nop 0
	v_add_f32_e32 v108, 1.0, v108
	v_rcp_f32_e32 v108, v108
	s_nop 0
	v_mul_f32_e32 v108, v111, v108
	v_mul_f32_e32 v107, v108, v107
	v_mul_f32_e32 v108, 0xbfb8aa3b, v100
	v_exp_f32_e32 v108, v108
	s_nop 0
	v_add_f32_e32 v108, 1.0, v108
	v_rcp_f32_e32 v108, v108
	s_nop 0
	v_mul_f32_e32 v100, v100, v108
	v_mul_f32_e32 v108, v100, v96
	v_mul_f32_e32 v96, 0xbfb8aa3b, v101
	v_exp_f32_e32 v96, v96
	s_nop 0
	v_add_f32_e32 v96, 1.0, v96
	v_rcp_f32_e32 v96, v96
	s_nop 0
	v_mul_f32_e32 v96, v101, v96
	v_mul_f32_e32 v109, v96, v97
	v_mul_f32_e32 v96, 0xbfb8aa3b, v102
	v_exp_f32_e32 v96, v96
	v_lshl_add_u64 v[100:101], v[114:115], 0, v[112:113]
	v_add_f32_e32 v96, 1.0, v96
	v_rcp_f32_e32 v96, v96
	s_nop 0
	v_mul_f32_e32 v96, v102, v96
	v_mul_f32_e32 v102, v96, v98
	v_mul_f32_e32 v96, 0xbfb8aa3b, v103
	v_exp_f32_e32 v96, v96
	s_nop 0
	v_add_f32_e32 v96, 1.0, v96
	v_rcp_f32_e32 v96, v96
	s_nop 0
	v_mul_f32_e32 v96, v103, v96
	v_mul_f32_e32 v99, v96, v99
	v_cvt_pk_bf16_f32 v96, v104, v105
	v_cvt_pk_bf16_f32 v97, v106, v107
	v_cvt_pk_bf16_f32 v98, v108, v109
	v_cvt_pk_bf16_f32 v99, v102, v99
	global_store_dwordx4 v[100:101], v[96:99], off
	s_nop 1
	v_mul_f32_e32 v98, 0xbfb8aa3b, v92
	v_exp_f32_e32 v98, v98
	v_or_b32_e32 v96, 32, v144
	v_mad_i64_i32 v[96:97], s[14:15], v96, s5, v[138:139]
	v_add_f32_e32 v98, 1.0, v98
	v_rcp_f32_e32 v98, v98
	s_nop 0
	v_mul_f32_e32 v92, v92, v98
	v_mul_f32_e32 v88, v92, v88
	v_mul_f32_e32 v92, 0xbfb8aa3b, v93
	v_exp_f32_e32 v92, v92
	s_nop 0
	v_add_f32_e32 v92, 1.0, v92
	v_rcp_f32_e32 v92, v92
	s_nop 0
	v_mul_f32_e32 v92, v93, v92
	v_mul_f32_e32 v89, v92, v89
	v_mul_f32_e32 v92, 0xbfb8aa3b, v94
	v_exp_f32_e32 v92, v92
	s_nop 0
	v_add_f32_e32 v92, 1.0, v92
	v_rcp_f32_e32 v92, v92
	s_nop 0
	v_mul_f32_e32 v92, v94, v92
	v_mul_f32_e32 v90, v92, v90
	v_mul_f32_e32 v92, 0xbfb8aa3b, v95
	v_exp_f32_e32 v92, v92
	s_nop 0
	v_add_f32_e32 v92, 1.0, v92
	v_rcp_f32_e32 v92, v92
	s_nop 0
	v_mul_f32_e32 v92, v95, v92
	v_mul_f32_e32 v91, v92, v91
	v_mul_f32_e32 v92, 0xbfb8aa3b, v84
	v_exp_f32_e32 v92, v92
	s_nop 0
	v_add_f32_e32 v92, 1.0, v92
	v_rcp_f32_e32 v92, v92
	s_nop 0
	v_mul_f32_e32 v84, v84, v92
	v_mul_f32_e32 v92, v84, v80
	v_mul_f32_e32 v80, 0xbfb8aa3b, v85
	v_exp_f32_e32 v80, v80
	s_nop 0
	v_add_f32_e32 v80, 1.0, v80
	v_rcp_f32_e32 v80, v80
	s_nop 0
	v_mul_f32_e32 v80, v85, v80
	v_mul_f32_e32 v93, v80, v81
	v_mul_f32_e32 v80, 0xbfb8aa3b, v86
	v_exp_f32_e32 v80, v80
	v_lshl_add_u64 v[84:85], v[96:97], 0, v[112:113]
	v_add_f32_e32 v80, 1.0, v80
	v_rcp_f32_e32 v80, v80
	s_nop 0
	v_mul_f32_e32 v80, v86, v80
	v_mul_f32_e32 v86, v80, v82
	v_mul_f32_e32 v80, 0xbfb8aa3b, v87
	v_exp_f32_e32 v80, v80
	s_nop 0
	v_add_f32_e32 v80, 1.0, v80
	v_rcp_f32_e32 v80, v80
	s_nop 0
	v_mul_f32_e32 v80, v87, v80
	v_mul_f32_e32 v83, v80, v83
	v_cvt_pk_bf16_f32 v80, v88, v89
	v_cvt_pk_bf16_f32 v81, v90, v91
	v_cvt_pk_bf16_f32 v82, v92, v93
	v_cvt_pk_bf16_f32 v83, v86, v83
	global_store_dwordx4 v[84:85], v[80:83], off
	s_nop 1
	v_mul_f32_e32 v82, 0xbfb8aa3b, v76
	v_exp_f32_e32 v82, v82
	v_or_b32_e32 v80, 48, v144
	v_mad_i64_i32 v[80:81], s[14:15], v80, s5, v[138:139]
	v_add_f32_e32 v82, 1.0, v82
	v_rcp_f32_e32 v82, v82
	s_nop 0
	v_mul_f32_e32 v76, v76, v82
	v_mul_f32_e32 v72, v76, v72
	v_mul_f32_e32 v76, 0xbfb8aa3b, v77
	v_exp_f32_e32 v76, v76
	s_nop 0
	v_add_f32_e32 v76, 1.0, v76
	v_rcp_f32_e32 v76, v76
	s_nop 0
	v_mul_f32_e32 v76, v77, v76
	v_mul_f32_e32 v73, v76, v73
	v_mul_f32_e32 v76, 0xbfb8aa3b, v78
	v_exp_f32_e32 v76, v76
	s_nop 0
	v_add_f32_e32 v76, 1.0, v76
	v_rcp_f32_e32 v76, v76
	s_nop 0
	v_mul_f32_e32 v76, v78, v76
	v_mul_f32_e32 v74, v76, v74
	v_mul_f32_e32 v76, 0xbfb8aa3b, v79
	v_exp_f32_e32 v76, v76
	s_nop 0
	v_add_f32_e32 v76, 1.0, v76
	v_rcp_f32_e32 v76, v76
	s_nop 0
	v_mul_f32_e32 v76, v79, v76
	v_mul_f32_e32 v75, v76, v75
	v_mul_f32_e32 v76, 0xbfb8aa3b, v68
	v_exp_f32_e32 v76, v76
	s_nop 0
	v_add_f32_e32 v76, 1.0, v76
	v_rcp_f32_e32 v76, v76
	s_nop 0
	v_mul_f32_e32 v68, v68, v76
	v_mul_f32_e32 v76, v68, v64
	v_mul_f32_e32 v64, 0xbfb8aa3b, v69
	v_exp_f32_e32 v64, v64
	s_nop 0
	v_add_f32_e32 v64, 1.0, v64
	v_rcp_f32_e32 v64, v64
	s_nop 0
	v_mul_f32_e32 v64, v69, v64
	v_mul_f32_e32 v77, v64, v65
	v_mul_f32_e32 v64, 0xbfb8aa3b, v70
	v_exp_f32_e32 v64, v64
	v_lshl_add_u64 v[68:69], v[80:81], 0, v[112:113]
	v_add_f32_e32 v64, 1.0, v64
	v_rcp_f32_e32 v64, v64
	s_nop 0
	v_mul_f32_e32 v64, v70, v64
	v_mul_f32_e32 v70, v64, v66
	v_mul_f32_e32 v64, 0xbfb8aa3b, v71
	v_exp_f32_e32 v64, v64
	s_nop 0
	v_add_f32_e32 v64, 1.0, v64
	v_rcp_f32_e32 v64, v64
	s_nop 0
	v_mul_f32_e32 v64, v71, v64
	v_mul_f32_e32 v67, v64, v67
	v_cvt_pk_bf16_f32 v64, v72, v73
	v_cvt_pk_bf16_f32 v65, v74, v75
	v_cvt_pk_bf16_f32 v66, v76, v77
	v_cvt_pk_bf16_f32 v67, v70, v67
	global_store_dwordx4 v[68:69], v[64:67], off
	s_nop 1
	v_mul_f32_e32 v66, 0xbfb8aa3b, v60
	v_exp_f32_e32 v66, v66
	v_add_u32_e32 v64, 0x80, v144
	v_mad_i64_i32 v[64:65], s[14:15], v64, s5, v[138:139]
	v_add_f32_e32 v66, 1.0, v66
	v_rcp_f32_e32 v66, v66
	s_nop 0
	v_mul_f32_e32 v60, v60, v66
	v_mul_f32_e32 v56, v60, v56
	v_mul_f32_e32 v60, 0xbfb8aa3b, v61
	v_exp_f32_e32 v60, v60
	s_nop 0
	v_add_f32_e32 v60, 1.0, v60
	v_rcp_f32_e32 v60, v60
	s_nop 0
	v_mul_f32_e32 v60, v61, v60
	v_mul_f32_e32 v57, v60, v57
	v_mul_f32_e32 v60, 0xbfb8aa3b, v62
	v_exp_f32_e32 v60, v60
	s_nop 0
	v_add_f32_e32 v60, 1.0, v60
	v_rcp_f32_e32 v60, v60
	s_nop 0
	v_mul_f32_e32 v60, v62, v60
	v_mul_f32_e32 v58, v60, v58
	v_mul_f32_e32 v60, 0xbfb8aa3b, v63
	v_exp_f32_e32 v60, v60
	s_nop 0
	v_add_f32_e32 v60, 1.0, v60
	v_rcp_f32_e32 v60, v60
	s_nop 0
	v_mul_f32_e32 v60, v63, v60
	v_mul_f32_e32 v59, v60, v59
	v_mul_f32_e32 v60, 0xbfb8aa3b, v52
	v_exp_f32_e32 v60, v60
	s_nop 0
	v_add_f32_e32 v60, 1.0, v60
	v_rcp_f32_e32 v60, v60
	s_nop 0
	v_mul_f32_e32 v52, v52, v60
	v_mul_f32_e32 v60, v52, v48
	v_mul_f32_e32 v48, 0xbfb8aa3b, v53
	v_exp_f32_e32 v48, v48
	s_nop 0
	v_add_f32_e32 v48, 1.0, v48
	v_rcp_f32_e32 v48, v48
	s_nop 0
	v_mul_f32_e32 v48, v53, v48
	v_mul_f32_e32 v61, v48, v49
	v_mul_f32_e32 v48, 0xbfb8aa3b, v54
	v_exp_f32_e32 v48, v48
	v_lshl_add_u64 v[52:53], v[64:65], 0, v[112:113]
	v_add_f32_e32 v48, 1.0, v48
	v_rcp_f32_e32 v48, v48
	s_nop 0
	v_mul_f32_e32 v48, v54, v48
	v_mul_f32_e32 v54, v48, v50
	v_mul_f32_e32 v48, 0xbfb8aa3b, v55
	v_exp_f32_e32 v48, v48
	s_nop 0
	v_add_f32_e32 v48, 1.0, v48
	v_rcp_f32_e32 v48, v48
	s_nop 0
	v_mul_f32_e32 v48, v55, v48
	v_mul_f32_e32 v51, v48, v51
	v_cvt_pk_bf16_f32 v48, v56, v57
	v_cvt_pk_bf16_f32 v49, v58, v59
	v_cvt_pk_bf16_f32 v50, v60, v61
	v_cvt_pk_bf16_f32 v51, v54, v51
	global_store_dwordx4 v[52:53], v[48:51], off
	s_nop 1
	v_mul_f32_e32 v50, 0xbfb8aa3b, v44
	v_exp_f32_e32 v50, v50
	v_add_u32_e32 v48, 0x90, v144
	v_mad_i64_i32 v[48:49], s[14:15], v48, s5, v[138:139]
	v_add_f32_e32 v50, 1.0, v50
	v_rcp_f32_e32 v50, v50
	s_nop 0
	v_mul_f32_e32 v44, v44, v50
	v_mul_f32_e32 v40, v44, v40
	v_mul_f32_e32 v44, 0xbfb8aa3b, v45
	v_exp_f32_e32 v44, v44
	s_nop 0
	v_add_f32_e32 v44, 1.0, v44
	v_rcp_f32_e32 v44, v44
	s_nop 0
	v_mul_f32_e32 v44, v45, v44
	v_mul_f32_e32 v41, v44, v41
	v_mul_f32_e32 v44, 0xbfb8aa3b, v46
	v_exp_f32_e32 v44, v44
	s_nop 0
	v_add_f32_e32 v44, 1.0, v44
	v_rcp_f32_e32 v44, v44
	s_nop 0
	v_mul_f32_e32 v44, v46, v44
	v_mul_f32_e32 v42, v44, v42
	v_mul_f32_e32 v44, 0xbfb8aa3b, v47
	v_exp_f32_e32 v44, v44
	s_nop 0
	v_add_f32_e32 v44, 1.0, v44
	v_rcp_f32_e32 v44, v44
	s_nop 0
	v_mul_f32_e32 v44, v47, v44
	v_mul_f32_e32 v43, v44, v43
	v_mul_f32_e32 v44, 0xbfb8aa3b, v36
	v_exp_f32_e32 v44, v44
	s_nop 0
	v_add_f32_e32 v44, 1.0, v44
	v_rcp_f32_e32 v44, v44
	s_nop 0
	v_mul_f32_e32 v36, v36, v44
	v_mul_f32_e32 v44, v36, v32
	v_mul_f32_e32 v32, 0xbfb8aa3b, v37
	v_exp_f32_e32 v32, v32
	s_nop 0
	v_add_f32_e32 v32, 1.0, v32
	v_rcp_f32_e32 v32, v32
	s_nop 0
	v_mul_f32_e32 v32, v37, v32
	v_mul_f32_e32 v45, v32, v33
	v_mul_f32_e32 v32, 0xbfb8aa3b, v38
	v_exp_f32_e32 v32, v32
	v_lshl_add_u64 v[36:37], v[48:49], 0, v[112:113]
	v_add_f32_e32 v32, 1.0, v32
	v_rcp_f32_e32 v32, v32
	s_nop 0
	v_mul_f32_e32 v32, v38, v32
	v_mul_f32_e32 v38, v32, v34
	v_mul_f32_e32 v32, 0xbfb8aa3b, v39
	v_exp_f32_e32 v32, v32
	s_nop 0
	v_add_f32_e32 v32, 1.0, v32
	v_rcp_f32_e32 v32, v32
	s_nop 0
	v_mul_f32_e32 v32, v39, v32
	v_mul_f32_e32 v35, v32, v35
	v_cvt_pk_bf16_f32 v32, v40, v41
	v_cvt_pk_bf16_f32 v33, v42, v43
	v_cvt_pk_bf16_f32 v34, v44, v45
	v_cvt_pk_bf16_f32 v35, v38, v35
	global_store_dwordx4 v[36:37], v[32:35], off
	s_nop 1
	v_mul_f32_e32 v34, 0xbfb8aa3b, v28
	v_exp_f32_e32 v34, v34
	v_add_u32_e32 v32, 0xa0, v144
	v_mad_i64_i32 v[32:33], s[14:15], v32, s5, v[138:139]
	v_add_f32_e32 v34, 1.0, v34
	v_rcp_f32_e32 v34, v34
	s_nop 0
	v_mul_f32_e32 v28, v28, v34
	v_mul_f32_e32 v24, v28, v24
	v_mul_f32_e32 v28, 0xbfb8aa3b, v29
	v_exp_f32_e32 v28, v28
	s_nop 0
	v_add_f32_e32 v28, 1.0, v28
	v_rcp_f32_e32 v28, v28
	s_nop 0
	v_mul_f32_e32 v28, v29, v28
	v_mul_f32_e32 v25, v28, v25
	v_mul_f32_e32 v28, 0xbfb8aa3b, v30
	v_exp_f32_e32 v28, v28
	s_nop 0
	v_add_f32_e32 v28, 1.0, v28
	v_rcp_f32_e32 v28, v28
	s_nop 0
	v_mul_f32_e32 v28, v30, v28
	v_mul_f32_e32 v26, v28, v26
	v_mul_f32_e32 v28, 0xbfb8aa3b, v31
	v_exp_f32_e32 v28, v28
	s_nop 0
	v_add_f32_e32 v28, 1.0, v28
	v_rcp_f32_e32 v28, v28
	s_nop 0
	v_mul_f32_e32 v28, v31, v28
	v_mul_f32_e32 v27, v28, v27
	v_mul_f32_e32 v28, 0xbfb8aa3b, v20
	v_exp_f32_e32 v28, v28
	s_nop 0
	v_add_f32_e32 v28, 1.0, v28
	v_rcp_f32_e32 v28, v28
	s_nop 0
	v_mul_f32_e32 v20, v20, v28
	v_mul_f32_e32 v28, v20, v16
	v_mul_f32_e32 v16, 0xbfb8aa3b, v21
	v_exp_f32_e32 v16, v16
	s_nop 0
	v_add_f32_e32 v16, 1.0, v16
	v_rcp_f32_e32 v16, v16
	s_nop 0
	v_mul_f32_e32 v16, v21, v16
	v_mul_f32_e32 v29, v16, v17
	v_mul_f32_e32 v16, 0xbfb8aa3b, v22
	v_exp_f32_e32 v16, v16
	v_lshl_add_u64 v[20:21], v[32:33], 0, v[112:113]
	v_add_f32_e32 v16, 1.0, v16
	v_rcp_f32_e32 v16, v16
	s_nop 0
	v_mul_f32_e32 v16, v22, v16
	v_mul_f32_e32 v22, v16, v18
	v_mul_f32_e32 v16, 0xbfb8aa3b, v23
	v_exp_f32_e32 v16, v16
	s_nop 0
	v_add_f32_e32 v16, 1.0, v16
	v_rcp_f32_e32 v16, v16
	s_nop 0
	v_mul_f32_e32 v16, v23, v16
	v_mul_f32_e32 v19, v16, v19
	v_cvt_pk_bf16_f32 v16, v24, v25
	v_cvt_pk_bf16_f32 v17, v26, v27
	v_cvt_pk_bf16_f32 v18, v28, v29
	v_cvt_pk_bf16_f32 v19, v22, v19
	global_store_dwordx4 v[20:21], v[16:19], off
	s_nop 1
	v_mul_f32_e32 v18, 0xbfb8aa3b, v12
	v_exp_f32_e32 v18, v18
	v_add_u32_e32 v16, 0xb0, v144
	v_mad_i64_i32 v[16:17], s[14:15], v16, s5, v[138:139]
	v_add_f32_e32 v18, 1.0, v18
	v_rcp_f32_e32 v18, v18
	s_mov_b64 s[14:15], s[8:9]
	v_mul_f32_e32 v12, v12, v18
	v_mul_f32_e32 v8, v12, v8
	v_mul_f32_e32 v12, 0xbfb8aa3b, v13
	v_exp_f32_e32 v12, v12
	s_nop 0
	v_add_f32_e32 v12, 1.0, v12
	v_rcp_f32_e32 v12, v12
	s_nop 0
	v_mul_f32_e32 v12, v13, v12
	v_mul_f32_e32 v9, v12, v9
	v_mul_f32_e32 v12, 0xbfb8aa3b, v14
	v_exp_f32_e32 v12, v12
	s_nop 0
	v_add_f32_e32 v12, 1.0, v12
	v_rcp_f32_e32 v12, v12
	s_nop 0
	v_mul_f32_e32 v12, v14, v12
	v_mul_f32_e32 v10, v12, v10
	v_mul_f32_e32 v12, 0xbfb8aa3b, v15
	v_exp_f32_e32 v12, v12
	s_nop 0
	v_add_f32_e32 v12, 1.0, v12
	v_rcp_f32_e32 v12, v12
	s_nop 0
	v_mul_f32_e32 v12, v15, v12
	v_mul_f32_e32 v11, v12, v11
	v_mul_f32_e32 v12, 0xbfb8aa3b, v4
	v_exp_f32_e32 v12, v12
	s_nop 0
	v_add_f32_e32 v12, 1.0, v12
	v_rcp_f32_e32 v12, v12
	s_nop 0
	v_mul_f32_e32 v4, v4, v12
	v_mul_f32_e32 v12, v4, v0
	v_mul_f32_e32 v0, 0xbfb8aa3b, v5
	v_exp_f32_e32 v0, v0
	s_nop 0
	v_add_f32_e32 v0, 1.0, v0
	v_rcp_f32_e32 v0, v0
	s_nop 0
	v_mul_f32_e32 v0, v5, v0
	v_mul_f32_e32 v13, v0, v1
	v_mul_f32_e32 v0, 0xbfb8aa3b, v6
	v_exp_f32_e32 v0, v0
	v_lshl_add_u64 v[4:5], v[16:17], 0, v[112:113]
	v_add_f32_e32 v0, 1.0, v0
	v_rcp_f32_e32 v0, v0
	s_nop 0
	v_mul_f32_e32 v0, v6, v0
	v_mul_f32_e32 v6, v0, v2
	v_mul_f32_e32 v0, 0xbfb8aa3b, v7
	v_exp_f32_e32 v0, v0
	s_nop 0
	v_add_f32_e32 v0, 1.0, v0
	v_rcp_f32_e32 v0, v0
	s_nop 0
	v_mul_f32_e32 v0, v7, v0
	v_mul_f32_e32 v3, v0, v3
	v_cvt_pk_bf16_f32 v0, v8, v9
	v_cvt_pk_bf16_f32 v1, v10, v11
	v_cvt_pk_bf16_f32 v2, v12, v13
	v_cvt_pk_bf16_f32 v3, v6, v3
	global_store_dwordx4 v[4:5], v[0:3], off
	s_cbranch_vccz .LBB0_214
	s_waitcnt vmcnt(0)
	v_readlane_b32 s34, v254, 18
	s_cmpk_gt_u32 s21, 0xff
	v_readlane_b32 s35, v254, 19
	v_readlane_b32 s31, v254, 20
	s_cbranch_scc1 .LBB0_221
	s_barrier

.LBB0_246:
	s_add_i32 s44, s12, 2
	s_add_u32 s14, s10, 0x80
	s_addc_u32 s13, s11, 0
	s_add_i32 s45, 0, 0x10000
	v_add_u32_e32 v132, s45, v191
	ds_read_b128 v[120:123], v132
	ds_read_b128 v[124:127], v132 offset:1024
	ds_read_b128 v[128:131], v132 offset:2048
	ds_read_b128 v[132:135], v132 offset:3072
	s_cmp_eq_u32 s36, s12
	s_cselect_b32 s12, s4, s14
	s_cselect_b32 s13, s5, s13
	s_cselect_b32 s15, s7, s43
	s_cselect_b32 s14, s6, s42
	v_lshl_add_u64 v[186:187], s[10:11], 0, v[174:175]
	s_add_i32 m0, s26, 0xc000
	ds_read_b128 v[144:147], v205
	ds_read_b128 v[148:151], v205 offset:1024
	ds_read_b128 v[152:155], v205 offset:2048
	ds_read_b128 v[156:159], v205 offset:3072
	ds_read_b128 v[160:163], v205 offset:4096
	ds_read_b128 v[164:167], v205 offset:5120
	ds_read_b128 v[178:181], v205 offset:6144
	ds_read_b128 v[182:185], v205 offset:7168
	global_load_lds_dwordx4 v[186:187], off
	v_lshl_add_u64 v[186:187], s[10:11], 0, v[176:177]
	s_add_i32 m0, s26, 0xe000
	s_nop 0
	global_load_lds_dwordx4 v[186:187], off
	s_waitcnt lgkmcnt(8)
	s_barrier
	s_waitcnt lgkmcnt(0)
	s_waitcnt lgkmcnt(0)
	v_mfma_f32_16x16x32_bf16 v[140:143], v[120:123], v[144:147], v[140:143]
	v_mfma_f32_16x16x32_bf16 v[136:139], v[128:131], v[144:147], v[136:139]
	v_mfma_f32_16x16x32_bf16 v[108:111], v[120:123], v[152:155], v[108:111]
	v_mfma_f32_16x16x32_bf16 v[104:107], v[128:131], v[152:155], v[104:107]
	v_mfma_f32_16x16x32_bf16 v[92:95], v[120:123], v[160:163], v[92:95]
	v_mfma_f32_16x16x32_bf16 v[88:91], v[128:131], v[160:163], v[88:91]
	v_mfma_f32_16x16x32_bf16 v[76:79], v[120:123], v[178:181], v[76:79]
	v_mfma_f32_16x16x32_bf16 v[72:75], v[128:131], v[178:181], v[72:75]
	v_mfma_f32_16x16x32_bf16 v[140:143], v[124:127], v[148:151], v[140:143]
	v_mfma_f32_16x16x32_bf16 v[136:139], v[132:135], v[148:151], v[136:139]
	v_mfma_f32_16x16x32_bf16 v[108:111], v[124:127], v[156:159], v[108:111]
	v_mfma_f32_16x16x32_bf16 v[104:107], v[132:135], v[156:159], v[104:107]
	v_mfma_f32_16x16x32_bf16 v[92:95], v[124:127], v[164:167], v[92:95]
	v_mfma_f32_16x16x32_bf16 v[88:91], v[132:135], v[164:167], v[88:91]
	v_mfma_f32_16x16x32_bf16 v[76:79], v[124:127], v[182:185], v[76:79]
	v_mfma_f32_16x16x32_bf16 v[72:75], v[132:135], v[182:185], v[72:75]
	s_barrier
	s_add_i32 s46, 0, 0x14000
	v_add_u32_e32 v210, s46, v191
	s_add_i32 s45, s45, s25
	ds_read_b128 v[186:189], v210
	ds_read_b128 v[196:199], v210 offset:1024
	ds_read_b128 v[206:209], v210 offset:2048
	ds_read_b128 v[214:217], v210 offset:3072
	v_lshl_add_u64 v[210:211], s[14:15], 0, v[192:193]
	s_mov_b32 m0, s45
	v_lshl_add_u64 v[218:219], s[14:15], 0, v[172:173]
	global_load_lds_dwordx4 v[210:211], off
	s_add_i32 m0, s45, 0x2000
	s_nop 0
	global_load_lds_dwordx4 v[218:219], off
	s_barrier
	s_waitcnt lgkmcnt(0)
	s_waitcnt lgkmcnt(0)
	v_mfma_f32_16x16x32_bf16 v[116:119], v[186:189], v[144:147], v[116:119]
	v_mfma_f32_16x16x32_bf16 v[112:115], v[206:209], v[144:147], v[112:115]
	v_mfma_f32_16x16x32_bf16 v[100:103], v[186:189], v[152:155], v[100:103]
	v_mfma_f32_16x16x32_bf16 v[96:99], v[206:209], v[152:155], v[96:99]
	v_mfma_f32_16x16x32_bf16 v[84:87], v[186:189], v[160:163], v[84:87]
	v_mfma_f32_16x16x32_bf16 v[80:83], v[206:209], v[160:163], v[80:83]
	v_mfma_f32_16x16x32_bf16 v[68:71], v[186:189], v[178:181], v[68:71]
	v_mfma_f32_16x16x32_bf16 v[64:67], v[206:209], v[178:181], v[64:67]
	v_mfma_f32_16x16x32_bf16 v[116:119], v[196:199], v[148:151], v[116:119]
	v_mfma_f32_16x16x32_bf16 v[112:115], v[214:217], v[148:151], v[112:115]
	v_mfma_f32_16x16x32_bf16 v[100:103], v[196:199], v[156:159], v[100:103]
	v_mfma_f32_16x16x32_bf16 v[96:99], v[214:217], v[156:159], v[96:99]
	v_mfma_f32_16x16x32_bf16 v[84:87], v[196:199], v[164:167], v[84:87]
	v_mfma_f32_16x16x32_bf16 v[80:83], v[214:217], v[164:167], v[80:83]
	v_mfma_f32_16x16x32_bf16 v[68:71], v[196:199], v[182:185], v[68:71]
	v_mfma_f32_16x16x32_bf16 v[64:67], v[214:217], v[182:185], v[64:67]
	s_mov_b32 m0, s26
	v_lshl_add_u64 v[220:221], s[12:13], 0, v[168:169]
	s_barrier
	ds_read_b128 v[144:147], v205 offset:16384
	ds_read_b128 v[148:151], v205 offset:17408
	ds_read_b128 v[152:155], v205 offset:18432
	ds_read_b128 v[156:159], v205 offset:19456
	ds_read_b128 v[160:163], v205 offset:20480
	ds_read_b128 v[164:167], v205 offset:21504
	ds_read_b128 v[178:181], v205 offset:22528
	ds_read_b128 v[182:185], v205 offset:23552
	global_load_lds_dwordx4 v[220:221], off
	v_lshl_add_u64 v[222:223], s[12:13], 0, v[170:171]
	s_mov_b32 m0, s27
	s_nop 0
	global_load_lds_dwordx4 v[222:223], off
	s_barrier
	s_waitcnt lgkmcnt(0)
	s_waitcnt lgkmcnt(0)
	v_mfma_f32_16x16x32_bf16 v[60:63], v[120:123], v[144:147], v[60:63]
	v_mfma_f32_16x16x32_bf16 v[56:59], v[128:131], v[144:147], v[56:59]
	v_mfma_f32_16x16x32_bf16 v[44:47], v[120:123], v[152:155], v[44:47]
	v_mfma_f32_16x16x32_bf16 v[40:43], v[128:131], v[152:155], v[40:43]
	v_mfma_f32_16x16x32_bf16 v[28:31], v[120:123], v[160:163], v[28:31]
	v_mfma_f32_16x16x32_bf16 v[24:27], v[128:131], v[160:163], v[24:27]
	v_mfma_f32_16x16x32_bf16 v[12:15], v[120:123], v[178:181], v[12:15]
	v_mfma_f32_16x16x32_bf16 v[8:11], v[128:131], v[178:181], v[8:11]
	v_mfma_f32_16x16x32_bf16 v[60:63], v[124:127], v[148:151], v[60:63]
	v_mfma_f32_16x16x32_bf16 v[56:59], v[132:135], v[148:151], v[56:59]
	v_mfma_f32_16x16x32_bf16 v[44:47], v[124:127], v[156:159], v[44:47]
	v_mfma_f32_16x16x32_bf16 v[40:43], v[132:135], v[156:159], v[40:43]
	v_mfma_f32_16x16x32_bf16 v[28:31], v[124:127], v[164:167], v[28:31]
	v_mfma_f32_16x16x32_bf16 v[24:27], v[132:135], v[164:167], v[24:27]
	v_mfma_f32_16x16x32_bf16 v[12:15], v[124:127], v[182:185], v[12:15]
	v_mfma_f32_16x16x32_bf16 v[8:11], v[132:135], v[182:185], v[8:11]
	s_barrier
	s_add_u32 s14, s14, s52
	s_addc_u32 s15, s15, 0
	s_add_i32 s45, s46, s25
	v_lshl_add_u64 v[224:225], s[14:15], 0, v[192:193]
	s_mov_b32 m0, s45
	v_lshl_add_u64 v[226:227], s[14:15], 0, v[172:173]
	global_load_lds_dwordx4 v[224:225], off
	s_add_i32 m0, s45, 0x2000
	s_nop 0
	global_load_lds_dwordx4 v[226:227], off
	s_waitcnt vmcnt(6)
	s_barrier
	v_mfma_f32_16x16x32_bf16 v[52:55], v[186:189], v[144:147], v[52:55]
	v_mfma_f32_16x16x32_bf16 v[48:51], v[206:209], v[144:147], v[48:51]
	v_mfma_f32_16x16x32_bf16 v[36:39], v[186:189], v[152:155], v[36:39]
	v_mfma_f32_16x16x32_bf16 v[32:35], v[206:209], v[152:155], v[32:35]
	v_mfma_f32_16x16x32_bf16 v[20:23], v[186:189], v[160:163], v[20:23]
	v_mfma_f32_16x16x32_bf16 v[16:19], v[206:209], v[160:163], v[16:19]
	v_mfma_f32_16x16x32_bf16 v[4:7], v[186:189], v[178:181], v[4:7]
	v_mfma_f32_16x16x32_bf16 v[0:3], v[206:209], v[178:181], v[0:3]
	v_mfma_f32_16x16x32_bf16 v[52:55], v[196:199], v[148:151], v[52:55]
	v_mfma_f32_16x16x32_bf16 v[48:51], v[214:217], v[148:151], v[48:51]
	v_mfma_f32_16x16x32_bf16 v[36:39], v[196:199], v[156:159], v[36:39]
	v_mfma_f32_16x16x32_bf16 v[32:35], v[214:217], v[156:159], v[32:35]
	v_mfma_f32_16x16x32_bf16 v[20:23], v[196:199], v[164:167], v[20:23]
	v_mfma_f32_16x16x32_bf16 v[16:19], v[214:217], v[164:167], v[16:19]
	v_mfma_f32_16x16x32_bf16 v[4:7], v[196:199], v[182:185], v[4:7]
	v_mfma_f32_16x16x32_bf16 v[0:3], v[214:217], v[182:185], v[0:3]
	s_add_i32 s14, 0, 0x18000
	v_add_u32_e32 v132, s14, v191
	s_barrier
	ds_read_b128 v[120:123], v132
	ds_read_b128 v[124:127], v132 offset:1024
	ds_read_b128 v[128:131], v132 offset:2048
	ds_read_b128 v[132:135], v132 offset:3072
	s_add_u32 s12, s12, s52
	s_addc_u32 s13, s13, 0
	s_mov_b32 m0, s28
	v_lshl_add_u64 v[186:187], s[12:13], 0, v[168:169]
	ds_read_b128 v[144:147], v205 offset:32768
	ds_read_b128 v[148:151], v205 offset:33792
	ds_read_b128 v[152:155], v205 offset:34816
	ds_read_b128 v[156:159], v205 offset:35840
	ds_read_b128 v[160:163], v205 offset:36864
	ds_read_b128 v[164:167], v205 offset:37888
	ds_read_b128 v[178:181], v205 offset:38912
	ds_read_b128 v[182:185], v205 offset:39936
	global_load_lds_dwordx4 v[186:187], off
	v_lshl_add_u64 v[186:187], s[12:13], 0, v[170:171]
	s_mov_b32 m0, s29
	s_nop 0
	global_load_lds_dwordx4 v[186:187], off
	s_waitcnt lgkmcnt(8)
	s_barrier
	s_waitcnt lgkmcnt(0)
	s_waitcnt lgkmcnt(0)
	v_mfma_f32_16x16x32_bf16 v[140:143], v[120:123], v[144:147], v[140:143]
	v_mfma_f32_16x16x32_bf16 v[136:139], v[128:131], v[144:147], v[136:139]
	v_mfma_f32_16x16x32_bf16 v[108:111], v[120:123], v[152:155], v[108:111]
	v_mfma_f32_16x16x32_bf16 v[104:107], v[128:131], v[152:155], v[104:107]
	v_mfma_f32_16x16x32_bf16 v[92:95], v[120:123], v[160:163], v[92:95]
	v_mfma_f32_16x16x32_bf16 v[88:91], v[128:131], v[160:163], v[88:91]
	v_mfma_f32_16x16x32_bf16 v[76:79], v[120:123], v[178:181], v[76:79]
	v_mfma_f32_16x16x32_bf16 v[72:75], v[128:131], v[178:181], v[72:75]
	v_mfma_f32_16x16x32_bf16 v[140:143], v[124:127], v[148:151], v[140:143]
	v_mfma_f32_16x16x32_bf16 v[136:139], v[132:135], v[148:151], v[136:139]
	v_mfma_f32_16x16x32_bf16 v[108:111], v[124:127], v[156:159], v[108:111]
	v_mfma_f32_16x16x32_bf16 v[104:107], v[132:135], v[156:159], v[104:107]
	v_mfma_f32_16x16x32_bf16 v[92:95], v[124:127], v[164:167], v[92:95]
	v_mfma_f32_16x16x32_bf16 v[88:91], v[132:135], v[164:167], v[88:91]
	v_mfma_f32_16x16x32_bf16 v[76:79], v[124:127], v[182:185], v[76:79]
	v_mfma_f32_16x16x32_bf16 v[72:75], v[132:135], v[182:185], v[72:75]
	s_barrier
	s_add_i32 s12, 0, 0x1c000
	s_add_i32 s13, s14, s25
	v_add_u32_e32 v212, s12, v191
	v_lshl_add_u64 v[210:211], v[210:211], 0, s[48:49]
	s_mov_b32 m0, s13
	ds_read_b128 v[186:189], v212
	ds_read_b128 v[196:199], v212 offset:1024
	ds_read_b128 v[206:209], v212 offset:2048
	ds_read_b128 v[214:217], v212 offset:3072
	global_load_lds_dwordx4 v[210:211], off
	v_lshl_add_u64 v[210:211], v[218:219], 0, s[48:49]
	s_add_i32 m0, s13, 0x2000
	s_nop 0
	global_load_lds_dwordx4 v[210:211], off
	s_barrier
	s_waitcnt lgkmcnt(0)
	s_waitcnt lgkmcnt(0)
	v_mfma_f32_16x16x32_bf16 v[116:119], v[186:189], v[144:147], v[116:119]
	v_mfma_f32_16x16x32_bf16 v[112:115], v[206:209], v[144:147], v[112:115]
	v_mfma_f32_16x16x32_bf16 v[100:103], v[186:189], v[152:155], v[100:103]
	v_mfma_f32_16x16x32_bf16 v[96:99], v[206:209], v[152:155], v[96:99]
	v_mfma_f32_16x16x32_bf16 v[84:87], v[186:189], v[160:163], v[84:87]
	v_mfma_f32_16x16x32_bf16 v[80:83], v[206:209], v[160:163], v[80:83]
	v_mfma_f32_16x16x32_bf16 v[68:71], v[186:189], v[178:181], v[68:71]
	v_mfma_f32_16x16x32_bf16 v[64:67], v[206:209], v[178:181], v[64:67]
	v_mfma_f32_16x16x32_bf16 v[116:119], v[196:199], v[148:151], v[116:119]
	v_mfma_f32_16x16x32_bf16 v[112:115], v[214:217], v[148:151], v[112:115]
	v_mfma_f32_16x16x32_bf16 v[100:103], v[196:199], v[156:159], v[100:103]
	v_mfma_f32_16x16x32_bf16 v[96:99], v[214:217], v[156:159], v[96:99]
	v_mfma_f32_16x16x32_bf16 v[84:87], v[196:199], v[164:167], v[84:87]
	v_mfma_f32_16x16x32_bf16 v[80:83], v[214:217], v[164:167], v[80:83]
	v_mfma_f32_16x16x32_bf16 v[68:71], v[196:199], v[182:185], v[68:71]
	v_mfma_f32_16x16x32_bf16 v[64:67], v[214:217], v[182:185], v[64:67]
	s_mov_b32 m0, s34
	v_lshl_add_u64 v[210:211], v[220:221], 0, s[48:49]
	s_barrier
	ds_read_b128 v[144:147], v205 offset:49152
	ds_read_b128 v[148:151], v205 offset:50176
	ds_read_b128 v[152:155], v205 offset:51200
	ds_read_b128 v[156:159], v205 offset:52224
	ds_read_b128 v[160:163], v205 offset:53248
	ds_read_b128 v[164:167], v205 offset:54272
	ds_read_b128 v[178:181], v205 offset:55296
	ds_read_b128 v[182:185], v205 offset:56320
	global_load_lds_dwordx4 v[210:211], off
	v_lshl_add_u64 v[210:211], v[222:223], 0, s[48:49]
	s_mov_b32 m0, s35
	s_nop 0
	global_load_lds_dwordx4 v[210:211], off
	s_barrier
	s_waitcnt lgkmcnt(0)
	s_waitcnt lgkmcnt(0)
	v_mfma_f32_16x16x32_bf16 v[60:63], v[120:123], v[144:147], v[60:63]
	v_mfma_f32_16x16x32_bf16 v[56:59], v[128:131], v[144:147], v[56:59]
	v_mfma_f32_16x16x32_bf16 v[44:47], v[120:123], v[152:155], v[44:47]
	v_mfma_f32_16x16x32_bf16 v[40:43], v[128:131], v[152:155], v[40:43]
	v_mfma_f32_16x16x32_bf16 v[28:31], v[120:123], v[160:163], v[28:31]
	v_mfma_f32_16x16x32_bf16 v[24:27], v[128:131], v[160:163], v[24:27]
	v_mfma_f32_16x16x32_bf16 v[12:15], v[120:123], v[178:181], v[12:15]
	v_mfma_f32_16x16x32_bf16 v[8:11], v[128:131], v[178:181], v[8:11]
	v_mfma_f32_16x16x32_bf16 v[60:63], v[124:127], v[148:151], v[60:63]
	v_mfma_f32_16x16x32_bf16 v[56:59], v[132:135], v[148:151], v[56:59]
	v_mfma_f32_16x16x32_bf16 v[44:47], v[124:127], v[156:159], v[44:47]
	v_mfma_f32_16x16x32_bf16 v[40:43], v[132:135], v[156:159], v[40:43]
	v_mfma_f32_16x16x32_bf16 v[28:31], v[124:127], v[164:167], v[28:31]
	v_mfma_f32_16x16x32_bf16 v[24:27], v[132:135], v[164:167], v[24:27]
	v_mfma_f32_16x16x32_bf16 v[12:15], v[124:127], v[182:185], v[12:15]
	v_mfma_f32_16x16x32_bf16 v[8:11], v[132:135], v[182:185], v[8:11]
	s_barrier
	s_add_i32 s12, s12, s25
	v_lshl_add_u64 v[120:121], v[224:225], 0, s[48:49]
	s_mov_b32 m0, s12
	s_nop 0
	global_load_lds_dwordx4 v[120:121], off
	v_lshl_add_u64 v[120:121], v[226:227], 0, s[48:49]
	s_add_i32 m0, s12, 0x2000
	s_nop 0
	global_load_lds_dwordx4 v[120:121], off
	s_waitcnt vmcnt(6)
	s_barrier
	v_mfma_f32_16x16x32_bf16 v[52:55], v[186:189], v[144:147], v[52:55]
	v_mfma_f32_16x16x32_bf16 v[48:51], v[206:209], v[144:147], v[48:51]
	v_mfma_f32_16x16x32_bf16 v[36:39], v[186:189], v[152:155], v[36:39]
	v_mfma_f32_16x16x32_bf16 v[32:35], v[206:209], v[152:155], v[32:35]
	v_mfma_f32_16x16x32_bf16 v[20:23], v[186:189], v[160:163], v[20:23]
	v_mfma_f32_16x16x32_bf16 v[16:19], v[206:209], v[160:163], v[16:19]
	v_mfma_f32_16x16x32_bf16 v[4:7], v[186:189], v[178:181], v[4:7]
	v_mfma_f32_16x16x32_bf16 v[0:3], v[206:209], v[178:181], v[0:3]
	v_mfma_f32_16x16x32_bf16 v[52:55], v[196:199], v[148:151], v[52:55]
	v_mfma_f32_16x16x32_bf16 v[48:51], v[214:217], v[148:151], v[48:51]
	v_mfma_f32_16x16x32_bf16 v[36:39], v[196:199], v[156:159], v[36:39]
	v_mfma_f32_16x16x32_bf16 v[32:35], v[214:217], v[156:159], v[32:35]
	v_mfma_f32_16x16x32_bf16 v[20:23], v[196:199], v[164:167], v[20:23]
	v_mfma_f32_16x16x32_bf16 v[16:19], v[214:217], v[164:167], v[16:19]
	v_mfma_f32_16x16x32_bf16 v[4:7], v[196:199], v[182:185], v[4:7]
	v_mfma_f32_16x16x32_bf16 v[0:3], v[214:217], v[182:185], v[0:3]
	s_add_u32 s10, s10, 0x100
	s_addc_u32 s11, s11, 0
	s_add_u32 s42, s42, 0x100
	s_addc_u32 s43, s43, 0
	s_cmp_ge_u32 s44, s33
	s_mov_b32 s12, s44
	s_barrier
	s_cbranch_scc0 .LBB0_246
	v_lshl_or_b32 v144, s41, 8, v204
	s_ashr_i32 s10, s40, 4
	s_mul_hi_i32 s11, s10, 0xc000
	s_mul_i32 s10, s10, 0xc000
	v_ashrrev_i32_e32 v145, 31, v144
	v_lshl_add_u32 v146, s40, 8, v190
	s_add_u32 s10, s30, s10
	v_lshlrev_b64 v[178:179], 1, v[144:145]
	v_ashrrev_i32_e32 v147, 31, v146
	s_addc_u32 s11, s31, s11
	v_lshl_add_u64 v[180:181], s[2:3], 0, v[178:179]
	v_lshlrev_b64 v[182:183], 12, v[146:147]
	v_lshl_add_u64 v[124:125], v[144:145], 2, s[10:11]
	v_lshl_add_u64 v[144:145], v[180:181], 0, v[182:183]
	global_load_dwordx4 v[128:131], v[124:125], off offset:16
	global_load_dwordx4 v[132:135], v[124:125], off
	global_load_dwordx4 v[120:123], v[124:125], off offset:528
	s_nop 0
	global_load_dwordx4 v[124:127], v[124:125], off offset:512
	s_nop 0
	global_load_dwordx4 v[196:199], v[144:145], off
	global_load_dwordx4 v[206:209], v[144:145], off offset:256
	v_or_b32_e32 v144, 16, v146
	v_ashrrev_i32_e32 v145, 31, v144
	v_lshlrev_b64 v[188:189], 12, v[144:145]
	v_lshl_add_u64 v[144:145], v[180:181], 0, v[188:189]
	global_load_dwordx4 v[164:167], v[144:145], off
	global_load_dwordx4 v[160:163], v[144:145], off offset:256
	v_or_b32_e32 v144, 32, v146
	v_ashrrev_i32_e32 v145, 31, v144
	v_lshlrev_b64 v[186:187], 12, v[144:145]
	v_lshl_add_u64 v[144:145], v[180:181], 0, v[186:187]
	global_load_dwordx4 v[156:159], v[144:145], off
	global_load_dwordx4 v[152:155], v[144:145], off offset:256
	v_or_b32_e32 v144, 48, v146
	v_ashrrev_i32_e32 v145, 31, v144
	v_lshlrev_b64 v[184:185], 12, v[144:145]
	v_lshl_add_u64 v[144:145], v[180:181], 0, v[184:185]
	global_load_dwordx4 v[148:151], v[144:145], off
	s_nop 0
	global_load_dwordx4 v[144:147], v[144:145], off offset:256
	s_mov_b64 s[10:11], 0x80000
	s_and_b64 vcc, exec, s[0:1]
	s_mov_b32 s41, s38
	s_mov_b32 s40, s39
	s_mov_b64 s[12:13], s[6:7]
	v_readlane_b32 s14, v254, 21
	s_movk_i32 s15, 0x2000
	s_waitcnt vmcnt(0)
	v_lshlrev_b32_e32 v210, 16, v196
	v_and_b32_e32 v211, 0xffff0000, v196
	v_lshlrev_b32_e32 v196, 16, v197
	v_and_b32_e32 v197, 0xffff0000, v197
	v_lshlrev_b32_e32 v214, 16, v198
	v_and_b32_e32 v215, 0xffff0000, v198
	v_lshlrev_b32_e32 v198, 16, v199
	v_and_b32_e32 v199, 0xffff0000, v199
	v_pk_fma_f32 v[140:141], v[140:141], v[132:133], v[210:211]
	v_pk_fma_f32 v[142:143], v[142:143], v[134:135], v[196:197]
	v_pk_fma_f32 v[196:197], v[138:139], v[130:131], v[198:199]
	v_pk_fma_f32 v[138:139], v[136:137], v[128:129], v[214:215]
	v_cvt_pk_bf16_f32 v136, v140, v141
	v_lshl_add_u64 v[140:141], s[8:9], 0, v[182:183]
	v_cvt_pk_bf16_f32 v137, v142, v143
	v_cvt_pk_bf16_f32 v138, v138, v139
	v_cvt_pk_bf16_f32 v139, v196, v197
	v_lshl_add_u64 v[140:141], v[140:141], 0, v[178:179]
	global_store_dwordx4 v[140:141], v[136:139], off
	v_lshlrev_b32_e32 v142, 16, v208
	v_and_b32_e32 v143, 0xffff0000, v208
	v_lshlrev_b32_e32 v136, 16, v206
	v_and_b32_e32 v137, 0xffff0000, v206
	v_lshlrev_b32_e32 v138, 16, v207
	v_and_b32_e32 v139, 0xffff0000, v207
	v_lshlrev_b32_e32 v196, 16, v209
	v_and_b32_e32 v197, 0xffff0000, v209
	v_pk_fma_f32 v[118:119], v[118:119], v[126:127], v[138:139]
	v_pk_fma_f32 v[116:117], v[116:117], v[124:125], v[136:137]
	v_pk_fma_f32 v[136:137], v[114:115], v[122:123], v[196:197]
	v_pk_fma_f32 v[114:115], v[112:113], v[120:121], v[142:143]
	v_cvt_pk_bf16_f32 v112, v116, v117
	v_cvt_pk_bf16_f32 v113, v118, v119
	v_lshlrev_b32_e32 v116, 16, v166
	v_cvt_pk_bf16_f32 v114, v114, v115
	v_cvt_pk_bf16_f32 v115, v136, v137
	global_store_dwordx4 v[140:141], v[112:115], off offset:256
	v_and_b32_e32 v117, 0xffff0000, v166
	v_lshlrev_b32_e32 v118, 16, v167
	v_lshlrev_b32_e32 v112, 16, v164
	v_and_b32_e32 v113, 0xffff0000, v164
	v_and_b32_e32 v119, 0xffff0000, v167
	v_pk_fma_f32 v[108:109], v[108:109], v[132:133], v[112:113]
	v_lshlrev_b32_e32 v114, 16, v165
	v_and_b32_e32 v115, 0xffff0000, v165
	v_pk_fma_f32 v[112:113], v[106:107], v[130:131], v[118:119]
	v_pk_fma_f32 v[106:107], v[104:105], v[128:129], v[116:117]
	v_cvt_pk_bf16_f32 v104, v108, v109
	v_lshl_add_u64 v[108:109], s[8:9], 0, v[188:189]
	v_pk_fma_f32 v[110:111], v[110:111], v[134:135], v[114:115]
	v_lshl_add_u64 v[108:109], v[108:109], 0, v[178:179]
	v_cvt_pk_bf16_f32 v105, v110, v111
	v_cvt_pk_bf16_f32 v106, v106, v107
	v_cvt_pk_bf16_f32 v107, v112, v113
	global_store_dwordx4 v[108:109], v[104:107], off
	v_lshlrev_b32_e32 v110, 16, v162
	v_and_b32_e32 v111, 0xffff0000, v162
	v_lshlrev_b32_e32 v104, 16, v160
	v_and_b32_e32 v105, 0xffff0000, v160
	v_lshlrev_b32_e32 v106, 16, v161
	v_and_b32_e32 v107, 0xffff0000, v161
	v_lshlrev_b32_e32 v112, 16, v163
	v_and_b32_e32 v113, 0xffff0000, v163
	v_pk_fma_f32 v[102:103], v[102:103], v[126:127], v[106:107]
	v_pk_fma_f32 v[100:101], v[100:101], v[124:125], v[104:105]
	v_pk_fma_f32 v[104:105], v[98:99], v[122:123], v[112:113]
	v_pk_fma_f32 v[98:99], v[96:97], v[120:121], v[110:111]
	v_cvt_pk_bf16_f32 v96, v100, v101
	v_cvt_pk_bf16_f32 v97, v102, v103
	v_lshlrev_b32_e32 v100, 16, v158
	v_cvt_pk_bf16_f32 v98, v98, v99
	v_cvt_pk_bf16_f32 v99, v104, v105
	global_store_dwordx4 v[108:109], v[96:99], off offset:256
	v_and_b32_e32 v101, 0xffff0000, v158
	v_lshlrev_b32_e32 v102, 16, v159
	v_lshlrev_b32_e32 v96, 16, v156
	v_and_b32_e32 v97, 0xffff0000, v156
	v_and_b32_e32 v103, 0xffff0000, v159
	v_pk_fma_f32 v[92:93], v[92:93], v[132:133], v[96:97]
	v_lshlrev_b32_e32 v98, 16, v157
	v_and_b32_e32 v99, 0xffff0000, v157
	v_pk_fma_f32 v[96:97], v[90:91], v[130:131], v[102:103]
	v_pk_fma_f32 v[90:91], v[88:89], v[128:129], v[100:101]
	v_cvt_pk_bf16_f32 v88, v92, v93
	v_lshl_add_u64 v[92:93], s[8:9], 0, v[186:187]
	v_pk_fma_f32 v[94:95], v[94:95], v[134:135], v[98:99]
	v_lshl_add_u64 v[92:93], v[92:93], 0, v[178:179]
	v_cvt_pk_bf16_f32 v89, v94, v95
	v_cvt_pk_bf16_f32 v90, v90, v91
	v_cvt_pk_bf16_f32 v91, v96, v97
	global_store_dwordx4 v[92:93], v[88:91], off
	v_lshlrev_b32_e32 v94, 16, v154
	v_and_b32_e32 v95, 0xffff0000, v154
	v_lshlrev_b32_e32 v88, 16, v152
	v_and_b32_e32 v89, 0xffff0000, v152
	v_lshlrev_b32_e32 v90, 16, v153
	v_and_b32_e32 v91, 0xffff0000, v153
	v_lshlrev_b32_e32 v96, 16, v155
	v_and_b32_e32 v97, 0xffff0000, v155
	v_pk_fma_f32 v[86:87], v[86:87], v[126:127], v[90:91]
	v_pk_fma_f32 v[84:85], v[84:85], v[124:125], v[88:89]
	v_pk_fma_f32 v[88:89], v[82:83], v[122:123], v[96:97]
	v_pk_fma_f32 v[82:83], v[80:81], v[120:121], v[94:95]
	v_cvt_pk_bf16_f32 v80, v84, v85
	v_cvt_pk_bf16_f32 v81, v86, v87
	v_lshlrev_b32_e32 v84, 16, v150
	v_cvt_pk_bf16_f32 v82, v82, v83
	v_cvt_pk_bf16_f32 v83, v88, v89
	global_store_dwordx4 v[92:93], v[80:83], off offset:256
	v_and_b32_e32 v85, 0xffff0000, v150
	v_lshlrev_b32_e32 v86, 16, v151
	v_lshlrev_b32_e32 v80, 16, v148
	v_and_b32_e32 v81, 0xffff0000, v148
	v_and_b32_e32 v87, 0xffff0000, v151
	v_pk_fma_f32 v[76:77], v[76:77], v[132:133], v[80:81]
	v_lshlrev_b32_e32 v82, 16, v149
	v_and_b32_e32 v83, 0xffff0000, v149
	v_pk_fma_f32 v[80:81], v[74:75], v[130:131], v[86:87]
	v_pk_fma_f32 v[74:75], v[72:73], v[128:129], v[84:85]
	v_cvt_pk_bf16_f32 v72, v76, v77
	v_lshl_add_u64 v[76:77], s[8:9], 0, v[184:185]
	v_pk_fma_f32 v[78:79], v[78:79], v[134:135], v[82:83]
	v_lshl_add_u64 v[76:77], v[76:77], 0, v[178:179]
	v_cvt_pk_bf16_f32 v73, v78, v79
	v_cvt_pk_bf16_f32 v74, v74, v75
	v_cvt_pk_bf16_f32 v75, v80, v81
	global_store_dwordx4 v[76:77], v[72:75], off
	v_lshlrev_b32_e32 v78, 16, v146
	v_and_b32_e32 v79, 0xffff0000, v146
	v_lshlrev_b32_e32 v72, 16, v144
	v_and_b32_e32 v73, 0xffff0000, v144
	v_lshlrev_b32_e32 v74, 16, v145
	v_and_b32_e32 v75, 0xffff0000, v145
	v_lshlrev_b32_e32 v80, 16, v147
	v_and_b32_e32 v81, 0xffff0000, v147
	v_pk_fma_f32 v[70:71], v[70:71], v[126:127], v[74:75]
	v_pk_fma_f32 v[68:69], v[68:69], v[124:125], v[72:73]
	v_pk_fma_f32 v[72:73], v[66:67], v[122:123], v[80:81]
	v_pk_fma_f32 v[66:67], v[64:65], v[120:121], v[78:79]
	v_cvt_pk_bf16_f32 v64, v68, v69
	v_cvt_pk_bf16_f32 v65, v70, v71
	v_lshl_add_u64 v[98:99], v[182:183], 0, s[10:11]
	v_cvt_pk_bf16_f32 v66, v66, v67
	v_cvt_pk_bf16_f32 v67, v72, v73
	global_store_dwordx4 v[76:77], v[64:67], off offset:256
	s_mov_b64 s[10:11], 0x90000
	v_lshl_add_u64 v[100:101], v[182:183], 0, s[10:11]
	v_lshl_add_u64 v[64:65], v[180:181], 0, v[98:99]
	global_load_dwordx4 v[74:77], v[64:65], off
	global_load_dwordx4 v[78:81], v[64:65], off offset:256
	v_lshl_add_u64 v[64:65], v[180:181], 0, v[100:101]
	global_load_dwordx4 v[82:85], v[64:65], off
	global_load_dwordx4 v[86:89], v[64:65], off offset:256
	s_mov_b64 s[10:11], 0xa0000
	v_lshl_add_u64 v[102:103], v[182:183], 0, s[10:11]
	v_lshl_add_u64 v[64:65], v[180:181], 0, v[102:103]
	global_load_dwordx4 v[90:93], v[64:65], off
	global_load_dwordx4 v[94:97], v[64:65], off offset:256
	s_mov_b64 s[10:11], 0xb0000
	v_lshl_add_u64 v[72:73], v[182:183], 0, s[10:11]
	v_lshl_add_u64 v[64:65], v[180:181], 0, v[72:73]
	global_load_dwordx4 v[68:71], v[64:65], off
	s_nop 0
	global_load_dwordx4 v[64:67], v[64:65], off offset:256
	s_mov_b64 s[10:11], s[4:5]
	s_waitcnt vmcnt(0)
	v_lshlrev_b32_e32 v104, 16, v74
	v_and_b32_e32 v105, 0xffff0000, v74
	v_lshlrev_b32_e32 v74, 16, v75
	v_and_b32_e32 v75, 0xffff0000, v75
	v_lshlrev_b32_e32 v106, 16, v76
	v_and_b32_e32 v107, 0xffff0000, v76
	v_lshlrev_b32_e32 v76, 16, v77
	v_and_b32_e32 v77, 0xffff0000, v77
	v_pk_fma_f32 v[60:61], v[60:61], v[132:133], v[104:105]
	v_pk_fma_f32 v[62:63], v[62:63], v[134:135], v[74:75]
	v_pk_fma_f32 v[74:75], v[58:59], v[130:131], v[76:77]
	v_pk_fma_f32 v[58:59], v[56:57], v[128:129], v[106:107]
	v_cvt_pk_bf16_f32 v56, v60, v61
	v_lshl_add_u64 v[60:61], s[8:9], 0, v[98:99]
	v_cvt_pk_bf16_f32 v57, v62, v63
	v_cvt_pk_bf16_f32 v58, v58, v59
	v_cvt_pk_bf16_f32 v59, v74, v75
	v_lshl_add_u64 v[60:61], v[60:61], 0, v[178:179]
	global_store_dwordx4 v[60:61], v[56:59], off
	v_lshlrev_b32_e32 v62, 16, v80
	v_and_b32_e32 v63, 0xffff0000, v80
	v_lshlrev_b32_e32 v56, 16, v78
	v_and_b32_e32 v57, 0xffff0000, v78
	v_lshlrev_b32_e32 v58, 16, v79
	v_and_b32_e32 v59, 0xffff0000, v79
	v_lshlrev_b32_e32 v74, 16, v81
	v_and_b32_e32 v75, 0xffff0000, v81
	v_pk_fma_f32 v[54:55], v[54:55], v[126:127], v[58:59]
	v_pk_fma_f32 v[52:53], v[52:53], v[124:125], v[56:57]
	v_pk_fma_f32 v[56:57], v[50:51], v[122:123], v[74:75]
	v_pk_fma_f32 v[50:51], v[48:49], v[120:121], v[62:63]
	v_cvt_pk_bf16_f32 v48, v52, v53
	v_cvt_pk_bf16_f32 v49, v54, v55
	v_lshlrev_b32_e32 v52, 16, v84
	v_cvt_pk_bf16_f32 v50, v50, v51
	v_cvt_pk_bf16_f32 v51, v56, v57
	global_store_dwordx4 v[60:61], v[48:51], off offset:256
	v_and_b32_e32 v53, 0xffff0000, v84
	v_lshlrev_b32_e32 v54, 16, v85
	v_lshlrev_b32_e32 v48, 16, v82
	v_and_b32_e32 v49, 0xffff0000, v82
	v_and_b32_e32 v55, 0xffff0000, v85
	v_pk_fma_f32 v[44:45], v[44:45], v[132:133], v[48:49]
	v_lshlrev_b32_e32 v50, 16, v83
	v_and_b32_e32 v51, 0xffff0000, v83
	v_pk_fma_f32 v[48:49], v[42:43], v[130:131], v[54:55]
	v_pk_fma_f32 v[42:43], v[40:41], v[128:129], v[52:53]
	v_cvt_pk_bf16_f32 v40, v44, v45
	v_lshl_add_u64 v[44:45], s[8:9], 0, v[100:101]
	v_pk_fma_f32 v[46:47], v[46:47], v[134:135], v[50:51]
	v_lshl_add_u64 v[44:45], v[44:45], 0, v[178:179]
	v_cvt_pk_bf16_f32 v41, v46, v47
	v_cvt_pk_bf16_f32 v42, v42, v43
	v_cvt_pk_bf16_f32 v43, v48, v49
	global_store_dwordx4 v[44:45], v[40:43], off
	v_lshlrev_b32_e32 v46, 16, v88
	v_and_b32_e32 v47, 0xffff0000, v88
	v_lshlrev_b32_e32 v40, 16, v86
	v_and_b32_e32 v41, 0xffff0000, v86
	v_lshlrev_b32_e32 v42, 16, v87
	v_and_b32_e32 v43, 0xffff0000, v87
	v_lshlrev_b32_e32 v48, 16, v89
	v_and_b32_e32 v49, 0xffff0000, v89
	v_pk_fma_f32 v[38:39], v[38:39], v[126:127], v[42:43]
	v_pk_fma_f32 v[36:37], v[36:37], v[124:125], v[40:41]
	v_pk_fma_f32 v[40:41], v[34:35], v[122:123], v[48:49]
	v_pk_fma_f32 v[34:35], v[32:33], v[120:121], v[46:47]
	v_cvt_pk_bf16_f32 v32, v36, v37
	v_cvt_pk_bf16_f32 v33, v38, v39
	v_lshlrev_b32_e32 v36, 16, v92
	v_cvt_pk_bf16_f32 v34, v34, v35
	v_cvt_pk_bf16_f32 v35, v40, v41
	global_store_dwordx4 v[44:45], v[32:35], off offset:256
	v_and_b32_e32 v37, 0xffff0000, v92
	v_lshlrev_b32_e32 v38, 16, v93
	v_lshlrev_b32_e32 v32, 16, v90
	v_and_b32_e32 v33, 0xffff0000, v90
	v_and_b32_e32 v39, 0xffff0000, v93
	v_pk_fma_f32 v[28:29], v[28:29], v[132:133], v[32:33]
	v_lshlrev_b32_e32 v34, 16, v91
	v_and_b32_e32 v35, 0xffff0000, v91
	v_pk_fma_f32 v[32:33], v[26:27], v[130:131], v[38:39]
	v_pk_fma_f32 v[26:27], v[24:25], v[128:129], v[36:37]
	v_cvt_pk_bf16_f32 v24, v28, v29
	v_lshl_add_u64 v[28:29], s[8:9], 0, v[102:103]
	v_pk_fma_f32 v[30:31], v[30:31], v[134:135], v[34:35]
	v_lshl_add_u64 v[28:29], v[28:29], 0, v[178:179]
	v_cvt_pk_bf16_f32 v25, v30, v31
	v_cvt_pk_bf16_f32 v26, v26, v27
	v_cvt_pk_bf16_f32 v27, v32, v33
	global_store_dwordx4 v[28:29], v[24:27], off
	v_lshlrev_b32_e32 v30, 16, v96
	v_and_b32_e32 v31, 0xffff0000, v96
	v_lshlrev_b32_e32 v24, 16, v94
	v_and_b32_e32 v25, 0xffff0000, v94
	v_lshlrev_b32_e32 v26, 16, v95
	v_and_b32_e32 v27, 0xffff0000, v95
	v_lshlrev_b32_e32 v32, 16, v97
	v_and_b32_e32 v33, 0xffff0000, v97
	v_pk_fma_f32 v[22:23], v[22:23], v[126:127], v[26:27]
	v_pk_fma_f32 v[20:21], v[20:21], v[124:125], v[24:25]
	v_pk_fma_f32 v[24:25], v[18:19], v[122:123], v[32:33]
	v_pk_fma_f32 v[18:19], v[16:17], v[120:121], v[30:31]
	v_cvt_pk_bf16_f32 v16, v20, v21
	v_cvt_pk_bf16_f32 v17, v22, v23
	v_lshlrev_b32_e32 v20, 16, v70
	v_cvt_pk_bf16_f32 v18, v18, v19
	v_cvt_pk_bf16_f32 v19, v24, v25
	global_store_dwordx4 v[28:29], v[16:19], off offset:256
	v_and_b32_e32 v21, 0xffff0000, v70
	v_lshlrev_b32_e32 v22, 16, v71
	v_lshlrev_b32_e32 v16, 16, v68
	v_and_b32_e32 v17, 0xffff0000, v68
	v_and_b32_e32 v23, 0xffff0000, v71
	v_pk_fma_f32 v[12:13], v[12:13], v[132:133], v[16:17]
	v_lshlrev_b32_e32 v18, 16, v69
	v_and_b32_e32 v19, 0xffff0000, v69
	v_pk_fma_f32 v[16:17], v[10:11], v[130:131], v[22:23]
	v_pk_fma_f32 v[10:11], v[8:9], v[128:129], v[20:21]
	v_cvt_pk_bf16_f32 v8, v12, v13
	v_lshl_add_u64 v[12:13], s[8:9], 0, v[72:73]
	v_pk_fma_f32 v[14:15], v[14:15], v[134:135], v[18:19]
	v_lshl_add_u64 v[12:13], v[12:13], 0, v[178:179]
	v_cvt_pk_bf16_f32 v9, v14, v15
	v_cvt_pk_bf16_f32 v10, v10, v11
	v_cvt_pk_bf16_f32 v11, v16, v17
	global_store_dwordx4 v[12:13], v[8:11], off
	v_lshlrev_b32_e32 v14, 16, v66
	v_and_b32_e32 v15, 0xffff0000, v66
	v_lshlrev_b32_e32 v8, 16, v64
	v_and_b32_e32 v9, 0xffff0000, v64
	v_lshlrev_b32_e32 v16, 16, v67
	v_and_b32_e32 v17, 0xffff0000, v67
	v_lshlrev_b32_e32 v10, 16, v65
	v_and_b32_e32 v11, 0xffff0000, v65
	v_pk_fma_f32 v[4:5], v[4:5], v[124:125], v[8:9]
	v_pk_fma_f32 v[8:9], v[2:3], v[122:123], v[16:17]
	v_pk_fma_f32 v[2:3], v[0:1], v[120:121], v[14:15]
	v_pk_fma_f32 v[6:7], v[6:7], v[126:127], v[10:11]
	v_cvt_pk_bf16_f32 v0, v4, v5
	s_nop 0
	v_cvt_pk_bf16_f32 v1, v6, v7
	v_cvt_pk_bf16_f32 v2, v2, v3
	v_cvt_pk_bf16_f32 v3, v8, v9
	global_store_dwordx4 v[12:13], v[0:3], off offset:256
	s_cbranch_vccz .LBB0_235
	s_waitcnt vmcnt(0)
	s_cmpk_gt_u32 s16, 0xff
	s_cbranch_scc1 .LBB0_250
	s_barrier

.LBB0_272:
	s_add_u32 s10, s8, 0x100
	s_addc_u32 s11, s9, 0
	s_add_i32 s42, 0, 0x10000
	v_add_u32_e32 v120, s42, v187
	ds_read_b128 v[108:111], v120
	ds_read_b128 v[112:115], v120 offset:1024
	ds_read_b128 v[116:119], v120 offset:2048
	ds_read_b128 v[120:123], v120 offset:3072
	s_cmpk_eq_i32 s41, 0x54
	s_cselect_b32 s15, s5, s11
	s_cselect_b32 s14, s4, s10
	s_cselect_b32 s13, s7, s40
	s_cselect_b32 s12, s6, s39
	v_lshl_add_u64 v[190:191], s[8:9], 0, v[170:171]
	s_add_i32 m0, s25, 0xc000
	ds_read_b128 v[144:147], v189
	ds_read_b128 v[148:151], v189 offset:1024
	ds_read_b128 v[152:155], v189 offset:2048
	ds_read_b128 v[156:159], v189 offset:3072
	ds_read_b128 v[160:163], v189 offset:4096
	ds_read_b128 v[174:177], v189 offset:5120
	ds_read_b128 v[178:181], v189 offset:6144
	ds_read_b128 v[182:185], v189 offset:7168
	global_load_lds_dwordx4 v[190:191], off
	v_lshl_add_u64 v[190:191], s[8:9], 0, v[172:173]
	s_add_i32 m0, s25, 0xe000
	s_nop 0
	global_load_lds_dwordx4 v[190:191], off
	s_waitcnt lgkmcnt(8)
	s_barrier
	s_waitcnt lgkmcnt(0)
	s_waitcnt lgkmcnt(0)
	v_mfma_f32_16x16x32_bf16 v[140:143], v[108:111], v[144:147], v[140:143]
	v_mfma_f32_16x16x32_bf16 v[136:139], v[116:119], v[144:147], v[136:139]
	v_mfma_f32_16x16x32_bf16 v[132:135], v[108:111], v[152:155], v[132:135]
	v_mfma_f32_16x16x32_bf16 v[104:107], v[116:119], v[152:155], v[104:107]
	v_mfma_f32_16x16x32_bf16 v[96:99], v[108:111], v[160:163], v[96:99]
	v_mfma_f32_16x16x32_bf16 v[88:91], v[116:119], v[160:163], v[88:91]
	v_mfma_f32_16x16x32_bf16 v[80:83], v[108:111], v[178:181], v[80:83]
	v_mfma_f32_16x16x32_bf16 v[72:75], v[116:119], v[178:181], v[72:75]
	v_mfma_f32_16x16x32_bf16 v[140:143], v[112:115], v[148:151], v[140:143]
	v_mfma_f32_16x16x32_bf16 v[136:139], v[120:123], v[148:151], v[136:139]
	v_mfma_f32_16x16x32_bf16 v[132:135], v[112:115], v[156:159], v[132:135]
	v_mfma_f32_16x16x32_bf16 v[104:107], v[120:123], v[156:159], v[104:107]
	v_mfma_f32_16x16x32_bf16 v[96:99], v[112:115], v[174:177], v[96:99]
	v_mfma_f32_16x16x32_bf16 v[88:91], v[120:123], v[174:177], v[88:91]
	v_mfma_f32_16x16x32_bf16 v[80:83], v[112:115], v[182:185], v[80:83]
	v_mfma_f32_16x16x32_bf16 v[72:75], v[120:123], v[182:185], v[72:75]
	s_barrier
	s_add_i32 s43, 0, 0x14000
	v_add_u32_e32 v190, s43, v187
	s_add_i32 s8, s42, s19
	ds_read_b128 v[196:199], v190
	ds_read_b128 v[204:207], v190 offset:1024
	ds_read_b128 v[208:211], v190 offset:2048
	ds_read_b128 v[214:217], v190 offset:3072
	v_lshl_add_u64 v[190:191], s[12:13], 0, v[192:193]
	s_mov_b32 m0, s8
	v_lshl_add_u64 v[218:219], s[12:13], 0, v[168:169]
	global_load_lds_dwordx4 v[190:191], off
	s_add_i32 m0, s8, 0x2000
	s_nop 0
	global_load_lds_dwordx4 v[218:219], off
	s_barrier
	s_waitcnt lgkmcnt(0)
	s_waitcnt lgkmcnt(0)
	v_mfma_f32_16x16x32_bf16 v[128:131], v[196:199], v[144:147], v[128:131]
	v_mfma_f32_16x16x32_bf16 v[124:127], v[208:211], v[144:147], v[124:127]
	v_mfma_f32_16x16x32_bf16 v[100:103], v[196:199], v[152:155], v[100:103]
	v_mfma_f32_16x16x32_bf16 v[92:95], v[208:211], v[152:155], v[92:95]
	v_mfma_f32_16x16x32_bf16 v[84:87], v[196:199], v[160:163], v[84:87]
	v_mfma_f32_16x16x32_bf16 v[76:79], v[208:211], v[160:163], v[76:79]
	v_mfma_f32_16x16x32_bf16 v[68:71], v[196:199], v[178:181], v[68:71]
	v_mfma_f32_16x16x32_bf16 v[64:67], v[208:211], v[178:181], v[64:67]
	v_mfma_f32_16x16x32_bf16 v[128:131], v[204:207], v[148:151], v[128:131]
	v_mfma_f32_16x16x32_bf16 v[124:127], v[214:217], v[148:151], v[124:127]
	v_mfma_f32_16x16x32_bf16 v[100:103], v[204:207], v[156:159], v[100:103]
	v_mfma_f32_16x16x32_bf16 v[92:95], v[214:217], v[156:159], v[92:95]
	v_mfma_f32_16x16x32_bf16 v[84:87], v[204:207], v[174:177], v[84:87]
	v_mfma_f32_16x16x32_bf16 v[76:79], v[214:217], v[174:177], v[76:79]
	v_mfma_f32_16x16x32_bf16 v[68:71], v[204:207], v[182:185], v[68:71]
	v_mfma_f32_16x16x32_bf16 v[64:67], v[214:217], v[182:185], v[64:67]
	s_mov_b32 m0, s25
	v_lshl_add_u64 v[220:221], s[14:15], 0, v[164:165]
	s_barrier
	ds_read_b128 v[144:147], v189 offset:16384
	ds_read_b128 v[148:151], v189 offset:17408
	ds_read_b128 v[152:155], v189 offset:18432
	ds_read_b128 v[156:159], v189 offset:19456
	ds_read_b128 v[160:163], v189 offset:20480
	ds_read_b128 v[174:177], v189 offset:21504
	ds_read_b128 v[178:181], v189 offset:22528
	ds_read_b128 v[182:185], v189 offset:23552
	global_load_lds_dwordx4 v[220:221], off
	v_lshl_add_u64 v[222:223], s[14:15], 0, v[166:167]
	s_mov_b32 m0, s26
	s_nop 0
	global_load_lds_dwordx4 v[222:223], off
	s_barrier
	s_waitcnt lgkmcnt(0)
	s_waitcnt lgkmcnt(0)
	v_mfma_f32_16x16x32_bf16 v[60:63], v[108:111], v[144:147], v[60:63]
	v_mfma_f32_16x16x32_bf16 v[56:59], v[116:119], v[144:147], v[56:59]
	v_mfma_f32_16x16x32_bf16 v[48:51], v[108:111], v[152:155], v[48:51]
	v_mfma_f32_16x16x32_bf16 v[40:43], v[116:119], v[152:155], v[40:43]
	v_mfma_f32_16x16x32_bf16 v[32:35], v[108:111], v[160:163], v[32:35]
	v_mfma_f32_16x16x32_bf16 v[24:27], v[116:119], v[160:163], v[24:27]
	v_mfma_f32_16x16x32_bf16 v[16:19], v[108:111], v[178:181], v[16:19]
	v_mfma_f32_16x16x32_bf16 v[8:11], v[116:119], v[178:181], v[8:11]
	v_mfma_f32_16x16x32_bf16 v[60:63], v[112:115], v[148:151], v[60:63]
	v_mfma_f32_16x16x32_bf16 v[56:59], v[120:123], v[148:151], v[56:59]
	v_mfma_f32_16x16x32_bf16 v[48:51], v[112:115], v[156:159], v[48:51]
	v_mfma_f32_16x16x32_bf16 v[40:43], v[120:123], v[156:159], v[40:43]
	v_mfma_f32_16x16x32_bf16 v[32:35], v[112:115], v[174:177], v[32:35]
	v_mfma_f32_16x16x32_bf16 v[24:27], v[120:123], v[174:177], v[24:27]
	v_mfma_f32_16x16x32_bf16 v[16:19], v[112:115], v[182:185], v[16:19]
	v_mfma_f32_16x16x32_bf16 v[8:11], v[120:123], v[182:185], v[8:11]
	s_barrier
	s_add_u32 s8, s12, 0x160000
	s_addc_u32 s9, s13, 0
	s_add_i32 s42, s43, s19
	v_lshl_add_u64 v[108:109], s[8:9], 0, v[192:193]
	s_mov_b32 m0, s42
	s_nop 0
	global_load_lds_dwordx4 v[108:109], off
	v_lshl_add_u64 v[108:109], s[8:9], 0, v[168:169]
	s_add_i32 m0, s42, 0x2000
	s_nop 0
	global_load_lds_dwordx4 v[108:109], off
	s_waitcnt vmcnt(6)
	s_barrier
	v_mfma_f32_16x16x32_bf16 v[52:55], v[196:199], v[144:147], v[52:55]
	v_mfma_f32_16x16x32_bf16 v[44:47], v[208:211], v[144:147], v[44:47]
	v_mfma_f32_16x16x32_bf16 v[36:39], v[196:199], v[152:155], v[36:39]
	v_mfma_f32_16x16x32_bf16 v[28:31], v[208:211], v[152:155], v[28:31]
	v_mfma_f32_16x16x32_bf16 v[20:23], v[196:199], v[160:163], v[20:23]
	v_mfma_f32_16x16x32_bf16 v[12:15], v[208:211], v[160:163], v[12:15]
	v_mfma_f32_16x16x32_bf16 v[4:7], v[196:199], v[178:181], v[4:7]
	v_mfma_f32_16x16x32_bf16 v[0:3], v[208:211], v[178:181], v[0:3]
	v_mfma_f32_16x16x32_bf16 v[52:55], v[204:207], v[148:151], v[52:55]
	v_mfma_f32_16x16x32_bf16 v[44:47], v[214:217], v[148:151], v[44:47]
	v_mfma_f32_16x16x32_bf16 v[36:39], v[204:207], v[156:159], v[36:39]
	v_mfma_f32_16x16x32_bf16 v[28:31], v[214:217], v[156:159], v[28:31]
	v_mfma_f32_16x16x32_bf16 v[20:23], v[204:207], v[174:177], v[20:23]
	v_mfma_f32_16x16x32_bf16 v[12:15], v[214:217], v[174:177], v[12:15]
	v_mfma_f32_16x16x32_bf16 v[4:7], v[204:207], v[182:185], v[4:7]
	v_mfma_f32_16x16x32_bf16 v[0:3], v[214:217], v[182:185], v[0:3]
	s_add_i32 s42, 0, 0x18000
	v_add_u32_e32 v120, s42, v187
	s_barrier
	ds_read_b128 v[108:111], v120
	ds_read_b128 v[112:115], v120 offset:1024
	ds_read_b128 v[116:119], v120 offset:2048
	ds_read_b128 v[120:123], v120 offset:3072
	s_add_u32 s8, s14, 0x160000
	s_addc_u32 s9, s15, 0
	s_mov_b32 m0, s27
	v_lshl_add_u64 v[196:197], s[8:9], 0, v[164:165]
	ds_read_b128 v[144:147], v189 offset:32768
	ds_read_b128 v[148:151], v189 offset:33792
	ds_read_b128 v[152:155], v189 offset:34816
	ds_read_b128 v[156:159], v189 offset:35840
	ds_read_b128 v[160:163], v189 offset:36864
	ds_read_b128 v[174:177], v189 offset:37888
	ds_read_b128 v[178:181], v189 offset:38912
	ds_read_b128 v[182:185], v189 offset:39936
	global_load_lds_dwordx4 v[196:197], off
	v_lshl_add_u64 v[196:197], s[8:9], 0, v[166:167]
	s_mov_b32 m0, s28
	s_nop 0
	global_load_lds_dwordx4 v[196:197], off
	s_waitcnt lgkmcnt(8)
	s_barrier
	s_waitcnt lgkmcnt(0)
	s_waitcnt lgkmcnt(0)
	v_mfma_f32_16x16x32_bf16 v[140:143], v[108:111], v[144:147], v[140:143]
	v_mfma_f32_16x16x32_bf16 v[136:139], v[116:119], v[144:147], v[136:139]
	v_mfma_f32_16x16x32_bf16 v[132:135], v[108:111], v[152:155], v[132:135]
	v_mfma_f32_16x16x32_bf16 v[104:107], v[116:119], v[152:155], v[104:107]
	v_mfma_f32_16x16x32_bf16 v[96:99], v[108:111], v[160:163], v[96:99]
	v_mfma_f32_16x16x32_bf16 v[88:91], v[116:119], v[160:163], v[88:91]
	v_mfma_f32_16x16x32_bf16 v[80:83], v[108:111], v[178:181], v[80:83]
	v_mfma_f32_16x16x32_bf16 v[72:75], v[116:119], v[178:181], v[72:75]
	v_mfma_f32_16x16x32_bf16 v[140:143], v[112:115], v[148:151], v[140:143]
	v_mfma_f32_16x16x32_bf16 v[136:139], v[120:123], v[148:151], v[136:139]
	v_mfma_f32_16x16x32_bf16 v[132:135], v[112:115], v[156:159], v[132:135]
	v_mfma_f32_16x16x32_bf16 v[104:107], v[120:123], v[156:159], v[104:107]
	v_mfma_f32_16x16x32_bf16 v[96:99], v[112:115], v[174:177], v[96:99]
	v_mfma_f32_16x16x32_bf16 v[88:91], v[120:123], v[174:177], v[88:91]
	v_mfma_f32_16x16x32_bf16 v[80:83], v[112:115], v[182:185], v[80:83]
	v_mfma_f32_16x16x32_bf16 v[72:75], v[120:123], v[182:185], v[72:75]
	s_barrier
	s_add_i32 s14, 0, 0x1c000
	s_add_i32 s8, s42, s19
	v_add_u32_e32 v212, s14, v187
	v_lshl_add_u64 v[190:191], v[190:191], 0, s[44:45]
	s_mov_b32 m0, s8
	ds_read_b128 v[196:199], v212
	ds_read_b128 v[204:207], v212 offset:1024
	ds_read_b128 v[208:211], v212 offset:2048
	ds_read_b128 v[214:217], v212 offset:3072
	global_load_lds_dwordx4 v[190:191], off
	v_lshl_add_u64 v[190:191], v[218:219], 0, s[44:45]
	s_add_i32 m0, s8, 0x2000
	s_nop 0
	global_load_lds_dwordx4 v[190:191], off
	s_barrier
	s_waitcnt lgkmcnt(0)
	s_waitcnt lgkmcnt(0)
	v_mfma_f32_16x16x32_bf16 v[128:131], v[196:199], v[144:147], v[128:131]
	v_mfma_f32_16x16x32_bf16 v[124:127], v[208:211], v[144:147], v[124:127]
	v_mfma_f32_16x16x32_bf16 v[100:103], v[196:199], v[152:155], v[100:103]
	v_mfma_f32_16x16x32_bf16 v[92:95], v[208:211], v[152:155], v[92:95]
	v_mfma_f32_16x16x32_bf16 v[84:87], v[196:199], v[160:163], v[84:87]
	v_mfma_f32_16x16x32_bf16 v[76:79], v[208:211], v[160:163], v[76:79]
	v_mfma_f32_16x16x32_bf16 v[68:71], v[196:199], v[178:181], v[68:71]
	v_mfma_f32_16x16x32_bf16 v[64:67], v[208:211], v[178:181], v[64:67]
	v_mfma_f32_16x16x32_bf16 v[128:131], v[204:207], v[148:151], v[128:131]
	v_mfma_f32_16x16x32_bf16 v[124:127], v[214:217], v[148:151], v[124:127]
	v_mfma_f32_16x16x32_bf16 v[100:103], v[204:207], v[156:159], v[100:103]
	v_mfma_f32_16x16x32_bf16 v[92:95], v[214:217], v[156:159], v[92:95]
	v_mfma_f32_16x16x32_bf16 v[84:87], v[204:207], v[174:177], v[84:87]
	v_mfma_f32_16x16x32_bf16 v[76:79], v[214:217], v[174:177], v[76:79]
	v_mfma_f32_16x16x32_bf16 v[68:71], v[204:207], v[182:185], v[68:71]
	v_mfma_f32_16x16x32_bf16 v[64:67], v[214:217], v[182:185], v[64:67]
	s_mov_b32 m0, s31
	v_lshl_add_u64 v[190:191], v[220:221], 0, s[44:45]
	s_barrier
	ds_read_b128 v[144:147], v189 offset:49152
	ds_read_b128 v[148:151], v189 offset:50176
	ds_read_b128 v[152:155], v189 offset:51200
	ds_read_b128 v[156:159], v189 offset:52224
	ds_read_b128 v[160:163], v189 offset:53248
	ds_read_b128 v[174:177], v189 offset:54272
	ds_read_b128 v[178:181], v189 offset:55296
	ds_read_b128 v[182:185], v189 offset:56320
	global_load_lds_dwordx4 v[190:191], off
	v_lshl_add_u64 v[190:191], v[222:223], 0, s[44:45]
	s_mov_b32 m0, s33
	s_nop 0
	global_load_lds_dwordx4 v[190:191], off
	s_barrier
	s_waitcnt lgkmcnt(0)
	s_waitcnt lgkmcnt(0)
	v_mfma_f32_16x16x32_bf16 v[60:63], v[108:111], v[144:147], v[60:63]
	v_mfma_f32_16x16x32_bf16 v[56:59], v[116:119], v[144:147], v[56:59]
	v_mfma_f32_16x16x32_bf16 v[48:51], v[108:111], v[152:155], v[48:51]
	v_mfma_f32_16x16x32_bf16 v[40:43], v[116:119], v[152:155], v[40:43]
	v_mfma_f32_16x16x32_bf16 v[32:35], v[108:111], v[160:163], v[32:35]
	v_mfma_f32_16x16x32_bf16 v[24:27], v[116:119], v[160:163], v[24:27]
	v_mfma_f32_16x16x32_bf16 v[16:19], v[108:111], v[178:181], v[16:19]
	v_mfma_f32_16x16x32_bf16 v[8:11], v[116:119], v[178:181], v[8:11]
	v_mfma_f32_16x16x32_bf16 v[60:63], v[112:115], v[148:151], v[60:63]
	v_mfma_f32_16x16x32_bf16 v[56:59], v[120:123], v[148:151], v[56:59]
	v_mfma_f32_16x16x32_bf16 v[48:51], v[112:115], v[156:159], v[48:51]
	v_mfma_f32_16x16x32_bf16 v[40:43], v[120:123], v[156:159], v[40:43]
	v_mfma_f32_16x16x32_bf16 v[32:35], v[112:115], v[174:177], v[32:35]
	v_mfma_f32_16x16x32_bf16 v[24:27], v[120:123], v[174:177], v[24:27]
	v_mfma_f32_16x16x32_bf16 v[16:19], v[112:115], v[182:185], v[16:19]
	v_mfma_f32_16x16x32_bf16 v[8:11], v[120:123], v[182:185], v[8:11]
	s_barrier
	s_add_u32 s8, s12, 0x160080
	s_addc_u32 s9, s13, 0
	s_add_i32 s12, s14, s19
	v_lshl_add_u64 v[108:109], s[8:9], 0, v[192:193]
	s_mov_b32 m0, s12
	s_nop 0
	global_load_lds_dwordx4 v[108:109], off
	v_lshl_add_u64 v[108:109], s[8:9], 0, v[168:169]
	s_add_i32 m0, s12, 0x2000
	s_nop 0
	global_load_lds_dwordx4 v[108:109], off
	s_waitcnt vmcnt(6)
	s_barrier
	v_mfma_f32_16x16x32_bf16 v[52:55], v[196:199], v[144:147], v[52:55]
	v_mfma_f32_16x16x32_bf16 v[44:47], v[208:211], v[144:147], v[44:47]
	v_mfma_f32_16x16x32_bf16 v[36:39], v[196:199], v[152:155], v[36:39]
	v_mfma_f32_16x16x32_bf16 v[28:31], v[208:211], v[152:155], v[28:31]
	v_mfma_f32_16x16x32_bf16 v[20:23], v[196:199], v[160:163], v[20:23]
	v_mfma_f32_16x16x32_bf16 v[12:15], v[208:211], v[160:163], v[12:15]
	v_mfma_f32_16x16x32_bf16 v[4:7], v[196:199], v[178:181], v[4:7]
	v_mfma_f32_16x16x32_bf16 v[0:3], v[208:211], v[178:181], v[0:3]
	v_mfma_f32_16x16x32_bf16 v[52:55], v[204:207], v[148:151], v[52:55]
	v_mfma_f32_16x16x32_bf16 v[44:47], v[214:217], v[148:151], v[44:47]
	v_mfma_f32_16x16x32_bf16 v[36:39], v[204:207], v[156:159], v[36:39]
	v_mfma_f32_16x16x32_bf16 v[28:31], v[214:217], v[156:159], v[28:31]
	v_mfma_f32_16x16x32_bf16 v[20:23], v[204:207], v[174:177], v[20:23]
	v_mfma_f32_16x16x32_bf16 v[12:15], v[214:217], v[174:177], v[12:15]
	v_mfma_f32_16x16x32_bf16 v[4:7], v[204:207], v[182:185], v[4:7]
	v_mfma_f32_16x16x32_bf16 v[0:3], v[214:217], v[182:185], v[0:3]
	s_add_i32 s41, s41, 2
	s_add_u32 s39, s39, 0x100
	s_addc_u32 s40, s40, 0
	s_cmpk_gt_u32 s41, 0x55
	s_mov_b64 s[8:9], s[10:11]
	s_barrier
	s_cbranch_scc0 .LBB0_272
	s_ashr_i32 s8, s37, 4
	v_lshl_or_b32 v144, s38, 8, v188
	s_mul_hi_i32 s9, s8, 0xc000
	s_mul_i32 s8, s8, 0xc000
	v_lshl_add_u32 v178, s37, 8, v186
	s_add_u32 s8, s29, s8
	v_ashrrev_i32_e32 v145, 31, v144
	v_ashrrev_i32_e32 v179, 31, v178
	s_addc_u32 s9, s30, s9
	v_lshlrev_b64 v[174:175], 2, v[144:145]
	v_lshl_add_u64 v[176:177], v[144:145], 1, s[2:3]
	v_lshlrev_b64 v[144:145], 12, v[178:179]
	v_lshl_add_u64 v[112:113], s[8:9], 0, v[174:175]
	v_lshl_add_u64 v[144:145], v[176:177], 0, v[144:145]
	global_load_dwordx4 v[116:119], v[112:113], off offset:16
	global_load_dwordx4 v[120:123], v[112:113], off
	global_load_dwordx4 v[108:111], v[112:113], off offset:528
	s_nop 0
	global_load_dwordx4 v[112:115], v[112:113], off offset:512
	s_nop 0
	global_load_dwordx4 v[196:199], v[144:145], off
	global_load_dwordx4 v[204:207], v[144:145], off offset:256
	v_or_b32_e32 v184, 16, v178
	v_ashrrev_i32_e32 v185, 31, v184
	v_lshlrev_b64 v[144:145], 12, v[184:185]
	v_lshl_add_u64 v[144:145], v[176:177], 0, v[144:145]
	global_load_dwordx4 v[208:211], v[144:145], off
	global_load_dwordx4 v[160:163], v[144:145], off offset:256
	v_or_b32_e32 v182, 32, v178
	v_ashrrev_i32_e32 v183, 31, v182
	v_lshlrev_b64 v[144:145], 12, v[182:183]
	v_lshl_add_u64 v[144:145], v[176:177], 0, v[144:145]
	global_load_dwordx4 v[156:159], v[144:145], off
	global_load_dwordx4 v[152:155], v[144:145], off offset:256
	v_or_b32_e32 v180, 48, v178
	v_ashrrev_i32_e32 v181, 31, v180
	v_lshlrev_b64 v[144:145], 12, v[180:181]
	v_lshl_add_u64 v[144:145], v[176:177], 0, v[144:145]
	global_load_dwordx4 v[148:151], v[144:145], off
	s_nop 0
	global_load_dwordx4 v[144:147], v[144:145], off offset:256
	v_readlane_b32 s52, v254, 39
	v_readlane_b32 s66, v254, 53
	v_readlane_b32 s67, v254, 54
	s_and_b64 vcc, exec, s[0:1]
	s_mov_b32 s38, s35
	s_mov_b32 s37, s36
	s_mov_b64 s[10:11], s[6:7]
	s_mov_b64 s[8:9], s[4:5]
	v_readlane_b32 s14, v254, 21
	s_movk_i32 s15, 0x2000
	v_readlane_b32 s53, v254, 40
	v_readlane_b32 s54, v254, 41
	v_readlane_b32 s55, v254, 42
	v_readlane_b32 s56, v254, 43
	v_readlane_b32 s57, v254, 44
	v_readlane_b32 s58, v254, 45
	v_readlane_b32 s59, v254, 46
	v_readlane_b32 s60, v254, 47
	v_readlane_b32 s61, v254, 48
	v_readlane_b32 s62, v254, 49
	v_readlane_b32 s63, v254, 50
	v_readlane_b32 s64, v254, 51
	v_readlane_b32 s65, v254, 52
	s_waitcnt vmcnt(0)
	v_lshlrev_b32_e32 v190, 16, v196
	v_and_b32_e32 v191, 0xffff0000, v196
	v_pk_fma_f32 v[140:141], v[140:141], v[120:121], v[190:191]
	v_lshlrev_b64 v[190:191], 13, v[178:179]
	v_lshlrev_b32_e32 v196, 16, v197
	v_and_b32_e32 v197, 0xffff0000, v197
	v_lshl_add_u64 v[190:191], s[66:67], 0, v[190:191]
	v_pk_fma_f32 v[142:143], v[142:143], v[122:123], v[196:197]
	v_lshl_add_u64 v[190:191], v[190:191], 0, v[174:175]
	global_store_dwordx4 v[190:191], v[140:143], off
	v_lshlrev_b32_e32 v214, 16, v198
	v_and_b32_e32 v215, 0xffff0000, v198
	v_lshlrev_b32_e32 v140, 16, v206
	v_and_b32_e32 v141, 0xffff0000, v206
	v_lshlrev_b32_e32 v142, 16, v207
	v_and_b32_e32 v143, 0xffff0000, v207
	v_pk_fma_f32 v[126:127], v[126:127], v[110:111], v[142:143]
	v_pk_fma_f32 v[124:125], v[124:125], v[108:109], v[140:141]
	global_store_dwordx4 v[190:191], v[124:127], off offset:528
	v_lshlrev_b32_e32 v198, 16, v199
	v_and_b32_e32 v199, 0xffff0000, v199
	v_lshlrev_b32_e32 v124, 16, v208
	v_and_b32_e32 v125, 0xffff0000, v208
	v_pk_fma_f32 v[124:125], v[132:133], v[120:121], v[124:125]
	v_lshlrev_b64 v[132:133], 13, v[184:185]
	v_lshlrev_b32_e32 v126, 16, v209
	v_and_b32_e32 v127, 0xffff0000, v209
	v_lshl_add_u64 v[132:133], s[66:67], 0, v[132:133]
	v_pk_fma_f32 v[126:127], v[134:135], v[122:123], v[126:127]
	v_lshl_add_u64 v[132:133], v[132:133], 0, v[174:175]
	v_pk_fma_f32 v[138:139], v[138:139], v[118:119], v[198:199]
	v_pk_fma_f32 v[136:137], v[136:137], v[116:117], v[214:215]
	global_store_dwordx4 v[132:133], v[124:127], off
	global_store_dwordx4 v[190:191], v[136:139], off offset:16
	s_nop 0
	v_lshlrev_b32_e32 v124, 16, v162
	v_and_b32_e32 v125, 0xffff0000, v162
	v_lshlrev_b32_e32 v126, 16, v163
	v_and_b32_e32 v127, 0xffff0000, v163
	v_lshlrev_b32_e32 v136, 16, v204
	v_and_b32_e32 v137, 0xffff0000, v204
	v_lshlrev_b32_e32 v138, 16, v205
	v_and_b32_e32 v139, 0xffff0000, v205
	v_pk_fma_f32 v[94:95], v[94:95], v[110:111], v[126:127]
	v_pk_fma_f32 v[92:93], v[92:93], v[108:109], v[124:125]
	v_pk_fma_f32 v[130:131], v[130:131], v[114:115], v[138:139]
	v_pk_fma_f32 v[128:129], v[128:129], v[112:113], v[136:137]
	global_store_dwordx4 v[132:133], v[92:95], off offset:528
	global_store_dwordx4 v[190:191], v[128:131], off offset:512
	s_nop 0
	v_lshlrev_b32_e32 v92, 16, v156
	v_and_b32_e32 v93, 0xffff0000, v156
	v_lshlrev_b32_e32 v128, 16, v210
	v_and_b32_e32 v129, 0xffff0000, v210
	v_lshlrev_b32_e32 v130, 16, v211
	v_and_b32_e32 v131, 0xffff0000, v211
	v_pk_fma_f32 v[92:93], v[96:97], v[120:121], v[92:93]
	v_lshlrev_b64 v[96:97], 13, v[182:183]
	v_pk_fma_f32 v[106:107], v[106:107], v[118:119], v[130:131]
	v_pk_fma_f32 v[104:105], v[104:105], v[116:117], v[128:129]
	v_lshlrev_b32_e32 v94, 16, v157
	v_and_b32_e32 v95, 0xffff0000, v157
	v_lshl_add_u64 v[96:97], s[66:67], 0, v[96:97]
	global_store_dwordx4 v[132:133], v[104:107], off offset:16
	v_pk_fma_f32 v[94:95], v[98:99], v[122:123], v[94:95]
	v_lshl_add_u64 v[96:97], v[96:97], 0, v[174:175]
	v_lshlrev_b32_e32 v104, 16, v160
	v_and_b32_e32 v105, 0xffff0000, v160
	v_lshlrev_b32_e32 v106, 16, v161
	v_and_b32_e32 v107, 0xffff0000, v161
	v_pk_fma_f32 v[102:103], v[102:103], v[114:115], v[106:107]
	v_pk_fma_f32 v[100:101], v[100:101], v[112:113], v[104:105]
	global_store_dwordx4 v[96:97], v[92:95], off
	global_store_dwordx4 v[132:133], v[100:103], off offset:512
	v_add_u32_e32 v98, 0x90, v178
	v_lshlrev_b32_e32 v92, 16, v154
	v_and_b32_e32 v93, 0xffff0000, v154
	v_lshlrev_b32_e32 v94, 16, v155
	v_and_b32_e32 v95, 0xffff0000, v155
	v_lshlrev_b32_e32 v100, 16, v158
	v_and_b32_e32 v101, 0xffff0000, v158
	v_lshlrev_b32_e32 v102, 16, v159
	v_and_b32_e32 v103, 0xffff0000, v159
	v_pk_fma_f32 v[78:79], v[78:79], v[110:111], v[94:95]
	v_pk_fma_f32 v[76:77], v[76:77], v[108:109], v[92:93]
	v_pk_fma_f32 v[90:91], v[90:91], v[118:119], v[102:103]
	v_pk_fma_f32 v[88:89], v[88:89], v[116:117], v[100:101]
	global_store_dwordx4 v[96:97], v[76:79], off offset:528
	global_store_dwordx4 v[96:97], v[88:91], off offset:16
	v_ashrrev_i32_e32 v99, 31, v98
	v_lshlrev_b32_e32 v76, 16, v148
	v_and_b32_e32 v77, 0xffff0000, v148
	v_lshlrev_b32_e32 v88, 16, v152
	v_and_b32_e32 v89, 0xffff0000, v152
	v_lshlrev_b32_e32 v90, 16, v153
	v_and_b32_e32 v91, 0xffff0000, v153
	v_pk_fma_f32 v[76:77], v[80:81], v[120:121], v[76:77]
	v_lshlrev_b64 v[80:81], 13, v[180:181]
	v_pk_fma_f32 v[86:87], v[86:87], v[114:115], v[90:91]
	v_pk_fma_f32 v[84:85], v[84:85], v[112:113], v[88:89]
	v_lshlrev_b32_e32 v78, 16, v149
	v_and_b32_e32 v79, 0xffff0000, v149
	v_lshl_add_u64 v[80:81], s[66:67], 0, v[80:81]
	global_store_dwordx4 v[96:97], v[84:87], off offset:512
	v_pk_fma_f32 v[78:79], v[82:83], v[122:123], v[78:79]
	v_lshl_add_u64 v[80:81], v[80:81], 0, v[174:175]
	v_lshlrev_b32_e32 v84, 16, v150
	v_and_b32_e32 v85, 0xffff0000, v150
	v_lshlrev_b32_e32 v86, 16, v151
	v_and_b32_e32 v87, 0xffff0000, v151
	global_store_dwordx4 v[80:81], v[76:79], off
	v_pk_fma_f32 v[74:75], v[74:75], v[118:119], v[86:87]
	v_pk_fma_f32 v[72:73], v[72:73], v[116:117], v[84:85]
	v_lshlrev_b32_e32 v76, 16, v146
	v_and_b32_e32 v77, 0xffff0000, v146
	v_lshlrev_b32_e32 v78, 16, v147
	v_and_b32_e32 v79, 0xffff0000, v147
	v_add_u32_e32 v96, 0x80, v178
	global_store_dwordx4 v[80:81], v[72:75], off offset:16
	v_pk_fma_f32 v[66:67], v[66:67], v[110:111], v[78:79]
	v_pk_fma_f32 v[64:65], v[64:65], v[108:109], v[76:77]
	v_lshlrev_b32_e32 v72, 16, v144
	v_and_b32_e32 v73, 0xffff0000, v144
	v_lshlrev_b32_e32 v74, 16, v145
	v_and_b32_e32 v75, 0xffff0000, v145
	v_ashrrev_i32_e32 v97, 31, v96
	v_pk_fma_f32 v[70:71], v[70:71], v[114:115], v[74:75]
	v_pk_fma_f32 v[68:69], v[68:69], v[112:113], v[72:73]
	global_store_dwordx4 v[80:81], v[64:67], off offset:528
	global_store_dwordx4 v[80:81], v[68:71], off offset:512
	v_add_u32_e32 v100, 0xa0, v178
	v_lshlrev_b64 v[64:65], 12, v[96:97]
	v_lshl_add_u64 v[64:65], v[176:177], 0, v[64:65]
	global_load_dwordx4 v[68:71], v[64:65], off
	global_load_dwordx4 v[72:75], v[64:65], off offset:256
	v_lshlrev_b64 v[64:65], 12, v[98:99]
	v_lshl_add_u64 v[64:65], v[176:177], 0, v[64:65]
	global_load_dwordx4 v[76:79], v[64:65], off
	global_load_dwordx4 v[80:83], v[64:65], off offset:256
	v_ashrrev_i32_e32 v101, 31, v100
	v_lshlrev_b64 v[64:65], 12, v[100:101]
	v_lshl_add_u64 v[64:65], v[176:177], 0, v[64:65]
	global_load_dwordx4 v[84:87], v[64:65], off
	global_load_dwordx4 v[88:91], v[64:65], off offset:256
	v_add_u32_e32 v102, 0xb0, v178
	v_ashrrev_i32_e32 v103, 31, v102
	v_lshlrev_b64 v[64:65], 12, v[102:103]
	v_lshl_add_u64 v[64:65], v[176:177], 0, v[64:65]
	global_load_dwordx4 v[92:95], v[64:65], off
	s_nop 0
	global_load_dwordx4 v[64:67], v[64:65], off offset:256
	s_waitcnt vmcnt(0)
	v_lshlrev_b32_e32 v104, 16, v68
	v_and_b32_e32 v105, 0xffff0000, v68
	v_lshlrev_b32_e32 v68, 16, v69
	v_and_b32_e32 v69, 0xffff0000, v69
	v_pk_fma_f32 v[62:63], v[62:63], v[122:123], v[68:69]
	v_lshlrev_b64 v[68:69], 13, v[96:97]
	v_lshl_add_u64 v[68:69], s[66:67], 0, v[68:69]
	v_pk_fma_f32 v[60:61], v[60:61], v[120:121], v[104:105]
	v_lshl_add_u64 v[68:69], v[68:69], 0, v[174:175]
	global_store_dwordx4 v[68:69], v[60:63], off
	v_lshlrev_b32_e32 v106, 16, v70
	v_and_b32_e32 v107, 0xffff0000, v70
	v_lshlrev_b32_e32 v60, 16, v74
	v_and_b32_e32 v61, 0xffff0000, v74
	v_lshlrev_b32_e32 v62, 16, v75
	v_and_b32_e32 v63, 0xffff0000, v75
	v_pk_fma_f32 v[46:47], v[46:47], v[110:111], v[62:63]
	v_pk_fma_f32 v[44:45], v[44:45], v[108:109], v[60:61]
	global_store_dwordx4 v[68:69], v[44:47], off offset:528
	v_lshlrev_b32_e32 v70, 16, v71
	v_and_b32_e32 v71, 0xffff0000, v71
	v_lshlrev_b32_e32 v44, 16, v76
	v_and_b32_e32 v45, 0xffff0000, v76
	v_pk_fma_f32 v[44:45], v[48:49], v[120:121], v[44:45]
	v_lshlrev_b64 v[48:49], 13, v[98:99]
	v_lshlrev_b32_e32 v46, 16, v77
	v_and_b32_e32 v47, 0xffff0000, v77
	v_lshl_add_u64 v[48:49], s[66:67], 0, v[48:49]
	v_pk_fma_f32 v[58:59], v[58:59], v[118:119], v[70:71]
	v_pk_fma_f32 v[56:57], v[56:57], v[116:117], v[106:107]
	v_pk_fma_f32 v[46:47], v[50:51], v[122:123], v[46:47]
	v_lshl_add_u64 v[48:49], v[48:49], 0, v[174:175]
	global_store_dwordx4 v[68:69], v[56:59], off offset:16
	global_store_dwordx4 v[48:49], v[44:47], off
	s_nop 0
	v_lshlrev_b32_e32 v56, 16, v72
	v_and_b32_e32 v57, 0xffff0000, v72
	v_lshlrev_b32_e32 v58, 16, v73
	v_and_b32_e32 v59, 0xffff0000, v73
	v_lshlrev_b32_e32 v44, 16, v82
	v_and_b32_e32 v45, 0xffff0000, v82
	v_lshlrev_b32_e32 v46, 16, v83
	v_and_b32_e32 v47, 0xffff0000, v83
	v_pk_fma_f32 v[54:55], v[54:55], v[114:115], v[58:59]
	v_pk_fma_f32 v[52:53], v[52:53], v[112:113], v[56:57]
	v_pk_fma_f32 v[30:31], v[30:31], v[110:111], v[46:47]
	v_pk_fma_f32 v[28:29], v[28:29], v[108:109], v[44:45]
	global_store_dwordx4 v[68:69], v[52:55], off offset:512
	global_store_dwordx4 v[48:49], v[28:31], off offset:528
	s_nop 0
	v_lshlrev_b32_e32 v52, 16, v78
	v_and_b32_e32 v53, 0xffff0000, v78
	v_lshlrev_b32_e32 v54, 16, v79
	v_and_b32_e32 v55, 0xffff0000, v79
	v_lshlrev_b32_e32 v28, 16, v84
	v_and_b32_e32 v29, 0xffff0000, v84
	v_pk_fma_f32 v[42:43], v[42:43], v[118:119], v[54:55]
	v_pk_fma_f32 v[40:41], v[40:41], v[116:117], v[52:53]
	v_pk_fma_f32 v[28:29], v[32:33], v[120:121], v[28:29]
	v_lshlrev_b64 v[32:33], 13, v[100:101]
	global_store_dwordx4 v[48:49], v[40:43], off offset:16
	v_lshlrev_b32_e32 v30, 16, v85
	v_and_b32_e32 v31, 0xffff0000, v85
	v_lshlrev_b32_e32 v40, 16, v80
	v_and_b32_e32 v41, 0xffff0000, v80
	v_lshlrev_b32_e32 v42, 16, v81
	v_and_b32_e32 v43, 0xffff0000, v81
	v_lshl_add_u64 v[32:33], s[66:67], 0, v[32:33]
	v_pk_fma_f32 v[38:39], v[38:39], v[114:115], v[42:43]
	v_pk_fma_f32 v[36:37], v[36:37], v[112:113], v[40:41]
	v_pk_fma_f32 v[30:31], v[34:35], v[122:123], v[30:31]
	v_lshl_add_u64 v[32:33], v[32:33], 0, v[174:175]
	global_store_dwordx4 v[48:49], v[36:39], off offset:512
	global_store_dwordx4 v[32:33], v[28:31], off
	s_nop 0
	v_lshlrev_b32_e32 v36, 16, v86
	v_and_b32_e32 v37, 0xffff0000, v86
	v_lshlrev_b32_e32 v38, 16, v87
	v_and_b32_e32 v39, 0xffff0000, v87
	v_lshlrev_b32_e32 v28, 16, v90
	v_and_b32_e32 v29, 0xffff0000, v90
	v_lshlrev_b32_e32 v30, 16, v91
	v_and_b32_e32 v31, 0xffff0000, v91
	v_pk_fma_f32 v[26:27], v[26:27], v[118:119], v[38:39]
	v_pk_fma_f32 v[24:25], v[24:25], v[116:117], v[36:37]
	v_pk_fma_f32 v[14:15], v[14:15], v[110:111], v[30:31]
	v_pk_fma_f32 v[12:13], v[12:13], v[108:109], v[28:29]
	global_store_dwordx4 v[32:33], v[24:27], off offset:16
	global_store_dwordx4 v[32:33], v[12:15], off offset:528
	s_nop 0
	v_lshlrev_b32_e32 v24, 16, v88
	v_and_b32_e32 v25, 0xffff0000, v88
	v_lshlrev_b32_e32 v26, 16, v89
	v_and_b32_e32 v27, 0xffff0000, v89
	v_lshlrev_b32_e32 v12, 16, v92
	v_and_b32_e32 v13, 0xffff0000, v92
	v_pk_fma_f32 v[22:23], v[22:23], v[114:115], v[26:27]
	v_pk_fma_f32 v[20:21], v[20:21], v[112:113], v[24:25]
	v_pk_fma_f32 v[12:13], v[16:17], v[120:121], v[12:13]
	v_lshlrev_b64 v[16:17], 13, v[102:103]
	global_store_dwordx4 v[32:33], v[20:23], off offset:512
	v_lshlrev_b32_e32 v14, 16, v93
	v_and_b32_e32 v15, 0xffff0000, v93
	v_lshlrev_b32_e32 v20, 16, v94
	v_and_b32_e32 v21, 0xffff0000, v94
	v_lshlrev_b32_e32 v22, 16, v95
	v_and_b32_e32 v23, 0xffff0000, v95
	v_lshl_add_u64 v[16:17], s[66:67], 0, v[16:17]
	v_pk_fma_f32 v[14:15], v[18:19], v[122:123], v[14:15]
	v_lshl_add_u64 v[16:17], v[16:17], 0, v[174:175]
	v_pk_fma_f32 v[10:11], v[10:11], v[118:119], v[22:23]
	v_pk_fma_f32 v[8:9], v[8:9], v[116:117], v[20:21]
	global_store_dwordx4 v[16:17], v[12:15], off
	global_store_dwordx4 v[16:17], v[8:11], off offset:16
	s_nop 0
	v_lshlrev_b32_e32 v12, 16, v66
	v_lshlrev_b32_e32 v8, 16, v64
	v_and_b32_e32 v9, 0xffff0000, v64
	v_lshlrev_b32_e32 v10, 16, v65
	v_and_b32_e32 v11, 0xffff0000, v65
	v_and_b32_e32 v13, 0xffff0000, v66
	v_lshlrev_b32_e32 v14, 16, v67
	v_and_b32_e32 v15, 0xffff0000, v67
	v_pk_fma_f32 v[6:7], v[6:7], v[114:115], v[10:11]
	v_pk_fma_f32 v[4:5], v[4:5], v[112:113], v[8:9]
	v_pk_fma_f32 v[2:3], v[2:3], v[110:111], v[14:15]
	v_pk_fma_f32 v[0:1], v[0:1], v[108:109], v[12:13]
	global_store_dwordx4 v[16:17], v[4:7], off offset:512
	global_store_dwordx4 v[16:17], v[0:3], off offset:528
	s_cbranch_vccz .LBB0_261
	s_waitcnt vmcnt(0)
	s_cmpk_gt_u32 s16, 0xff
	s_cbranch_scc1 .LBB0_276
	s_barrier

.LBB0_294:
	s_add_u32 s16, s14, 0xfff80080
	s_addc_u32 s17, s15, -1
	s_add_i32 s43, 0, 0x10000
	v_add_u32_e32 v76, s43, v159
	ds_read_b128 v[64:67], v76
	ds_read_b128 v[68:71], v76 offset:1024
	ds_read_b128 v[72:75], v76 offset:2048
	ds_read_b128 v[76:79], v76 offset:3072
	s_cmp_eq_u32 s42, 28
	s_cselect_b32 s19, s7, s17
	s_cselect_b32 s18, s38, s16
	s_cselect_b32 s17, s5, s41
	s_cselect_b32 s16, s39, s40
	v_lshl_add_u64 v[190:191], s[14:15], 0, v[150:151]
	s_add_i32 m0, s13, 0xc000
	ds_read_b128 v[154:157], v161
	ds_read_b128 v[162:165], v161 offset:1024
	ds_read_b128 v[166:169], v161 offset:2048
	ds_read_b128 v[170:173], v161 offset:3072
	ds_read_b128 v[174:177], v161 offset:4096
	ds_read_b128 v[178:181], v161 offset:5120
	ds_read_b128 v[182:185], v161 offset:6144
	ds_read_b128 v[186:189], v161 offset:7168
	global_load_lds_dwordx4 v[190:191], off
	v_lshl_add_u64 v[190:191], s[14:15], 0, v[152:153]
	s_add_i32 m0, s13, 0xe000
	s_nop 0
	global_load_lds_dwordx4 v[190:191], off
	s_waitcnt lgkmcnt(8)
	s_barrier
	s_waitcnt lgkmcnt(0)
	s_waitcnt lgkmcnt(0)
	v_mfma_f32_16x16x32_bf16 v[140:143], v[64:67], v[154:157], v[140:143]
	v_mfma_f32_16x16x32_bf16 v[136:139], v[72:75], v[154:157], v[136:139]
	v_mfma_f32_16x16x32_bf16 v[132:135], v[64:67], v[166:169], v[132:135]
	v_mfma_f32_16x16x32_bf16 v[128:131], v[72:75], v[166:169], v[128:131]
	v_mfma_f32_16x16x32_bf16 v[108:111], v[64:67], v[174:177], v[108:111]
	v_mfma_f32_16x16x32_bf16 v[104:107], v[72:75], v[174:177], v[104:107]
	v_mfma_f32_16x16x32_bf16 v[100:103], v[64:67], v[182:185], v[100:103]
	v_mfma_f32_16x16x32_bf16 v[96:99], v[72:75], v[182:185], v[96:99]
	v_mfma_f32_16x16x32_bf16 v[140:143], v[68:71], v[162:165], v[140:143]
	v_mfma_f32_16x16x32_bf16 v[136:139], v[76:79], v[162:165], v[136:139]
	v_mfma_f32_16x16x32_bf16 v[132:135], v[68:71], v[170:173], v[132:135]
	v_mfma_f32_16x16x32_bf16 v[128:131], v[76:79], v[170:173], v[128:131]
	v_mfma_f32_16x16x32_bf16 v[108:111], v[68:71], v[178:181], v[108:111]
	v_mfma_f32_16x16x32_bf16 v[104:107], v[76:79], v[178:181], v[104:107]
	v_mfma_f32_16x16x32_bf16 v[100:103], v[68:71], v[186:189], v[100:103]
	v_mfma_f32_16x16x32_bf16 v[96:99], v[76:79], v[186:189], v[96:99]
	s_barrier
	s_add_i32 s46, 0, 0x14000
	v_add_u32_e32 v190, s46, v159
	s_add_i32 s43, s43, s27
	ds_read_b128 v[196:199], v190
	ds_read_b128 v[204:207], v190 offset:1024
	ds_read_b128 v[208:211], v190 offset:2048
	ds_read_b128 v[214:217], v190 offset:3072
	v_lshl_add_u64 v[190:191], s[16:17], 0, v[192:193]
	s_mov_b32 m0, s43
	v_lshl_add_u64 v[218:219], s[16:17], 0, v[148:149]
	global_load_lds_dwordx4 v[190:191], off
	s_add_i32 m0, s43, 0x2000
	s_nop 0
	global_load_lds_dwordx4 v[218:219], off
	s_barrier
	s_waitcnt lgkmcnt(0)
	s_waitcnt lgkmcnt(0)
	v_mfma_f32_16x16x32_bf16 v[124:127], v[196:199], v[154:157], v[124:127]
	v_mfma_f32_16x16x32_bf16 v[120:123], v[208:211], v[154:157], v[120:123]
	v_mfma_f32_16x16x32_bf16 v[116:119], v[196:199], v[166:169], v[116:119]
	v_mfma_f32_16x16x32_bf16 v[112:115], v[208:211], v[166:169], v[112:115]
	v_mfma_f32_16x16x32_bf16 v[92:95], v[196:199], v[174:177], v[92:95]
	v_mfma_f32_16x16x32_bf16 v[88:91], v[208:211], v[174:177], v[88:91]
	v_mfma_f32_16x16x32_bf16 v[84:87], v[196:199], v[182:185], v[84:87]
	v_mfma_f32_16x16x32_bf16 v[80:83], v[208:211], v[182:185], v[80:83]
	v_mfma_f32_16x16x32_bf16 v[124:127], v[204:207], v[162:165], v[124:127]
	v_mfma_f32_16x16x32_bf16 v[120:123], v[214:217], v[162:165], v[120:123]
	v_mfma_f32_16x16x32_bf16 v[116:119], v[204:207], v[170:173], v[116:119]
	v_mfma_f32_16x16x32_bf16 v[112:115], v[214:217], v[170:173], v[112:115]
	v_mfma_f32_16x16x32_bf16 v[92:95], v[204:207], v[178:181], v[92:95]
	v_mfma_f32_16x16x32_bf16 v[88:91], v[214:217], v[178:181], v[88:91]
	v_mfma_f32_16x16x32_bf16 v[84:87], v[204:207], v[186:189], v[84:87]
	v_mfma_f32_16x16x32_bf16 v[80:83], v[214:217], v[186:189], v[80:83]
	s_mov_b32 m0, s13
	v_lshl_add_u64 v[220:221], s[18:19], 0, v[144:145]
	s_barrier
	ds_read_b128 v[154:157], v161 offset:16384
	ds_read_b128 v[162:165], v161 offset:17408
	ds_read_b128 v[166:169], v161 offset:18432
	ds_read_b128 v[170:173], v161 offset:19456
	ds_read_b128 v[174:177], v161 offset:20480
	ds_read_b128 v[178:181], v161 offset:21504
	ds_read_b128 v[182:185], v161 offset:22528
	ds_read_b128 v[186:189], v161 offset:23552
	global_load_lds_dwordx4 v[220:221], off
	v_lshl_add_u64 v[222:223], s[18:19], 0, v[146:147]
	s_mov_b32 m0, s28
	s_nop 0
	global_load_lds_dwordx4 v[222:223], off
	s_barrier
	s_waitcnt lgkmcnt(0)
	s_waitcnt lgkmcnt(0)
	v_mfma_f32_16x16x32_bf16 v[60:63], v[64:67], v[154:157], v[60:63]
	v_mfma_f32_16x16x32_bf16 v[56:59], v[72:75], v[154:157], v[56:59]
	v_mfma_f32_16x16x32_bf16 v[52:55], v[64:67], v[166:169], v[52:55]
	v_mfma_f32_16x16x32_bf16 v[48:51], v[72:75], v[166:169], v[48:51]
	v_mfma_f32_16x16x32_bf16 v[28:31], v[64:67], v[174:177], v[28:31]
	v_mfma_f32_16x16x32_bf16 v[24:27], v[72:75], v[174:177], v[24:27]
	v_mfma_f32_16x16x32_bf16 v[20:23], v[64:67], v[182:185], v[20:23]
	v_mfma_f32_16x16x32_bf16 v[16:19], v[72:75], v[182:185], v[16:19]
	v_mfma_f32_16x16x32_bf16 v[60:63], v[68:71], v[162:165], v[60:63]
	v_mfma_f32_16x16x32_bf16 v[56:59], v[76:79], v[162:165], v[56:59]
	v_mfma_f32_16x16x32_bf16 v[52:55], v[68:71], v[170:173], v[52:55]
	v_mfma_f32_16x16x32_bf16 v[48:51], v[76:79], v[170:173], v[48:51]
	v_mfma_f32_16x16x32_bf16 v[28:31], v[68:71], v[178:181], v[28:31]
	v_mfma_f32_16x16x32_bf16 v[24:27], v[76:79], v[178:181], v[24:27]
	v_mfma_f32_16x16x32_bf16 v[20:23], v[68:71], v[186:189], v[20:23]
	v_mfma_f32_16x16x32_bf16 v[16:19], v[76:79], v[186:189], v[16:19]
	s_barrier
	s_add_u32 s44, s16, 0x80000
	s_addc_u32 s45, s17, 0
	s_add_i32 s43, s46, s27
	v_lshl_add_u64 v[64:65], s[44:45], 0, v[192:193]
	s_mov_b32 m0, s43
	s_nop 0
	global_load_lds_dwordx4 v[64:65], off
	v_lshl_add_u64 v[64:65], s[44:45], 0, v[148:149]
	s_add_i32 m0, s43, 0x2000
	s_nop 0
	global_load_lds_dwordx4 v[64:65], off
	s_waitcnt vmcnt(6)
	s_barrier
	v_mfma_f32_16x16x32_bf16 v[44:47], v[196:199], v[154:157], v[44:47]
	v_mfma_f32_16x16x32_bf16 v[40:43], v[208:211], v[154:157], v[40:43]
	v_mfma_f32_16x16x32_bf16 v[36:39], v[196:199], v[166:169], v[36:39]
	v_mfma_f32_16x16x32_bf16 v[32:35], v[208:211], v[166:169], v[32:35]
	v_mfma_f32_16x16x32_bf16 v[12:15], v[196:199], v[174:177], v[12:15]
	v_mfma_f32_16x16x32_bf16 v[8:11], v[208:211], v[174:177], v[8:11]
	v_mfma_f32_16x16x32_bf16 v[4:7], v[196:199], v[182:185], v[4:7]
	v_mfma_f32_16x16x32_bf16 v[0:3], v[208:211], v[182:185], v[0:3]
	v_mfma_f32_16x16x32_bf16 v[44:47], v[204:207], v[162:165], v[44:47]
	v_mfma_f32_16x16x32_bf16 v[40:43], v[214:217], v[162:165], v[40:43]
	v_mfma_f32_16x16x32_bf16 v[36:39], v[204:207], v[170:173], v[36:39]
	v_mfma_f32_16x16x32_bf16 v[32:35], v[214:217], v[170:173], v[32:35]
	v_mfma_f32_16x16x32_bf16 v[12:15], v[204:207], v[178:181], v[12:15]
	v_mfma_f32_16x16x32_bf16 v[8:11], v[214:217], v[178:181], v[8:11]
	v_mfma_f32_16x16x32_bf16 v[4:7], v[204:207], v[186:189], v[4:7]
	v_mfma_f32_16x16x32_bf16 v[0:3], v[214:217], v[186:189], v[0:3]
	s_add_i32 s43, 0, 0x18000
	v_add_u32_e32 v76, s43, v159
	s_barrier
	ds_read_b128 v[64:67], v76
	ds_read_b128 v[68:71], v76 offset:1024
	ds_read_b128 v[72:75], v76 offset:2048
	ds_read_b128 v[76:79], v76 offset:3072
	s_add_u32 s18, s18, 0x80000
	s_addc_u32 s19, s19, 0
	s_mov_b32 m0, s29
	v_lshl_add_u64 v[196:197], s[18:19], 0, v[144:145]
	ds_read_b128 v[154:157], v161 offset:32768
	ds_read_b128 v[162:165], v161 offset:33792
	ds_read_b128 v[166:169], v161 offset:34816
	ds_read_b128 v[170:173], v161 offset:35840
	ds_read_b128 v[174:177], v161 offset:36864
	ds_read_b128 v[178:181], v161 offset:37888
	ds_read_b128 v[182:185], v161 offset:38912
	ds_read_b128 v[186:189], v161 offset:39936
	global_load_lds_dwordx4 v[196:197], off
	v_lshl_add_u64 v[196:197], s[18:19], 0, v[146:147]
	s_mov_b32 m0, s30
	s_nop 0
	global_load_lds_dwordx4 v[196:197], off
	s_waitcnt lgkmcnt(8)
	s_barrier
	s_waitcnt lgkmcnt(0)
	s_waitcnt lgkmcnt(0)
	v_mfma_f32_16x16x32_bf16 v[140:143], v[64:67], v[154:157], v[140:143]
	v_mfma_f32_16x16x32_bf16 v[136:139], v[72:75], v[154:157], v[136:139]
	v_mfma_f32_16x16x32_bf16 v[132:135], v[64:67], v[166:169], v[132:135]
	v_mfma_f32_16x16x32_bf16 v[128:131], v[72:75], v[166:169], v[128:131]
	v_mfma_f32_16x16x32_bf16 v[108:111], v[64:67], v[174:177], v[108:111]
	v_mfma_f32_16x16x32_bf16 v[104:107], v[72:75], v[174:177], v[104:107]
	v_mfma_f32_16x16x32_bf16 v[100:103], v[64:67], v[182:185], v[100:103]
	v_mfma_f32_16x16x32_bf16 v[96:99], v[72:75], v[182:185], v[96:99]
	v_mfma_f32_16x16x32_bf16 v[140:143], v[68:71], v[162:165], v[140:143]
	v_mfma_f32_16x16x32_bf16 v[136:139], v[76:79], v[162:165], v[136:139]
	v_mfma_f32_16x16x32_bf16 v[132:135], v[68:71], v[170:173], v[132:135]
	v_mfma_f32_16x16x32_bf16 v[128:131], v[76:79], v[170:173], v[128:131]
	v_mfma_f32_16x16x32_bf16 v[108:111], v[68:71], v[178:181], v[108:111]
	v_mfma_f32_16x16x32_bf16 v[104:107], v[76:79], v[178:181], v[104:107]
	v_mfma_f32_16x16x32_bf16 v[100:103], v[68:71], v[186:189], v[100:103]
	v_mfma_f32_16x16x32_bf16 v[96:99], v[76:79], v[186:189], v[96:99]
	s_barrier
	s_add_i32 s18, 0, 0x1c000
	s_add_i32 s19, s43, s27
	v_add_u32_e32 v212, s18, v159
	v_lshl_add_u64 v[190:191], v[190:191], 0, s[48:49]
	s_mov_b32 m0, s19
	ds_read_b128 v[196:199], v212
	ds_read_b128 v[204:207], v212 offset:1024
	ds_read_b128 v[208:211], v212 offset:2048
	ds_read_b128 v[214:217], v212 offset:3072
	global_load_lds_dwordx4 v[190:191], off
	v_lshl_add_u64 v[190:191], v[218:219], 0, s[48:49]
	s_add_i32 m0, s19, 0x2000
	s_nop 0
	global_load_lds_dwordx4 v[190:191], off
	s_barrier
	s_waitcnt lgkmcnt(0)
	s_waitcnt lgkmcnt(0)
	v_mfma_f32_16x16x32_bf16 v[124:127], v[196:199], v[154:157], v[124:127]
	v_mfma_f32_16x16x32_bf16 v[120:123], v[208:211], v[154:157], v[120:123]
	v_mfma_f32_16x16x32_bf16 v[116:119], v[196:199], v[166:169], v[116:119]
	v_mfma_f32_16x16x32_bf16 v[112:115], v[208:211], v[166:169], v[112:115]
	v_mfma_f32_16x16x32_bf16 v[92:95], v[196:199], v[174:177], v[92:95]
	v_mfma_f32_16x16x32_bf16 v[88:91], v[208:211], v[174:177], v[88:91]
	v_mfma_f32_16x16x32_bf16 v[84:87], v[196:199], v[182:185], v[84:87]
	v_mfma_f32_16x16x32_bf16 v[80:83], v[208:211], v[182:185], v[80:83]
	v_mfma_f32_16x16x32_bf16 v[124:127], v[204:207], v[162:165], v[124:127]
	v_mfma_f32_16x16x32_bf16 v[120:123], v[214:217], v[162:165], v[120:123]
	v_mfma_f32_16x16x32_bf16 v[116:119], v[204:207], v[170:173], v[116:119]
	v_mfma_f32_16x16x32_bf16 v[112:115], v[214:217], v[170:173], v[112:115]
	v_mfma_f32_16x16x32_bf16 v[92:95], v[204:207], v[178:181], v[92:95]
	v_mfma_f32_16x16x32_bf16 v[88:91], v[214:217], v[178:181], v[88:91]
	v_mfma_f32_16x16x32_bf16 v[84:87], v[204:207], v[186:189], v[84:87]
	v_mfma_f32_16x16x32_bf16 v[80:83], v[214:217], v[186:189], v[80:83]
	s_mov_b32 m0, s34
	v_lshl_add_u64 v[190:191], v[220:221], 0, s[48:49]
	s_barrier
	ds_read_b128 v[154:157], v161 offset:49152
	ds_read_b128 v[162:165], v161 offset:50176
	ds_read_b128 v[166:169], v161 offset:51200
	ds_read_b128 v[170:173], v161 offset:52224
	ds_read_b128 v[174:177], v161 offset:53248
	ds_read_b128 v[178:181], v161 offset:54272
	ds_read_b128 v[182:185], v161 offset:55296
	ds_read_b128 v[186:189], v161 offset:56320
	global_load_lds_dwordx4 v[190:191], off
	v_lshl_add_u64 v[190:191], v[222:223], 0, s[48:49]
	s_mov_b32 m0, s35
	s_nop 0
	global_load_lds_dwordx4 v[190:191], off
	s_barrier
	s_waitcnt lgkmcnt(0)
	s_waitcnt lgkmcnt(0)
	v_mfma_f32_16x16x32_bf16 v[60:63], v[64:67], v[154:157], v[60:63]
	v_mfma_f32_16x16x32_bf16 v[56:59], v[72:75], v[154:157], v[56:59]
	v_mfma_f32_16x16x32_bf16 v[52:55], v[64:67], v[166:169], v[52:55]
	v_mfma_f32_16x16x32_bf16 v[48:51], v[72:75], v[166:169], v[48:51]
	v_mfma_f32_16x16x32_bf16 v[28:31], v[64:67], v[174:177], v[28:31]
	v_mfma_f32_16x16x32_bf16 v[24:27], v[72:75], v[174:177], v[24:27]
	v_mfma_f32_16x16x32_bf16 v[20:23], v[64:67], v[182:185], v[20:23]
	v_mfma_f32_16x16x32_bf16 v[16:19], v[72:75], v[182:185], v[16:19]
	v_mfma_f32_16x16x32_bf16 v[60:63], v[68:71], v[162:165], v[60:63]
	v_mfma_f32_16x16x32_bf16 v[56:59], v[76:79], v[162:165], v[56:59]
	v_mfma_f32_16x16x32_bf16 v[52:55], v[68:71], v[170:173], v[52:55]
	v_mfma_f32_16x16x32_bf16 v[48:51], v[76:79], v[170:173], v[48:51]
	v_mfma_f32_16x16x32_bf16 v[28:31], v[68:71], v[178:181], v[28:31]
	v_mfma_f32_16x16x32_bf16 v[24:27], v[76:79], v[178:181], v[24:27]
	v_mfma_f32_16x16x32_bf16 v[20:23], v[68:71], v[186:189], v[20:23]
	v_mfma_f32_16x16x32_bf16 v[16:19], v[76:79], v[186:189], v[16:19]
	s_barrier
	s_add_u32 s16, s16, 0x80080
	s_addc_u32 s17, s17, 0
	s_add_i32 s18, s18, s27
	v_lshl_add_u64 v[64:65], s[16:17], 0, v[192:193]
	s_mov_b32 m0, s18
	s_nop 0
	global_load_lds_dwordx4 v[64:65], off
	v_lshl_add_u64 v[64:65], s[16:17], 0, v[148:149]
	s_add_i32 m0, s18, 0x2000
	s_nop 0
	global_load_lds_dwordx4 v[64:65], off
	s_waitcnt vmcnt(6)
	s_barrier
	v_mfma_f32_16x16x32_bf16 v[44:47], v[196:199], v[154:157], v[44:47]
	v_mfma_f32_16x16x32_bf16 v[40:43], v[208:211], v[154:157], v[40:43]
	v_mfma_f32_16x16x32_bf16 v[36:39], v[196:199], v[166:169], v[36:39]
	v_mfma_f32_16x16x32_bf16 v[32:35], v[208:211], v[166:169], v[32:35]
	v_mfma_f32_16x16x32_bf16 v[12:15], v[196:199], v[174:177], v[12:15]
	v_mfma_f32_16x16x32_bf16 v[8:11], v[208:211], v[174:177], v[8:11]
	v_mfma_f32_16x16x32_bf16 v[4:7], v[196:199], v[182:185], v[4:7]
	v_mfma_f32_16x16x32_bf16 v[0:3], v[208:211], v[182:185], v[0:3]
	v_mfma_f32_16x16x32_bf16 v[44:47], v[204:207], v[162:165], v[44:47]
	v_mfma_f32_16x16x32_bf16 v[40:43], v[214:217], v[162:165], v[40:43]
	v_mfma_f32_16x16x32_bf16 v[36:39], v[204:207], v[170:173], v[36:39]
	v_mfma_f32_16x16x32_bf16 v[32:35], v[214:217], v[170:173], v[32:35]
	v_mfma_f32_16x16x32_bf16 v[12:15], v[204:207], v[178:181], v[12:15]
	v_mfma_f32_16x16x32_bf16 v[8:11], v[214:217], v[178:181], v[8:11]
	v_mfma_f32_16x16x32_bf16 v[4:7], v[204:207], v[186:189], v[4:7]
	v_mfma_f32_16x16x32_bf16 v[0:3], v[214:217], v[186:189], v[0:3]
	s_add_i32 s42, s42, 2
	s_add_u32 s14, s14, 0x100
	s_addc_u32 s15, s15, 0
	s_add_u32 s40, s40, 0x100
	s_addc_u32 s41, s41, 0
	s_cmp_gt_u32 s42, 29
	s_barrier
	s_cbranch_scc0 .LBB0_294
	s_ashr_i32 s5, s12, 4
	v_lshl_or_b32 v190, s37, 8, v160
	s_mul_hi_i32 s7, s5, 0xc000
	s_mul_i32 s5, s5, 0xc000
	s_add_u32 s14, s31, s5
	v_ashrrev_i32_e32 v191, 31, v190
	v_lshl_add_u32 v154, s12, 8, v158
	v_readlane_b32 s52, v254, 23
	s_addc_u32 s15, s33, s7
	v_lshlrev_b64 v[156:157], 2, v[190:191]
	v_readlane_b32 s53, v254, 24
	v_ashrrev_i32_e32 v155, 31, v154
	v_lshl_add_u64 v[68:69], s[14:15], 0, v[156:157]
	v_lshl_add_u64 v[156:157], s[52:53], 0, v[156:157]
	v_lshlrev_b64 v[162:163], 13, v[154:155]
	v_lshl_add_u64 v[174:175], v[156:157], 0, v[162:163]
	global_load_dwordx4 v[72:75], v[68:69], off offset:16
	global_load_dwordx4 v[76:79], v[68:69], off
	global_load_dwordx4 v[64:67], v[68:69], off offset:528
	s_nop 0
	global_load_dwordx4 v[68:71], v[68:69], off offset:512
	s_nop 0
	global_load_dwordx4 v[162:165], v[174:175], off offset:16
	global_load_dwordx4 v[166:169], v[174:175], off
	global_load_dwordx4 v[170:173], v[174:175], off offset:528
	s_nop 0
	global_load_dwordx4 v[174:177], v[174:175], off offset:512
	v_or_b32_e32 v204, 16, v154
	v_ashrrev_i32_e32 v205, 31, v204
	v_lshlrev_b64 v[178:179], 13, v[204:205]
	v_lshl_add_u64 v[196:197], v[156:157], 0, v[178:179]
	global_load_dwordx4 v[178:181], v[196:197], off offset:16
	global_load_dwordx4 v[182:185], v[196:197], off
	global_load_dwordx4 v[186:189], v[196:197], off offset:528
	s_nop 0
	global_load_dwordx4 v[196:199], v[196:197], off offset:512
	v_lshlrev_b64 v[206:207], 12, v[154:155]
	s_and_b64 vcc, exec, s[0:1]
	s_mov_b32 s37, s4
	s_mov_b32 s12, s6
	s_mov_b64 s[16:17], s[10:11]
	s_mov_b64 s[14:15], s[8:9]
	s_mov_b32 s11, 0xc000
	v_readlane_b32 s54, v254, 25
	v_readlane_b32 s55, v254, 26
	v_readlane_b32 s56, v254, 27
	v_readlane_b32 s57, v254, 28
	v_readlane_b32 s58, v254, 29
	v_readlane_b32 s59, v254, 30
	v_readlane_b32 s60, v254, 31
	v_readlane_b32 s61, v254, 32
	v_readlane_b32 s62, v254, 33
	v_readlane_b32 s63, v254, 34
	v_readlane_b32 s64, v254, 35
	v_readlane_b32 s65, v254, 36
	v_readlane_b32 s66, v254, 37
	v_readlane_b32 s67, v254, 38
	s_waitcnt vmcnt(0)
	v_pk_fma_f32 v[136:137], v[136:137], v[72:73], v[162:163]
	v_pk_fma_f32 v[142:143], v[142:143], v[78:79], v[168:169]
	v_pk_fma_f32 v[140:141], v[140:141], v[76:77], v[166:167]
	v_pk_fma_f32 v[164:165], v[138:139], v[74:75], v[164:165]
	v_cvt_pk_bf16_f32 v138, v140, v141
	v_cvt_pk_bf16_f32 v139, v142, v143
	v_cvt_pk_bf16_f32 v140, v136, v137
	v_lshl_add_u64 v[142:143], s[2:3], 0, v[206:207]
	v_lshlrev_b64 v[136:137], 1, v[190:191]
	v_lshl_add_u64 v[142:143], v[142:143], 0, v[136:137]
	v_pk_fma_f32 v[124:125], v[124:125], v[68:69], v[174:175]
	v_cvt_pk_bf16_f32 v141, v164, v165
	global_store_dwordx4 v[142:143], v[138:141], off
	v_pk_fma_f32 v[126:127], v[126:127], v[70:71], v[176:177]
	v_pk_fma_f32 v[128:129], v[128:129], v[72:73], v[178:179]
	v_pk_fma_f32 v[138:139], v[122:123], v[66:67], v[172:173]
	v_pk_fma_f32 v[122:123], v[120:121], v[64:65], v[170:171]
	v_cvt_pk_bf16_f32 v120, v124, v125
	v_cvt_pk_bf16_f32 v121, v126, v127
	v_lshlrev_b64 v[124:125], 12, v[204:205]
	v_cvt_pk_bf16_f32 v122, v122, v123
	v_cvt_pk_bf16_f32 v123, v138, v139
	global_store_dwordx4 v[142:143], v[120:123], off offset:256
	v_lshl_add_u64 v[124:125], s[2:3], 0, v[124:125]
	v_lshl_add_u64 v[124:125], v[124:125], 0, v[136:137]
	v_pk_fma_f32 v[120:121], v[132:133], v[76:77], v[182:183]
	v_pk_fma_f32 v[122:123], v[134:135], v[78:79], v[184:185]
	v_cvt_pk_bf16_f32 v120, v120, v121
	v_or_b32_e32 v142, 32, v154
	v_cvt_pk_bf16_f32 v121, v122, v123
	v_pk_fma_f32 v[126:127], v[130:131], v[74:75], v[180:181]
	v_cvt_pk_bf16_f32 v122, v128, v129
	v_pk_fma_f32 v[118:119], v[118:119], v[70:71], v[198:199]
	v_cvt_pk_bf16_f32 v123, v126, v127
	global_store_dwordx4 v[124:125], v[120:123], off
	v_pk_fma_f32 v[116:117], v[116:117], v[68:69], v[196:197]
	v_ashrrev_i32_e32 v143, 31, v142
	v_pk_fma_f32 v[120:121], v[114:115], v[66:67], v[188:189]
	v_pk_fma_f32 v[114:115], v[112:113], v[64:65], v[186:187]
	v_cvt_pk_bf16_f32 v112, v116, v117
	v_cvt_pk_bf16_f32 v113, v118, v119
	v_or_b32_e32 v166, 48, v154
	v_cvt_pk_bf16_f32 v114, v114, v115
	v_cvt_pk_bf16_f32 v115, v120, v121
	global_store_dwordx4 v[124:125], v[112:115], off offset:256
	v_ashrrev_i32_e32 v167, 31, v166
	v_lshlrev_b64 v[128:129], 13, v[166:167]
	v_lshlrev_b64 v[112:113], 13, v[142:143]
	v_lshl_add_u64 v[124:125], v[156:157], 0, v[112:113]
	global_load_dwordx4 v[112:115], v[124:125], off offset:16
	global_load_dwordx4 v[116:119], v[124:125], off
	global_load_dwordx4 v[120:123], v[124:125], off offset:528
	s_nop 0
	global_load_dwordx4 v[124:127], v[124:125], off offset:512
	v_lshl_add_u64 v[162:163], v[156:157], 0, v[128:129]
	global_load_dwordx4 v[128:131], v[162:163], off offset:16
	global_load_dwordx4 v[132:135], v[162:163], off
	global_load_dwordx4 v[138:141], v[162:163], off offset:528
	s_nop 0
	global_load_dwordx4 v[162:165], v[162:163], off offset:512
	v_lshlrev_b64 v[142:143], 12, v[142:143]
	s_waitcnt vmcnt(0)
	v_pk_fma_f32 v[114:115], v[106:107], v[74:75], v[114:115]
	v_pk_fma_f32 v[108:109], v[108:109], v[76:77], v[116:117]
	v_pk_fma_f32 v[106:107], v[104:105], v[72:73], v[112:113]
	v_cvt_pk_bf16_f32 v104, v108, v109
	v_lshl_add_u64 v[108:109], s[2:3], 0, v[142:143]
	v_pk_fma_f32 v[110:111], v[110:111], v[78:79], v[118:119]
	v_lshl_add_u64 v[108:109], v[108:109], 0, v[136:137]
	v_cvt_pk_bf16_f32 v105, v110, v111
	v_pk_fma_f32 v[92:93], v[92:93], v[68:69], v[124:125]
	v_cvt_pk_bf16_f32 v106, v106, v107
	v_cvt_pk_bf16_f32 v107, v114, v115
	global_store_dwordx4 v[108:109], v[104:107], off
	v_pk_fma_f32 v[94:95], v[94:95], v[70:71], v[126:127]
	v_add_u32_e32 v112, 0x80, v154
	v_pk_fma_f32 v[104:105], v[90:91], v[66:67], v[122:123]
	v_pk_fma_f32 v[90:91], v[88:89], v[64:65], v[120:121]
	v_cvt_pk_bf16_f32 v88, v92, v93
	v_cvt_pk_bf16_f32 v89, v94, v95
	v_lshlrev_b64 v[92:93], 12, v[166:167]
	v_cvt_pk_bf16_f32 v90, v90, v91
	v_cvt_pk_bf16_f32 v91, v104, v105
	global_store_dwordx4 v[108:109], v[88:91], off offset:256
	v_lshl_add_u64 v[92:93], s[2:3], 0, v[92:93]
	v_lshl_add_u64 v[92:93], v[92:93], 0, v[136:137]
	v_pk_fma_f32 v[88:89], v[100:101], v[76:77], v[132:133]
	v_pk_fma_f32 v[90:91], v[102:103], v[78:79], v[134:135]
	v_cvt_pk_bf16_f32 v88, v88, v89
	v_pk_fma_f32 v[94:95], v[98:99], v[74:75], v[130:131]
	v_cvt_pk_bf16_f32 v89, v90, v91
	v_pk_fma_f32 v[96:97], v[96:97], v[72:73], v[128:129]
	v_pk_fma_f32 v[86:87], v[86:87], v[70:71], v[164:165]
	v_cvt_pk_bf16_f32 v90, v96, v97
	v_cvt_pk_bf16_f32 v91, v94, v95
	global_store_dwordx4 v[92:93], v[88:91], off
	v_pk_fma_f32 v[84:85], v[84:85], v[68:69], v[162:163]
	v_ashrrev_i32_e32 v113, 31, v112
	v_pk_fma_f32 v[88:89], v[82:83], v[66:67], v[140:141]
	v_pk_fma_f32 v[82:83], v[80:81], v[64:65], v[138:139]
	v_cvt_pk_bf16_f32 v80, v84, v85
	v_cvt_pk_bf16_f32 v81, v86, v87
	v_add_u32_e32 v114, 0x90, v154
	v_cvt_pk_bf16_f32 v82, v82, v83
	v_cvt_pk_bf16_f32 v83, v88, v89
	global_store_dwordx4 v[92:93], v[80:83], off offset:256
	v_ashrrev_i32_e32 v115, 31, v114
	v_lshlrev_b64 v[96:97], 13, v[114:115]
	v_lshlrev_b64 v[80:81], 13, v[112:113]
	v_lshl_add_u64 v[92:93], v[156:157], 0, v[80:81]
	global_load_dwordx4 v[80:83], v[92:93], off offset:16
	global_load_dwordx4 v[84:87], v[92:93], off
	global_load_dwordx4 v[88:91], v[92:93], off offset:528
	s_nop 0
	global_load_dwordx4 v[92:95], v[92:93], off offset:512
	v_lshl_add_u64 v[108:109], v[156:157], 0, v[96:97]
	global_load_dwordx4 v[96:99], v[108:109], off offset:16
	global_load_dwordx4 v[100:103], v[108:109], off
	global_load_dwordx4 v[104:107], v[108:109], off offset:528
	s_nop 0
	global_load_dwordx4 v[108:111], v[108:109], off offset:512
	v_lshlrev_b64 v[112:113], 12, v[112:113]
	s_waitcnt vmcnt(0)
	v_pk_fma_f32 v[82:83], v[58:59], v[74:75], v[82:83]
	v_pk_fma_f32 v[60:61], v[60:61], v[76:77], v[84:85]
	v_pk_fma_f32 v[58:59], v[56:57], v[72:73], v[80:81]
	v_cvt_pk_bf16_f32 v56, v60, v61
	v_lshl_add_u64 v[60:61], s[2:3], 0, v[112:113]
	v_pk_fma_f32 v[62:63], v[62:63], v[78:79], v[86:87]
	v_lshl_add_u64 v[60:61], v[60:61], 0, v[136:137]
	v_cvt_pk_bf16_f32 v57, v62, v63
	v_pk_fma_f32 v[44:45], v[44:45], v[68:69], v[92:93]
	v_cvt_pk_bf16_f32 v58, v58, v59
	v_cvt_pk_bf16_f32 v59, v82, v83
	global_store_dwordx4 v[60:61], v[56:59], off
	v_pk_fma_f32 v[46:47], v[46:47], v[70:71], v[94:95]
	v_add_u32_e32 v80, 0xa0, v154
	v_pk_fma_f32 v[56:57], v[42:43], v[66:67], v[90:91]
	v_pk_fma_f32 v[42:43], v[40:41], v[64:65], v[88:89]
	v_cvt_pk_bf16_f32 v40, v44, v45
	v_cvt_pk_bf16_f32 v41, v46, v47
	v_lshlrev_b64 v[44:45], 12, v[114:115]
	v_cvt_pk_bf16_f32 v42, v42, v43
	v_cvt_pk_bf16_f32 v43, v56, v57
	global_store_dwordx4 v[60:61], v[40:43], off offset:256
	v_lshl_add_u64 v[44:45], s[2:3], 0, v[44:45]
	v_lshl_add_u64 v[44:45], v[44:45], 0, v[136:137]
	v_pk_fma_f32 v[40:41], v[52:53], v[76:77], v[100:101]
	v_pk_fma_f32 v[42:43], v[54:55], v[78:79], v[102:103]
	v_cvt_pk_bf16_f32 v40, v40, v41
	v_pk_fma_f32 v[46:47], v[50:51], v[74:75], v[98:99]
	v_cvt_pk_bf16_f32 v41, v42, v43
	v_pk_fma_f32 v[48:49], v[48:49], v[72:73], v[96:97]
	v_pk_fma_f32 v[38:39], v[38:39], v[70:71], v[110:111]
	v_cvt_pk_bf16_f32 v42, v48, v49
	v_cvt_pk_bf16_f32 v43, v46, v47
	global_store_dwordx4 v[44:45], v[40:43], off
	v_pk_fma_f32 v[36:37], v[36:37], v[68:69], v[108:109]
	v_ashrrev_i32_e32 v81, 31, v80
	v_pk_fma_f32 v[40:41], v[34:35], v[66:67], v[106:107]
	v_pk_fma_f32 v[34:35], v[32:33], v[64:65], v[104:105]
	v_cvt_pk_bf16_f32 v32, v36, v37
	v_cvt_pk_bf16_f32 v33, v38, v39
	v_add_u32_e32 v82, 0xb0, v154
	v_cvt_pk_bf16_f32 v34, v34, v35
	v_cvt_pk_bf16_f32 v35, v40, v41
	global_store_dwordx4 v[44:45], v[32:35], off offset:256
	v_ashrrev_i32_e32 v83, 31, v82
	v_lshlrev_b64 v[48:49], 13, v[82:83]
	v_lshlrev_b64 v[32:33], 13, v[80:81]
	v_lshl_add_u64 v[44:45], v[156:157], 0, v[32:33]
	global_load_dwordx4 v[32:35], v[44:45], off offset:16
	global_load_dwordx4 v[36:39], v[44:45], off
	global_load_dwordx4 v[40:43], v[44:45], off offset:528
	s_nop 0
	global_load_dwordx4 v[44:47], v[44:45], off offset:512
	v_lshl_add_u64 v[60:61], v[156:157], 0, v[48:49]
	global_load_dwordx4 v[48:51], v[60:61], off offset:16
	global_load_dwordx4 v[52:55], v[60:61], off
	global_load_dwordx4 v[56:59], v[60:61], off offset:528
	s_nop 0
	global_load_dwordx4 v[60:63], v[60:61], off offset:512
	v_lshlrev_b64 v[80:81], 12, v[80:81]
	s_waitcnt vmcnt(0)
	v_pk_fma_f32 v[34:35], v[26:27], v[74:75], v[34:35]
	v_pk_fma_f32 v[28:29], v[28:29], v[76:77], v[36:37]
	v_pk_fma_f32 v[26:27], v[24:25], v[72:73], v[32:33]
	v_cvt_pk_bf16_f32 v24, v28, v29
	v_lshl_add_u64 v[28:29], s[2:3], 0, v[80:81]
	v_pk_fma_f32 v[30:31], v[30:31], v[78:79], v[38:39]
	v_lshl_add_u64 v[28:29], v[28:29], 0, v[136:137]
	v_cvt_pk_bf16_f32 v25, v30, v31
	v_pk_fma_f32 v[12:13], v[12:13], v[68:69], v[44:45]
	v_cvt_pk_bf16_f32 v26, v26, v27
	v_cvt_pk_bf16_f32 v27, v34, v35
	global_store_dwordx4 v[28:29], v[24:27], off
	v_pk_fma_f32 v[14:15], v[14:15], v[70:71], v[46:47]
	v_pk_fma_f32 v[16:17], v[16:17], v[72:73], v[48:49]
	v_pk_fma_f32 v[24:25], v[10:11], v[66:67], v[42:43]
	v_pk_fma_f32 v[10:11], v[8:9], v[64:65], v[40:41]
	v_cvt_pk_bf16_f32 v8, v12, v13
	v_cvt_pk_bf16_f32 v9, v14, v15
	v_lshlrev_b64 v[12:13], 12, v[82:83]
	v_cvt_pk_bf16_f32 v10, v10, v11
	v_cvt_pk_bf16_f32 v11, v24, v25
	global_store_dwordx4 v[28:29], v[8:11], off offset:256
	v_lshl_add_u64 v[12:13], s[2:3], 0, v[12:13]
	v_lshl_add_u64 v[12:13], v[12:13], 0, v[136:137]
	v_pk_fma_f32 v[8:9], v[20:21], v[76:77], v[52:53]
	v_pk_fma_f32 v[10:11], v[22:23], v[78:79], v[54:55]
	v_cvt_pk_bf16_f32 v8, v8, v9
	v_pk_fma_f32 v[14:15], v[18:19], v[74:75], v[50:51]
	v_cvt_pk_bf16_f32 v9, v10, v11
	v_cvt_pk_bf16_f32 v10, v16, v17
	v_pk_fma_f32 v[6:7], v[6:7], v[70:71], v[62:63]
	v_cvt_pk_bf16_f32 v11, v14, v15
	global_store_dwordx4 v[12:13], v[8:11], off
	v_pk_fma_f32 v[4:5], v[4:5], v[68:69], v[60:61]
	s_nop 0
	v_pk_fma_f32 v[8:9], v[2:3], v[66:67], v[58:59]
	v_pk_fma_f32 v[2:3], v[0:1], v[64:65], v[56:57]
	v_cvt_pk_bf16_f32 v0, v4, v5
	v_cvt_pk_bf16_f32 v1, v6, v7
	s_nop 0
	v_cvt_pk_bf16_f32 v2, v2, v3
	v_cvt_pk_bf16_f32 v3, v8, v9
	global_store_dwordx4 v[12:13], v[0:3], off offset:256
	s_cbranch_vccz .LBB0_287
	s_waitcnt vmcnt(0)
	s_cmpk_gt_u32 s25, 0xff
	s_cbranch_scc1 .LBB0_298
	s_barrier

.LBB0_415:
	s_add_u32 s18, s16, 0xfff80080
	s_addc_u32 s19, s17, -1
	s_add_i32 s43, 0, 0x10000
	v_add_u32_e32 v140, s43, v143
	ds_read_b128 v[146:149], v140
	ds_read_b128 v[150:153], v140 offset:1024
	ds_read_b128 v[154:157], v140 offset:2048
	ds_read_b128 v[158:161], v140 offset:3072
	s_cmp_eq_u32 s42, 28
	s_cselect_b32 s21, s9, s19
	s_cselect_b32 s20, s38, s18
	s_cselect_b32 s19, s7, s41
	s_cselect_b32 s18, s39, s40
	v_lshl_add_u64 v[140:141], s[16:17], 0, v[136:137]
	s_add_i32 m0, s30, 0xc000
	ds_read_b128 v[162:165], v145
	ds_read_b128 v[166:169], v145 offset:1024
	ds_read_b128 v[170:173], v145 offset:2048
	ds_read_b128 v[174:177], v145 offset:3072
	ds_read_b128 v[178:181], v145 offset:4096
	ds_read_b128 v[182:185], v145 offset:5120
	ds_read_b128 v[186:189], v145 offset:6144
	ds_read_b128 v[204:207], v145 offset:7168
	global_load_lds_dwordx4 v[140:141], off
	v_lshl_add_u64 v[140:141], s[16:17], 0, v[138:139]
	s_add_i32 m0, s30, 0xe000
	s_nop 0
	global_load_lds_dwordx4 v[140:141], off
	s_waitcnt lgkmcnt(8)
	s_barrier
	s_waitcnt lgkmcnt(0)
	s_waitcnt lgkmcnt(0)
	v_mfma_f32_16x16x32_bf16 v[124:127], v[146:149], v[162:165], v[124:127]
	v_mfma_f32_16x16x32_bf16 v[120:123], v[154:157], v[162:165], v[120:123]
	v_mfma_f32_16x16x32_bf16 v[116:119], v[146:149], v[170:173], v[116:119]
	v_mfma_f32_16x16x32_bf16 v[108:111], v[154:157], v[170:173], v[108:111]
	v_mfma_f32_16x16x32_bf16 v[100:103], v[146:149], v[178:181], v[100:103]
	v_mfma_f32_16x16x32_bf16 v[92:95], v[154:157], v[178:181], v[92:95]
	v_mfma_f32_16x16x32_bf16 v[84:87], v[146:149], v[186:189], v[84:87]
	v_mfma_f32_16x16x32_bf16 v[76:79], v[154:157], v[186:189], v[76:79]
	v_mfma_f32_16x16x32_bf16 v[124:127], v[150:153], v[166:169], v[124:127]
	v_mfma_f32_16x16x32_bf16 v[120:123], v[158:161], v[166:169], v[120:123]
	v_mfma_f32_16x16x32_bf16 v[116:119], v[150:153], v[174:177], v[116:119]
	v_mfma_f32_16x16x32_bf16 v[108:111], v[158:161], v[174:177], v[108:111]
	v_mfma_f32_16x16x32_bf16 v[100:103], v[150:153], v[182:185], v[100:103]
	v_mfma_f32_16x16x32_bf16 v[92:95], v[158:161], v[182:185], v[92:95]
	v_mfma_f32_16x16x32_bf16 v[84:87], v[150:153], v[204:207], v[84:87]
	v_mfma_f32_16x16x32_bf16 v[76:79], v[158:161], v[204:207], v[76:79]
	s_barrier
	s_add_i32 s46, 0, 0x14000
	v_add_u32_e32 v140, s46, v143
	s_add_i32 s43, s43, s28
	ds_read_b128 v[208:211], v140
	ds_read_b128 v[214:217], v140 offset:1024
	ds_read_b128 v[218:221], v140 offset:2048
	ds_read_b128 v[222:225], v140 offset:3072
	v_lshl_add_u64 v[140:141], s[18:19], 0, v[192:193]
	s_mov_b32 m0, s43
	v_lshl_add_u64 v[190:191], s[18:19], 0, v[128:129]
	global_load_lds_dwordx4 v[140:141], off
	s_add_i32 m0, s43, 0x2000
	s_nop 0
	global_load_lds_dwordx4 v[190:191], off
	s_barrier
	s_waitcnt lgkmcnt(0)
	s_waitcnt lgkmcnt(0)
	v_mfma_f32_16x16x32_bf16 v[112:115], v[208:211], v[162:165], v[112:115]
	v_mfma_f32_16x16x32_bf16 v[104:107], v[218:221], v[162:165], v[104:107]
	v_mfma_f32_16x16x32_bf16 v[96:99], v[208:211], v[170:173], v[96:99]
	v_mfma_f32_16x16x32_bf16 v[88:91], v[218:221], v[170:173], v[88:91]
	v_mfma_f32_16x16x32_bf16 v[80:83], v[208:211], v[178:181], v[80:83]
	v_mfma_f32_16x16x32_bf16 v[72:75], v[218:221], v[178:181], v[72:75]
	v_mfma_f32_16x16x32_bf16 v[68:71], v[208:211], v[186:189], v[68:71]
	v_mfma_f32_16x16x32_bf16 v[64:67], v[218:221], v[186:189], v[64:67]
	v_mfma_f32_16x16x32_bf16 v[112:115], v[214:217], v[166:169], v[112:115]
	v_mfma_f32_16x16x32_bf16 v[104:107], v[222:225], v[166:169], v[104:107]
	v_mfma_f32_16x16x32_bf16 v[96:99], v[214:217], v[174:177], v[96:99]
	v_mfma_f32_16x16x32_bf16 v[88:91], v[222:225], v[174:177], v[88:91]
	v_mfma_f32_16x16x32_bf16 v[80:83], v[214:217], v[182:185], v[80:83]
	v_mfma_f32_16x16x32_bf16 v[72:75], v[222:225], v[182:185], v[72:75]
	v_mfma_f32_16x16x32_bf16 v[68:71], v[214:217], v[204:207], v[68:71]
	v_mfma_f32_16x16x32_bf16 v[64:67], v[222:225], v[204:207], v[64:67]
	s_mov_b32 m0, s30
	v_lshl_add_u64 v[196:197], s[20:21], 0, v[132:133]
	s_barrier
	ds_read_b128 v[162:165], v145 offset:16384
	ds_read_b128 v[166:169], v145 offset:17408
	ds_read_b128 v[170:173], v145 offset:18432
	ds_read_b128 v[174:177], v145 offset:19456
	ds_read_b128 v[178:181], v145 offset:20480
	ds_read_b128 v[182:185], v145 offset:21504
	ds_read_b128 v[186:189], v145 offset:22528
	ds_read_b128 v[204:207], v145 offset:23552
	global_load_lds_dwordx4 v[196:197], off
	v_lshl_add_u64 v[198:199], s[20:21], 0, v[130:131]
	s_mov_b32 m0, s31
	s_nop 0
	global_load_lds_dwordx4 v[198:199], off
	s_barrier
	s_waitcnt lgkmcnt(0)
	s_waitcnt lgkmcnt(0)
	v_mfma_f32_16x16x32_bf16 v[60:63], v[146:149], v[162:165], v[60:63]
	v_mfma_f32_16x16x32_bf16 v[56:59], v[154:157], v[162:165], v[56:59]
	v_mfma_f32_16x16x32_bf16 v[52:55], v[146:149], v[170:173], v[52:55]
	v_mfma_f32_16x16x32_bf16 v[44:47], v[154:157], v[170:173], v[44:47]
	v_mfma_f32_16x16x32_bf16 v[36:39], v[146:149], v[178:181], v[36:39]
	v_mfma_f32_16x16x32_bf16 v[28:31], v[154:157], v[178:181], v[28:31]
	v_mfma_f32_16x16x32_bf16 v[20:23], v[146:149], v[186:189], v[20:23]
	v_mfma_f32_16x16x32_bf16 v[12:15], v[154:157], v[186:189], v[12:15]
	v_mfma_f32_16x16x32_bf16 v[60:63], v[150:153], v[166:169], v[60:63]
	v_mfma_f32_16x16x32_bf16 v[56:59], v[158:161], v[166:169], v[56:59]
	v_mfma_f32_16x16x32_bf16 v[52:55], v[150:153], v[174:177], v[52:55]
	v_mfma_f32_16x16x32_bf16 v[44:47], v[158:161], v[174:177], v[44:47]
	v_mfma_f32_16x16x32_bf16 v[36:39], v[150:153], v[182:185], v[36:39]
	v_mfma_f32_16x16x32_bf16 v[28:31], v[158:161], v[182:185], v[28:31]
	v_mfma_f32_16x16x32_bf16 v[20:23], v[150:153], v[204:207], v[20:23]
	v_mfma_f32_16x16x32_bf16 v[12:15], v[158:161], v[204:207], v[12:15]
	s_barrier
	s_add_u32 s44, s18, 0x80000
	s_addc_u32 s45, s19, 0
	s_add_i32 s43, s46, s28
	v_lshl_add_u64 v[146:147], s[44:45], 0, v[192:193]
	s_mov_b32 m0, s43
	s_nop 0
	global_load_lds_dwordx4 v[146:147], off
	v_lshl_add_u64 v[146:147], s[44:45], 0, v[128:129]
	s_add_i32 m0, s43, 0x2000
	s_nop 0
	global_load_lds_dwordx4 v[146:147], off
	s_waitcnt vmcnt(6)
	s_barrier
	v_mfma_f32_16x16x32_bf16 v[48:51], v[208:211], v[162:165], v[48:51]
	v_mfma_f32_16x16x32_bf16 v[40:43], v[218:221], v[162:165], v[40:43]
	v_mfma_f32_16x16x32_bf16 v[32:35], v[208:211], v[170:173], v[32:35]
	v_mfma_f32_16x16x32_bf16 v[24:27], v[218:221], v[170:173], v[24:27]
	v_mfma_f32_16x16x32_bf16 v[16:19], v[208:211], v[178:181], v[16:19]
	v_mfma_f32_16x16x32_bf16 v[8:11], v[218:221], v[178:181], v[8:11]
	v_mfma_f32_16x16x32_bf16 v[4:7], v[208:211], v[186:189], v[4:7]
	v_mfma_f32_16x16x32_bf16 v[0:3], v[218:221], v[186:189], v[0:3]
	v_mfma_f32_16x16x32_bf16 v[48:51], v[214:217], v[166:169], v[48:51]
	v_mfma_f32_16x16x32_bf16 v[40:43], v[222:225], v[166:169], v[40:43]
	v_mfma_f32_16x16x32_bf16 v[32:35], v[214:217], v[174:177], v[32:35]
	v_mfma_f32_16x16x32_bf16 v[24:27], v[222:225], v[174:177], v[24:27]
	v_mfma_f32_16x16x32_bf16 v[16:19], v[214:217], v[182:185], v[16:19]
	v_mfma_f32_16x16x32_bf16 v[8:11], v[222:225], v[182:185], v[8:11]
	v_mfma_f32_16x16x32_bf16 v[4:7], v[214:217], v[204:207], v[4:7]
	v_mfma_f32_16x16x32_bf16 v[0:3], v[222:225], v[204:207], v[0:3]
	s_add_i32 s43, 0, 0x18000
	v_add_u32_e32 v158, s43, v143
	s_barrier
	ds_read_b128 v[146:149], v158
	ds_read_b128 v[150:153], v158 offset:1024
	ds_read_b128 v[154:157], v158 offset:2048
	ds_read_b128 v[158:161], v158 offset:3072
	s_add_u32 s20, s20, 0x80000
	s_addc_u32 s21, s21, 0
	s_mov_b32 m0, s33
	v_lshl_add_u64 v[208:209], s[20:21], 0, v[132:133]
	ds_read_b128 v[162:165], v145 offset:32768
	ds_read_b128 v[166:169], v145 offset:33792
	ds_read_b128 v[170:173], v145 offset:34816
	ds_read_b128 v[174:177], v145 offset:35840
	ds_read_b128 v[178:181], v145 offset:36864
	ds_read_b128 v[182:185], v145 offset:37888
	ds_read_b128 v[186:189], v145 offset:38912
	ds_read_b128 v[204:207], v145 offset:39936
	global_load_lds_dwordx4 v[208:209], off
	v_lshl_add_u64 v[208:209], s[20:21], 0, v[130:131]
	s_mov_b32 m0, s34
	s_nop 0
	global_load_lds_dwordx4 v[208:209], off
	s_waitcnt lgkmcnt(8)
	s_barrier
	s_waitcnt lgkmcnt(0)
	s_waitcnt lgkmcnt(0)
	v_mfma_f32_16x16x32_bf16 v[124:127], v[146:149], v[162:165], v[124:127]
	v_mfma_f32_16x16x32_bf16 v[120:123], v[154:157], v[162:165], v[120:123]
	v_mfma_f32_16x16x32_bf16 v[116:119], v[146:149], v[170:173], v[116:119]
	v_mfma_f32_16x16x32_bf16 v[108:111], v[154:157], v[170:173], v[108:111]
	v_mfma_f32_16x16x32_bf16 v[100:103], v[146:149], v[178:181], v[100:103]
	v_mfma_f32_16x16x32_bf16 v[92:95], v[154:157], v[178:181], v[92:95]
	v_mfma_f32_16x16x32_bf16 v[84:87], v[146:149], v[186:189], v[84:87]
	v_mfma_f32_16x16x32_bf16 v[76:79], v[154:157], v[186:189], v[76:79]
	v_mfma_f32_16x16x32_bf16 v[124:127], v[150:153], v[166:169], v[124:127]
	v_mfma_f32_16x16x32_bf16 v[120:123], v[158:161], v[166:169], v[120:123]
	v_mfma_f32_16x16x32_bf16 v[116:119], v[150:153], v[174:177], v[116:119]
	v_mfma_f32_16x16x32_bf16 v[108:111], v[158:161], v[174:177], v[108:111]
	v_mfma_f32_16x16x32_bf16 v[100:103], v[150:153], v[182:185], v[100:103]
	v_mfma_f32_16x16x32_bf16 v[92:95], v[158:161], v[182:185], v[92:95]
	v_mfma_f32_16x16x32_bf16 v[84:87], v[150:153], v[204:207], v[84:87]
	v_mfma_f32_16x16x32_bf16 v[76:79], v[158:161], v[204:207], v[76:79]
	s_barrier
	s_add_i32 s20, 0, 0x1c000
	s_add_i32 s21, s43, s28
	v_add_u32_e32 v212, s20, v143
	v_lshl_add_u64 v[140:141], v[140:141], 0, s[48:49]
	s_mov_b32 m0, s21
	ds_read_b128 v[208:211], v212
	ds_read_b128 v[214:217], v212 offset:1024
	ds_read_b128 v[218:221], v212 offset:2048
	ds_read_b128 v[222:225], v212 offset:3072
	global_load_lds_dwordx4 v[140:141], off
	v_lshl_add_u64 v[140:141], v[190:191], 0, s[48:49]
	s_add_i32 m0, s21, 0x2000
	s_nop 0
	global_load_lds_dwordx4 v[140:141], off
	s_barrier
	s_waitcnt lgkmcnt(0)
	s_waitcnt lgkmcnt(0)
	v_mfma_f32_16x16x32_bf16 v[112:115], v[208:211], v[162:165], v[112:115]
	v_mfma_f32_16x16x32_bf16 v[104:107], v[218:221], v[162:165], v[104:107]
	v_mfma_f32_16x16x32_bf16 v[96:99], v[208:211], v[170:173], v[96:99]
	v_mfma_f32_16x16x32_bf16 v[88:91], v[218:221], v[170:173], v[88:91]
	v_mfma_f32_16x16x32_bf16 v[80:83], v[208:211], v[178:181], v[80:83]
	v_mfma_f32_16x16x32_bf16 v[72:75], v[218:221], v[178:181], v[72:75]
	v_mfma_f32_16x16x32_bf16 v[68:71], v[208:211], v[186:189], v[68:71]
	v_mfma_f32_16x16x32_bf16 v[64:67], v[218:221], v[186:189], v[64:67]
	v_mfma_f32_16x16x32_bf16 v[112:115], v[214:217], v[166:169], v[112:115]
	v_mfma_f32_16x16x32_bf16 v[104:107], v[222:225], v[166:169], v[104:107]
	v_mfma_f32_16x16x32_bf16 v[96:99], v[214:217], v[174:177], v[96:99]
	v_mfma_f32_16x16x32_bf16 v[88:91], v[222:225], v[174:177], v[88:91]
	v_mfma_f32_16x16x32_bf16 v[80:83], v[214:217], v[182:185], v[80:83]
	v_mfma_f32_16x16x32_bf16 v[72:75], v[222:225], v[182:185], v[72:75]
	v_mfma_f32_16x16x32_bf16 v[68:71], v[214:217], v[204:207], v[68:71]
	v_mfma_f32_16x16x32_bf16 v[64:67], v[222:225], v[204:207], v[64:67]
	s_mov_b32 m0, s35
	v_lshl_add_u64 v[140:141], v[196:197], 0, s[48:49]
	s_barrier
	ds_read_b128 v[162:165], v145 offset:49152
	ds_read_b128 v[166:169], v145 offset:50176
	ds_read_b128 v[170:173], v145 offset:51200
	ds_read_b128 v[174:177], v145 offset:52224
	ds_read_b128 v[178:181], v145 offset:53248
	ds_read_b128 v[182:185], v145 offset:54272
	ds_read_b128 v[186:189], v145 offset:55296
	ds_read_b128 v[204:207], v145 offset:56320
	global_load_lds_dwordx4 v[140:141], off
	v_lshl_add_u64 v[140:141], v[198:199], 0, s[48:49]
	s_mov_b32 m0, s36
	s_nop 0
	global_load_lds_dwordx4 v[140:141], off
	s_barrier
	s_waitcnt lgkmcnt(0)
	s_waitcnt lgkmcnt(0)
	v_mfma_f32_16x16x32_bf16 v[60:63], v[146:149], v[162:165], v[60:63]
	v_mfma_f32_16x16x32_bf16 v[56:59], v[154:157], v[162:165], v[56:59]
	v_mfma_f32_16x16x32_bf16 v[52:55], v[146:149], v[170:173], v[52:55]
	v_mfma_f32_16x16x32_bf16 v[44:47], v[154:157], v[170:173], v[44:47]
	v_mfma_f32_16x16x32_bf16 v[36:39], v[146:149], v[178:181], v[36:39]
	v_mfma_f32_16x16x32_bf16 v[28:31], v[154:157], v[178:181], v[28:31]
	v_mfma_f32_16x16x32_bf16 v[20:23], v[146:149], v[186:189], v[20:23]
	v_mfma_f32_16x16x32_bf16 v[12:15], v[154:157], v[186:189], v[12:15]
	v_mfma_f32_16x16x32_bf16 v[60:63], v[150:153], v[166:169], v[60:63]
	v_mfma_f32_16x16x32_bf16 v[56:59], v[158:161], v[166:169], v[56:59]
	v_mfma_f32_16x16x32_bf16 v[52:55], v[150:153], v[174:177], v[52:55]
	v_mfma_f32_16x16x32_bf16 v[44:47], v[158:161], v[174:177], v[44:47]
	v_mfma_f32_16x16x32_bf16 v[36:39], v[150:153], v[182:185], v[36:39]
	v_mfma_f32_16x16x32_bf16 v[28:31], v[158:161], v[182:185], v[28:31]
	v_mfma_f32_16x16x32_bf16 v[20:23], v[150:153], v[204:207], v[20:23]
	v_mfma_f32_16x16x32_bf16 v[12:15], v[158:161], v[204:207], v[12:15]
	s_barrier
	s_add_u32 s18, s18, 0x80080
	s_addc_u32 s19, s19, 0
	s_add_i32 s20, s20, s28
	v_lshl_add_u64 v[140:141], s[18:19], 0, v[192:193]
	s_mov_b32 m0, s20
	s_nop 0
	global_load_lds_dwordx4 v[140:141], off
	v_lshl_add_u64 v[140:141], s[18:19], 0, v[128:129]
	s_add_i32 m0, s20, 0x2000
	s_nop 0
	global_load_lds_dwordx4 v[140:141], off
	s_waitcnt vmcnt(6)
	s_barrier
	v_mfma_f32_16x16x32_bf16 v[48:51], v[208:211], v[162:165], v[48:51]
	v_mfma_f32_16x16x32_bf16 v[40:43], v[218:221], v[162:165], v[40:43]
	v_mfma_f32_16x16x32_bf16 v[32:35], v[208:211], v[170:173], v[32:35]
	v_mfma_f32_16x16x32_bf16 v[24:27], v[218:221], v[170:173], v[24:27]
	v_mfma_f32_16x16x32_bf16 v[16:19], v[208:211], v[178:181], v[16:19]
	v_mfma_f32_16x16x32_bf16 v[8:11], v[218:221], v[178:181], v[8:11]
	v_mfma_f32_16x16x32_bf16 v[4:7], v[208:211], v[186:189], v[4:7]
	v_mfma_f32_16x16x32_bf16 v[0:3], v[218:221], v[186:189], v[0:3]
	v_mfma_f32_16x16x32_bf16 v[48:51], v[214:217], v[166:169], v[48:51]
	v_mfma_f32_16x16x32_bf16 v[40:43], v[222:225], v[166:169], v[40:43]
	v_mfma_f32_16x16x32_bf16 v[32:35], v[214:217], v[174:177], v[32:35]
	v_mfma_f32_16x16x32_bf16 v[24:27], v[222:225], v[174:177], v[24:27]
	v_mfma_f32_16x16x32_bf16 v[16:19], v[214:217], v[182:185], v[16:19]
	v_mfma_f32_16x16x32_bf16 v[8:11], v[222:225], v[182:185], v[8:11]
	v_mfma_f32_16x16x32_bf16 v[4:7], v[214:217], v[204:207], v[4:7]
	v_mfma_f32_16x16x32_bf16 v[0:3], v[222:225], v[204:207], v[0:3]
	s_add_i32 s42, s42, 2
	s_add_u32 s16, s16, 0x100
	s_addc_u32 s17, s17, 0
	s_add_u32 s40, s40, 0x100
	s_addc_u32 s41, s41, 0
	s_cmp_gt_u32 s42, 29
	s_barrier
	s_cbranch_scc0 .LBB0_415
	s_mul_hi_i32 s9, s15, 0x2aaaaaab
	v_lshl_add_u32 v153, s14, 8, v142
	s_lshr_b32 s14, s9, 31
	s_lshr_b32 s9, s9, 2
	s_add_i32 s9, s9, s14
	s_lshl_b32 s7, s15, 8
	s_mul_i32 s16, s9, 0x1800
	v_readlane_b32 s40, v254, 14
	v_readlane_b32 s41, v254, 15
	s_sub_i32 s40, s7, s16
	s_mov_b64 s[20:21], s[40:41]
	v_readlane_b32 s42, v254, 16
	v_readlane_b32 s43, v254, 17
	v_writelane_b32 v254, s20, 14
	s_mov_b64 s[14:15], -1
	s_cmpk_gt_i32 s40, 0xfff
	v_writelane_b32 v254, s21, 15
	v_writelane_b32 v254, s22, 16
	v_writelane_b32 v254, s23, 17
	v_or_b32_e32 v152, 16, v153
	v_or_b32_e32 v151, 32, v153
	v_or_b32_e32 v150, 48, v153
	v_add_u32_e32 v149, 0x80, v153
	v_add_u32_e32 v148, 0x90, v153
	v_add_u32_e32 v147, 0xa0, v153
	v_add_u32_e32 v146, 0xb0, v153
	s_cbranch_scc0 .LBB0_418
	v_mov_b32_e32 v156, v193
	v_mov_b32_e32 v157, v193
	s_ashr_i32 s17, s16, 31
	v_mov_b64_e32 v[140:141], s[2:3]
	s_mov_b32 s9, 0x9000
	v_cvt_pk_fp8_f32 v156, v124, v125
	v_cvt_pk_fp8_f32 v157, v120, v121
	s_lshl_b64 s[14:15], s[16:17], 1
	v_mad_i64_i32 v[154:155], s[16:17], v153, s9, v[140:141]
	s_add_u32 s14, s14, 0x2000
	v_readlane_b32 s16, v254, 14
	s_addc_u32 s15, s15, 0
	v_readlane_b32 s17, v254, 15
	v_lshl_add_u64 v[154:155], v[154:155], 0, s[14:15]
	s_mov_b64 s[20:21], s[16:17]
	v_cvt_pk_fp8_f32 v156, v126, v127 op_sel:[0,0,1]
	v_cvt_pk_fp8_f32 v157, v122, v123 op_sel:[0,0,1]
	v_lshl_add_u64 v[154:155], v[154:155], 0, s[20:21]
	v_lshl_add_u64 v[154:155], v[154:155], 0, s[4:5]
	v_lshl_add_u64 v[154:155], v[154:155], 0, v[134:135]
	global_store_dwordx2 v[154:155], v[156:157], off offset:-4096
	v_mov_b32_e32 v156, v193
	v_mov_b32_e32 v157, v193
	v_cvt_pk_fp8_f32 v156, v112, v113
	v_cvt_pk_fp8_f32 v157, v104, v105
	v_readlane_b32 s18, v254, 16
	v_readlane_b32 s19, v254, 17
	v_cvt_pk_fp8_f32 v156, v114, v115 op_sel:[0,0,1]
	v_cvt_pk_fp8_f32 v157, v106, v107 op_sel:[0,0,1]
	global_store_dwordx2 v[154:155], v[156:157], off offset:-3968
	v_mov_b32_e32 v156, v193
	v_mov_b32_e32 v157, v193
	v_cvt_pk_fp8_f32 v156, v116, v117
	v_cvt_pk_fp8_f32 v157, v108, v109
	v_mad_i64_i32 v[154:155], s[16:17], v152, s9, v[140:141]
	v_lshl_add_u64 v[154:155], v[154:155], 0, s[14:15]
	v_cvt_pk_fp8_f32 v156, v118, v119 op_sel:[0,0,1]
	v_cvt_pk_fp8_f32 v157, v110, v111 op_sel:[0,0,1]
	v_lshl_add_u64 v[154:155], v[154:155], 0, s[20:21]
	v_lshl_add_u64 v[154:155], v[154:155], 0, s[4:5]
	v_lshl_add_u64 v[154:155], v[154:155], 0, v[134:135]
	global_store_dwordx2 v[154:155], v[156:157], off offset:-4096
	v_mov_b32_e32 v156, v193
	v_mov_b32_e32 v157, v193
	v_cvt_pk_fp8_f32 v156, v96, v97
	v_cvt_pk_fp8_f32 v157, v88, v89
	v_cvt_pk_fp8_f32 v156, v98, v99 op_sel:[0,0,1]
	v_cvt_pk_fp8_f32 v157, v90, v91 op_sel:[0,0,1]
	global_store_dwordx2 v[154:155], v[156:157], off offset:-3968
	v_mov_b32_e32 v156, v193
	v_mov_b32_e32 v157, v193
	v_cvt_pk_fp8_f32 v156, v100, v101
	v_cvt_pk_fp8_f32 v157, v92, v93
	v_mad_i64_i32 v[154:155], s[16:17], v151, s9, v[140:141]
	v_lshl_add_u64 v[154:155], v[154:155], 0, s[14:15]
	v_cvt_pk_fp8_f32 v156, v102, v103 op_sel:[0,0,1]
	v_cvt_pk_fp8_f32 v157, v94, v95 op_sel:[0,0,1]
	v_lshl_add_u64 v[154:155], v[154:155], 0, s[20:21]
	v_lshl_add_u64 v[154:155], v[154:155], 0, s[4:5]
	v_lshl_add_u64 v[154:155], v[154:155], 0, v[134:135]
	global_store_dwordx2 v[154:155], v[156:157], off offset:-4096
	v_mov_b32_e32 v156, v193
	v_mov_b32_e32 v157, v193
	v_cvt_pk_fp8_f32 v156, v80, v81
	v_cvt_pk_fp8_f32 v157, v72, v73
	v_cvt_pk_fp8_f32 v156, v82, v83 op_sel:[0,0,1]
	v_cvt_pk_fp8_f32 v157, v74, v75 op_sel:[0,0,1]
	global_store_dwordx2 v[154:155], v[156:157], off offset:-3968
	v_mov_b32_e32 v156, v193
	v_mov_b32_e32 v157, v193
	v_cvt_pk_fp8_f32 v156, v84, v85
	v_cvt_pk_fp8_f32 v157, v76, v77
	v_mad_i64_i32 v[154:155], s[16:17], v150, s9, v[140:141]
	v_lshl_add_u64 v[154:155], v[154:155], 0, s[14:15]
	v_cvt_pk_fp8_f32 v156, v86, v87 op_sel:[0,0,1]
	v_cvt_pk_fp8_f32 v157, v78, v79 op_sel:[0,0,1]
	v_lshl_add_u64 v[154:155], v[154:155], 0, s[20:21]
	v_lshl_add_u64 v[154:155], v[154:155], 0, s[4:5]
	v_lshl_add_u64 v[154:155], v[154:155], 0, v[134:135]
	global_store_dwordx2 v[154:155], v[156:157], off offset:-4096
	v_mov_b32_e32 v156, v193
	v_mov_b32_e32 v157, v193
	v_cvt_pk_fp8_f32 v156, v68, v69
	v_cvt_pk_fp8_f32 v157, v64, v65
	v_cvt_pk_fp8_f32 v156, v70, v71 op_sel:[0,0,1]
	v_cvt_pk_fp8_f32 v157, v66, v67 op_sel:[0,0,1]
	global_store_dwordx2 v[154:155], v[156:157], off offset:-3968
	v_mov_b32_e32 v156, v193
	v_mov_b32_e32 v157, v193
	v_cvt_pk_fp8_f32 v156, v60, v61
	v_cvt_pk_fp8_f32 v157, v56, v57
	v_mad_i64_i32 v[154:155], s[16:17], v149, s9, v[140:141]
	v_lshl_add_u64 v[154:155], v[154:155], 0, s[14:15]
	v_cvt_pk_fp8_f32 v156, v62, v63 op_sel:[0,0,1]
	v_cvt_pk_fp8_f32 v157, v58, v59 op_sel:[0,0,1]
	v_lshl_add_u64 v[154:155], v[154:155], 0, s[20:21]
	v_lshl_add_u64 v[154:155], v[154:155], 0, s[4:5]
	v_lshl_add_u64 v[154:155], v[154:155], 0, v[134:135]
	global_store_dwordx2 v[154:155], v[156:157], off offset:-4096
	v_mov_b32_e32 v156, v193
	v_mov_b32_e32 v157, v193
	v_cvt_pk_fp8_f32 v156, v48, v49
	v_cvt_pk_fp8_f32 v157, v40, v41
	v_cvt_pk_fp8_f32 v156, v50, v51 op_sel:[0,0,1]
	v_cvt_pk_fp8_f32 v157, v42, v43 op_sel:[0,0,1]
	global_store_dwordx2 v[154:155], v[156:157], off offset:-3968
	v_mov_b32_e32 v156, v193
	v_mov_b32_e32 v157, v193
	v_cvt_pk_fp8_f32 v156, v52, v53
	v_cvt_pk_fp8_f32 v157, v44, v45
	v_mad_i64_i32 v[154:155], s[16:17], v148, s9, v[140:141]
	v_lshl_add_u64 v[154:155], v[154:155], 0, s[14:15]
	v_cvt_pk_fp8_f32 v156, v54, v55 op_sel:[0,0,1]
	v_cvt_pk_fp8_f32 v157, v46, v47 op_sel:[0,0,1]
	v_lshl_add_u64 v[154:155], v[154:155], 0, s[20:21]
	v_lshl_add_u64 v[154:155], v[154:155], 0, s[4:5]
	v_lshl_add_u64 v[154:155], v[154:155], 0, v[134:135]
	global_store_dwordx2 v[154:155], v[156:157], off offset:-4096
	v_mov_b32_e32 v156, v193
	v_mov_b32_e32 v157, v193
	v_cvt_pk_fp8_f32 v156, v32, v33
	v_cvt_pk_fp8_f32 v157, v24, v25
	v_cvt_pk_fp8_f32 v156, v34, v35 op_sel:[0,0,1]
	v_cvt_pk_fp8_f32 v157, v26, v27 op_sel:[0,0,1]
	global_store_dwordx2 v[154:155], v[156:157], off offset:-3968
	v_mov_b32_e32 v156, v193
	v_mov_b32_e32 v157, v193
	v_cvt_pk_fp8_f32 v156, v36, v37
	v_cvt_pk_fp8_f32 v157, v28, v29
	v_mad_i64_i32 v[154:155], s[16:17], v147, s9, v[140:141]
	v_lshl_add_u64 v[154:155], v[154:155], 0, s[14:15]
	v_cvt_pk_fp8_f32 v156, v38, v39 op_sel:[0,0,1]
	v_cvt_pk_fp8_f32 v157, v30, v31 op_sel:[0,0,1]
	v_lshl_add_u64 v[154:155], v[154:155], 0, s[20:21]
	v_lshl_add_u64 v[154:155], v[154:155], 0, s[4:5]
	v_lshl_add_u64 v[154:155], v[154:155], 0, v[134:135]
	global_store_dwordx2 v[154:155], v[156:157], off offset:-4096
	v_mov_b32_e32 v156, v193
	v_mov_b32_e32 v157, v193
	v_cvt_pk_fp8_f32 v156, v16, v17
	v_cvt_pk_fp8_f32 v157, v8, v9
	v_mad_i64_i32 v[140:141], s[16:17], v146, s9, v[140:141]
	v_cvt_pk_fp8_f32 v156, v18, v19 op_sel:[0,0,1]
	v_cvt_pk_fp8_f32 v157, v10, v11 op_sel:[0,0,1]
	v_lshl_add_u64 v[140:141], v[140:141], 0, s[14:15]
	v_lshl_add_u64 v[140:141], v[140:141], 0, s[20:21]
	v_lshl_add_u64 v[140:141], v[140:141], 0, s[4:5]
	global_store_dwordx2 v[154:155], v[156:157], off offset:-3968
	v_mov_b32_e32 v154, v193
	v_mov_b32_e32 v155, v193
	v_cvt_pk_fp8_f32 v154, v20, v21
	v_cvt_pk_fp8_f32 v155, v12, v13
	v_lshl_add_u64 v[140:141], v[140:141], 0, v[134:135]
	s_mov_b64 s[14:15], 0
	v_cvt_pk_fp8_f32 v154, v22, v23 op_sel:[0,0,1]
	v_cvt_pk_fp8_f32 v155, v14, v15 op_sel:[0,0,1]
	global_store_dwordx2 v[140:141], v[154:155], off offset:-4096
	v_mov_b32_e32 v154, v193
	v_mov_b32_e32 v155, v193
	v_cvt_pk_fp8_f32 v154, v4, v5
	v_cvt_pk_fp8_f32 v155, v0, v1
	v_cvt_pk_fp8_f32 v154, v6, v7 op_sel:[0,0,1]
	v_cvt_pk_fp8_f32 v155, v2, v3 op_sel:[0,0,1]
	global_store_dwordx2 v[140:141], v[154:155], off offset:-3968
